# baseline (speedup 1.0000x reference)
; #define GAS __attribute__((address_space(1)))
; #define PARAMS_LOCAL KParams PP_ = kparams(); const __attribute__((address_space(4))) Params& P = *PP_;
; __device__ __forceinline__ void phase_up(int pass) {
;   PARAMS_LOCAL
;   GAS unsigned char* ws = (GAS unsigned char*)P.ws; asm volatile("" : "+s"(ws));
;   const GAS bf16* Wgu = (const GAS bf16*)(ws + (pass ? OFF_WGU2 : OFF_WGU1));
;   const GAS bf16* A = (const GAS bf16*)(ws + OFF_XG);
;   GAS bf16* act = (GAS bf16*)(ws + OFF_RA);
;   const GAS float* ssq = (const GAS float*)(ws + OFF_SSQ);
;   constexpr int nN = 22, NT_ = 64 * nN;
;   int L = tile_first(), par = 0, pm, pn;
;   if (L < NT_) { tile_coords(L, nN, pm, pn); gemm_prefetch<DM>(A, Wgu, pm * 256, pn * 256); load_rr(ssq, pm * 256, 0); }
;   while (L < NT_) {
.LBB0_83:
	s_or_b64 exec, exec, s[12:13]
	s_add_u32 s35, s4, 0x5200000
	s_addc_u32 s36, s5, 0
	s_mov_b32 s37, 0
	s_movk_i32 s38, 0x3c0
	s_mov_b64 s[10:11], 0x100
	s_mov_b64 s[12:13], 0x180
	v_mov_b32_e32 v135, 0x358637bd
	s_mov_b32 s39, 0x800000
	s_movk_i32 s40, 0xb40
	s_waitcnt vmcnt(0)
	s_branch .LBB0_86

; #define GAS __attribute__((address_space(1)))
; __device__ __forceinline__ unsigned f2bf(float f) { return pk2(f, f) & 0xffffu; }
; __device__ __forceinline__ float sigmoidf_(float v) { return __builtin_amdgcn_rcpf(1.f + __builtin_amdgcn_exp2f(-LOG2E * v)); }
; __device__ __forceinline__ void phase_up(int pass) {
;     ...
;     EPI_IDS
;     const float* rr = (const float*)(smem_raw + LDS_RR) + par * 256;
;     GAS char* tb = (GAS char*)act + ((size_t)brow * FFP + (bcol >> 1)) * 2;
;     const unsigned off0 = (unsigned)((wr * 64 + fq * 4) * FFP + wc * 16 + fr) * 2u;
; #pragma unroll
;     for (int ai = 0; ai < 2; ++ai)
; #pragma unroll
;       for (int m = 0; m < 4; ++m)
; #pragma unroll
;         for (int j = 0; j < 4; ++j) {
;           const int rowl = ai * 128 + wr * 64 + m * 16 + fq * 4 + j;
;           const float r = rr[rowl];
; #pragma unroll
;           for (int bj = 0; bj < 2; ++bj) {
;             const float g = acc[ai][bj][m][0][j] * r, u = acc[ai][bj][m][1][j] * r;
;             const float v = g * sigmoidf_(g) * u;
;             *(GAS unsigned short*)(tb + (off0 + (unsigned)(((ai * 128 + m * 16 + j) * FFP + bj * 64) * 2))) = (unsigned short)f2bf(v);
;           }
;         }
.LBB0_85:
	v_and_b32_e32 v174, 15, v170
	v_lshrrev_b32_e32 v175, 8, v170
	v_lshl_or_b32 v175, v175, 6, v174
	v_bfe_u32 v176, v170, 4, 2
	v_bfe_u32 v177, v170, 6, 2
	v_lshlrev_b32_e32 v176, 2, v176
	v_lshl_or_b32 v176, v177, 4, v176
	v_mul_u32_u24_e32 v186, 0xb40, v175
	v_add_lshl_u32 v186, v186, v176, 1
	s_lshl_b32 s18, s37, 10
	s_add_i32 s18, s18, 0x20100
	v_lshl_add_u32 v174, v175, 2, s18
	ds_read_b32 v178, v174
	ds_read_b32 v179, v174 offset:64
	ds_read_b32 v180, v174 offset:128
	ds_read_b32 v181, v174 offset:192
	ds_read_b32 v182, v174 offset:512
	ds_read_b32 v183, v174 offset:576
	ds_read_b32 v184, v174 offset:640
	ds_read_b32 v185, v174 offset:704
	s_lshl_b32 s19, s41, 7
	s_mul_hi_i32 s17, s16, 0xb40
	s_mulk_i32 s16, 0xb40
	s_ashr_i32 s20, s19, 31
	s_add_u32 s16, s16, s19
	s_addc_u32 s17, s17, s20
	s_lshl_b64 s[16:17], s[16:17], 1
	s_add_u32 s16, s35, s16
	s_addc_u32 s17, s36, s17
	s_waitcnt lgkmcnt(0)
	v_mul_f32_e32 v118, v118, v178
	v_mul_f32_e32 v119, v119, v178
	v_mul_f32_e32 v120, v120, v178
	v_mul_f32_e32 v121, v121, v178
	v_mul_f32_e32 v174, 0xbfb8aa3b, v118
	v_mul_f32_e32 v175, 0xbfb8aa3b, v119
	v_mul_f32_e32 v176, 0xbfb8aa3b, v120
	v_mul_f32_e32 v177, 0xbfb8aa3b, v121
	v_exp_f32_e32 v174, v174
	v_exp_f32_e32 v175, v175
	v_exp_f32_e32 v176, v176
	v_exp_f32_e32 v177, v177
	v_mul_f32_e32 v114, v114, v178
	v_mul_f32_e32 v115, v115, v178
	v_mul_f32_e32 v116, v116, v178
	v_mul_f32_e32 v117, v117, v178
	v_add_f32_e32 v174, 1.0, v174
	v_add_f32_e32 v175, 1.0, v175
	v_add_f32_e32 v176, 1.0, v176
	v_add_f32_e32 v177, 1.0, v177
	v_rcp_f32_e32 v174, v174
	v_rcp_f32_e32 v175, v175
	v_rcp_f32_e32 v176, v176
	v_rcp_f32_e32 v177, v177
	v_mul_f32_e32 v118, v118, v174
	v_mul_f32_e32 v119, v119, v175
	v_mul_f32_e32 v120, v120, v176
	v_mul_f32_e32 v121, v121, v177
	v_mul_f32_e32 v114, v114, v118
	v_mul_f32_e32 v115, v115, v119
	v_mul_f32_e32 v116, v116, v120
	v_mul_f32_e32 v117, v117, v121
	v_cvt_pk_bf16_f32 v114, v114, v115
	v_cvt_pk_bf16_f32 v115, v116, v117
	global_store_dwordx2 v186, v[114:115], s[16:17]
	v_mul_f32_e32 v126, v126, v178
	v_mul_f32_e32 v127, v127, v178
	v_mul_f32_e32 v128, v128, v178
	v_mul_f32_e32 v129, v129, v178
	v_mul_f32_e32 v174, 0xbfb8aa3b, v126
	v_mul_f32_e32 v175, 0xbfb8aa3b, v127
	v_mul_f32_e32 v176, 0xbfb8aa3b, v128
	v_mul_f32_e32 v177, 0xbfb8aa3b, v129
	v_exp_f32_e32 v174, v174
	v_exp_f32_e32 v175, v175
	v_exp_f32_e32 v176, v176
	v_exp_f32_e32 v177, v177
	v_mul_f32_e32 v122, v122, v178
	v_mul_f32_e32 v123, v123, v178
	v_mul_f32_e32 v124, v124, v178
	v_mul_f32_e32 v125, v125, v178
	v_add_f32_e32 v174, 1.0, v174
	v_add_f32_e32 v175, 1.0, v175
	v_add_f32_e32 v176, 1.0, v176
	v_add_f32_e32 v177, 1.0, v177
	v_rcp_f32_e32 v174, v174
	v_rcp_f32_e32 v175, v175
	v_rcp_f32_e32 v176, v176
	v_rcp_f32_e32 v177, v177
	v_mul_f32_e32 v126, v126, v174
	v_mul_f32_e32 v127, v127, v175
	v_mul_f32_e32 v128, v128, v176
	v_mul_f32_e32 v129, v129, v177
	v_mul_f32_e32 v122, v122, v126
	v_mul_f32_e32 v123, v123, v127
	v_mul_f32_e32 v124, v124, v128
	v_mul_f32_e32 v125, v125, v129
	v_cvt_pk_bf16_f32 v122, v122, v123
	v_cvt_pk_bf16_f32 v123, v124, v125
	global_store_dwordx2 v186, v[122:123], s[16:17] offset:128
	s_add_u32 s16, s16, 0x16800
	s_addc_u32 s17, s17, 0
	v_mul_f32_e32 v102, v102, v179
	v_mul_f32_e32 v103, v103, v179
	v_mul_f32_e32 v104, v104, v179
	v_mul_f32_e32 v105, v105, v179
	v_mul_f32_e32 v174, 0xbfb8aa3b, v102
	v_mul_f32_e32 v175, 0xbfb8aa3b, v103
	v_mul_f32_e32 v176, 0xbfb8aa3b, v104
	v_mul_f32_e32 v177, 0xbfb8aa3b, v105
	v_exp_f32_e32 v174, v174
	v_exp_f32_e32 v175, v175
	v_exp_f32_e32 v176, v176
	v_exp_f32_e32 v177, v177
	v_mul_f32_e32 v98, v98, v179
	v_mul_f32_e32 v99, v99, v179
	v_mul_f32_e32 v100, v100, v179
	v_mul_f32_e32 v101, v101, v179
	v_add_f32_e32 v174, 1.0, v174
	v_add_f32_e32 v175, 1.0, v175
	v_add_f32_e32 v176, 1.0, v176
	v_add_f32_e32 v177, 1.0, v177
	v_rcp_f32_e32 v174, v174
	v_rcp_f32_e32 v175, v175
	v_rcp_f32_e32 v176, v176
	v_rcp_f32_e32 v177, v177
	v_mul_f32_e32 v102, v102, v174
	v_mul_f32_e32 v103, v103, v175
	v_mul_f32_e32 v104, v104, v176
	v_mul_f32_e32 v105, v105, v177
	v_mul_f32_e32 v98, v98, v102
	v_mul_f32_e32 v99, v99, v103
	v_mul_f32_e32 v100, v100, v104
	v_mul_f32_e32 v101, v101, v105
	v_cvt_pk_bf16_f32 v98, v98, v99
	v_cvt_pk_bf16_f32 v99, v100, v101
	global_store_dwordx2 v186, v[98:99], s[16:17]
	v_mul_f32_e32 v110, v110, v179
	v_mul_f32_e32 v111, v111, v179
	v_mul_f32_e32 v112, v112, v179
	v_mul_f32_e32 v113, v113, v179
	v_mul_f32_e32 v174, 0xbfb8aa3b, v110
	v_mul_f32_e32 v175, 0xbfb8aa3b, v111
	v_mul_f32_e32 v176, 0xbfb8aa3b, v112
	v_mul_f32_e32 v177, 0xbfb8aa3b, v113
	v_exp_f32_e32 v174, v174
	v_exp_f32_e32 v175, v175
	v_exp_f32_e32 v176, v176
	v_exp_f32_e32 v177, v177
	v_mul_f32_e32 v106, v106, v179
	v_mul_f32_e32 v107, v107, v179
	v_mul_f32_e32 v108, v108, v179
	v_mul_f32_e32 v109, v109, v179
	v_add_f32_e32 v174, 1.0, v174
	v_add_f32_e32 v175, 1.0, v175
	v_add_f32_e32 v176, 1.0, v176
	v_add_f32_e32 v177, 1.0, v177
	v_rcp_f32_e32 v174, v174
	v_rcp_f32_e32 v175, v175
	v_rcp_f32_e32 v176, v176
	v_rcp_f32_e32 v177, v177
	v_mul_f32_e32 v110, v110, v174
	v_mul_f32_e32 v111, v111, v175
	v_mul_f32_e32 v112, v112, v176
	v_mul_f32_e32 v113, v113, v177
	v_mul_f32_e32 v106, v106, v110
	v_mul_f32_e32 v107, v107, v111
	v_mul_f32_e32 v108, v108, v112
	v_mul_f32_e32 v109, v109, v113
	v_cvt_pk_bf16_f32 v106, v106, v107
	v_cvt_pk_bf16_f32 v107, v108, v109
	global_store_dwordx2 v186, v[106:107], s[16:17] offset:128
	s_add_u32 s16, s16, 0x16800
	s_addc_u32 s17, s17, 0
	v_mul_f32_e32 v86, v86, v180
	v_mul_f32_e32 v87, v87, v180
	v_mul_f32_e32 v88, v88, v180
	v_mul_f32_e32 v89, v89, v180
; #define GAS __attribute__((address_space(1)))
; __device__ __forceinline__ unsigned f2bf(float f) { return pk2(f, f) & 0xffffu; }
; __device__ __forceinline__ float sigmoidf_(float v) { return __builtin_amdgcn_rcpf(1.f + __builtin_amdgcn_exp2f(-LOG2E * v)); }
; __device__ __forceinline__ void phase_up(int pass) {
;     ...
; #pragma unroll
;     for (int ai = 0; ai < 2; ++ai)
; #pragma unroll
;       for (int m = 0; m < 4; ++m)
; #pragma unroll
;         for (int j = 0; j < 4; ++j) {
;           const int rowl = ai * 128 + wr * 64 + m * 16 + fq * 4 + j;
;           const float r = rr[rowl];
; #pragma unroll
;           for (int bj = 0; bj < 2; ++bj) {
;             const float g = acc[ai][bj][m][0][j] * r, u = acc[ai][bj][m][1][j] * r;
;             const float v = g * sigmoidf_(g) * u;
;             *(GAS unsigned short*)(tb + (off0 + (unsigned)(((ai * 128 + m * 16 + j) * FFP + bj * 64) * 2))) = (unsigned short)f2bf(v);
;           }
;         }
	v_mul_f32_e32 v174, 0xbfb8aa3b, v86
	v_mul_f32_e32 v175, 0xbfb8aa3b, v87
	v_mul_f32_e32 v176, 0xbfb8aa3b, v88
	v_mul_f32_e32 v177, 0xbfb8aa3b, v89
	v_exp_f32_e32 v174, v174
	v_exp_f32_e32 v175, v175
	v_exp_f32_e32 v176, v176
	v_exp_f32_e32 v177, v177
	v_mul_f32_e32 v82, v82, v180
	v_mul_f32_e32 v83, v83, v180
	v_mul_f32_e32 v84, v84, v180
	v_mul_f32_e32 v85, v85, v180
	v_add_f32_e32 v174, 1.0, v174
	v_add_f32_e32 v175, 1.0, v175
	v_add_f32_e32 v176, 1.0, v176
	v_add_f32_e32 v177, 1.0, v177
	v_rcp_f32_e32 v174, v174
	v_rcp_f32_e32 v175, v175
	v_rcp_f32_e32 v176, v176
	v_rcp_f32_e32 v177, v177
	v_mul_f32_e32 v86, v86, v174
	v_mul_f32_e32 v87, v87, v175
	v_mul_f32_e32 v88, v88, v176
	v_mul_f32_e32 v89, v89, v177
	v_mul_f32_e32 v82, v82, v86
	v_mul_f32_e32 v83, v83, v87
	v_mul_f32_e32 v84, v84, v88
	v_mul_f32_e32 v85, v85, v89
	v_cvt_pk_bf16_f32 v82, v82, v83
	v_cvt_pk_bf16_f32 v83, v84, v85
	global_store_dwordx2 v186, v[82:83], s[16:17]
	v_mul_f32_e32 v94, v94, v180
	v_mul_f32_e32 v95, v95, v180
	v_mul_f32_e32 v96, v96, v180
	v_mul_f32_e32 v97, v97, v180
	v_mul_f32_e32 v174, 0xbfb8aa3b, v94
	v_mul_f32_e32 v175, 0xbfb8aa3b, v95
	v_mul_f32_e32 v176, 0xbfb8aa3b, v96
	v_mul_f32_e32 v177, 0xbfb8aa3b, v97
	v_exp_f32_e32 v174, v174
	v_exp_f32_e32 v175, v175
	v_exp_f32_e32 v176, v176
	v_exp_f32_e32 v177, v177
	v_mul_f32_e32 v90, v90, v180
	v_mul_f32_e32 v91, v91, v180
	v_mul_f32_e32 v92, v92, v180
	v_mul_f32_e32 v93, v93, v180
	v_add_f32_e32 v174, 1.0, v174
	v_add_f32_e32 v175, 1.0, v175
	v_add_f32_e32 v176, 1.0, v176
	v_add_f32_e32 v177, 1.0, v177
	v_rcp_f32_e32 v174, v174
	v_rcp_f32_e32 v175, v175
	v_rcp_f32_e32 v176, v176
	v_rcp_f32_e32 v177, v177
	v_mul_f32_e32 v94, v94, v174
	v_mul_f32_e32 v95, v95, v175
	v_mul_f32_e32 v96, v96, v176
	v_mul_f32_e32 v97, v97, v177
	v_mul_f32_e32 v90, v90, v94
	v_mul_f32_e32 v91, v91, v95
	v_mul_f32_e32 v92, v92, v96
	v_mul_f32_e32 v93, v93, v97
	v_cvt_pk_bf16_f32 v90, v90, v91
	v_cvt_pk_bf16_f32 v91, v92, v93
	global_store_dwordx2 v186, v[90:91], s[16:17] offset:128
	s_add_u32 s16, s16, 0x16800
	s_addc_u32 s17, s17, 0
	v_mul_f32_e32 v70, v70, v181
	v_mul_f32_e32 v71, v71, v181
	v_mul_f32_e32 v72, v72, v181
	v_mul_f32_e32 v73, v73, v181
	v_mul_f32_e32 v174, 0xbfb8aa3b, v70
	v_mul_f32_e32 v175, 0xbfb8aa3b, v71
	v_mul_f32_e32 v176, 0xbfb8aa3b, v72
	v_mul_f32_e32 v177, 0xbfb8aa3b, v73
	v_exp_f32_e32 v174, v174
	v_exp_f32_e32 v175, v175
	v_exp_f32_e32 v176, v176
	v_exp_f32_e32 v177, v177
	v_mul_f32_e32 v66, v66, v181
	v_mul_f32_e32 v67, v67, v181
	v_mul_f32_e32 v68, v68, v181
	v_mul_f32_e32 v69, v69, v181
	v_add_f32_e32 v174, 1.0, v174
	v_add_f32_e32 v175, 1.0, v175
	v_add_f32_e32 v176, 1.0, v176
	v_add_f32_e32 v177, 1.0, v177
	v_rcp_f32_e32 v174, v174
	v_rcp_f32_e32 v175, v175
	v_rcp_f32_e32 v176, v176
	v_rcp_f32_e32 v177, v177
	v_mul_f32_e32 v70, v70, v174
	v_mul_f32_e32 v71, v71, v175
	v_mul_f32_e32 v72, v72, v176
	v_mul_f32_e32 v73, v73, v177
	v_mul_f32_e32 v66, v66, v70
	v_mul_f32_e32 v67, v67, v71
	v_mul_f32_e32 v68, v68, v72
	v_mul_f32_e32 v69, v69, v73
	v_cvt_pk_bf16_f32 v66, v66, v67
	v_cvt_pk_bf16_f32 v67, v68, v69
	global_store_dwordx2 v186, v[66:67], s[16:17]
	v_mul_f32_e32 v78, v78, v181
	v_mul_f32_e32 v79, v79, v181
	v_mul_f32_e32 v80, v80, v181
	v_mul_f32_e32 v81, v81, v181
	v_mul_f32_e32 v174, 0xbfb8aa3b, v78
	v_mul_f32_e32 v175, 0xbfb8aa3b, v79
	v_mul_f32_e32 v176, 0xbfb8aa3b, v80
	v_mul_f32_e32 v177, 0xbfb8aa3b, v81
	v_exp_f32_e32 v174, v174
	v_exp_f32_e32 v175, v175
	v_exp_f32_e32 v176, v176
	v_exp_f32_e32 v177, v177
	v_mul_f32_e32 v74, v74, v181
	v_mul_f32_e32 v75, v75, v181
	v_mul_f32_e32 v76, v76, v181
	v_mul_f32_e32 v77, v77, v181
	v_add_f32_e32 v174, 1.0, v174
	v_add_f32_e32 v175, 1.0, v175
	v_add_f32_e32 v176, 1.0, v176
	v_add_f32_e32 v177, 1.0, v177
	v_rcp_f32_e32 v174, v174
	v_rcp_f32_e32 v175, v175
	v_rcp_f32_e32 v176, v176
	v_rcp_f32_e32 v177, v177
	v_mul_f32_e32 v78, v78, v174
	v_mul_f32_e32 v79, v79, v175
	v_mul_f32_e32 v80, v80, v176
	v_mul_f32_e32 v81, v81, v177
	v_mul_f32_e32 v74, v74, v78
	v_mul_f32_e32 v75, v75, v79
	v_mul_f32_e32 v76, v76, v80
	v_mul_f32_e32 v77, v77, v81
	v_cvt_pk_bf16_f32 v74, v74, v75
	v_cvt_pk_bf16_f32 v75, v76, v77
	global_store_dwordx2 v186, v[74:75], s[16:17] offset:128
	s_add_u32 s16, s16, 0x70800
	s_addc_u32 s17, s17, 0
	v_mul_f32_e32 v54, v54, v182
	v_mul_f32_e32 v55, v55, v182
	v_mul_f32_e32 v56, v56, v182
	v_mul_f32_e32 v57, v57, v182
	v_mul_f32_e32 v174, 0xbfb8aa3b, v54
	v_mul_f32_e32 v175, 0xbfb8aa3b, v55
	v_mul_f32_e32 v176, 0xbfb8aa3b, v56
	v_mul_f32_e32 v177, 0xbfb8aa3b, v57
	v_exp_f32_e32 v174, v174
	v_exp_f32_e32 v175, v175
	v_exp_f32_e32 v176, v176
	v_exp_f32_e32 v177, v177
	v_mul_f32_e32 v50, v50, v182
	v_mul_f32_e32 v51, v51, v182
	v_mul_f32_e32 v52, v52, v182
	v_mul_f32_e32 v53, v53, v182
	v_add_f32_e32 v174, 1.0, v174
	v_add_f32_e32 v175, 1.0, v175
	v_add_f32_e32 v176, 1.0, v176
	v_add_f32_e32 v177, 1.0, v177
	v_rcp_f32_e32 v174, v174
	v_rcp_f32_e32 v175, v175
	v_rcp_f32_e32 v176, v176
	v_rcp_f32_e32 v177, v177
	v_mul_f32_e32 v54, v54, v174
	v_mul_f32_e32 v55, v55, v175
	v_mul_f32_e32 v56, v56, v176
	v_mul_f32_e32 v57, v57, v177
	v_mul_f32_e32 v50, v50, v54
	v_mul_f32_e32 v51, v51, v55
	v_mul_f32_e32 v52, v52, v56
	v_mul_f32_e32 v53, v53, v57
	v_cvt_pk_bf16_f32 v50, v50, v51
	v_cvt_pk_bf16_f32 v51, v52, v53
	global_store_dwordx2 v186, v[50:51], s[16:17]
	v_mul_f32_e32 v62, v62, v182
	v_mul_f32_e32 v63, v63, v182
	v_mul_f32_e32 v64, v64, v182
	v_mul_f32_e32 v65, v65, v182
	v_mul_f32_e32 v174, 0xbfb8aa3b, v62
	v_mul_f32_e32 v175, 0xbfb8aa3b, v63
	v_mul_f32_e32 v176, 0xbfb8aa3b, v64
	v_mul_f32_e32 v177, 0xbfb8aa3b, v65
	v_exp_f32_e32 v174, v174
; #define GAS __attribute__((address_space(1)))
; __device__ __forceinline__ unsigned f2bf(float f) { return pk2(f, f) & 0xffffu; }
; __device__ __forceinline__ float sigmoidf_(float v) { return __builtin_amdgcn_rcpf(1.f + __builtin_amdgcn_exp2f(-LOG2E * v)); }
; __device__ __forceinline__ void phase_up(int pass) {
;     ...
; #pragma unroll
;     for (int ai = 0; ai < 2; ++ai)
; #pragma unroll
;       for (int m = 0; m < 4; ++m)
; #pragma unroll
;         for (int j = 0; j < 4; ++j) {
;           const int rowl = ai * 128 + wr * 64 + m * 16 + fq * 4 + j;
;           const float r = rr[rowl];
; #pragma unroll
;           for (int bj = 0; bj < 2; ++bj) {
;             const float g = acc[ai][bj][m][0][j] * r, u = acc[ai][bj][m][1][j] * r;
;             const float v = g * sigmoidf_(g) * u;
;             *(GAS unsigned short*)(tb + (off0 + (unsigned)(((ai * 128 + m * 16 + j) * FFP + bj * 64) * 2))) = (unsigned short)f2bf(v);
;           }
;         }
	v_exp_f32_e32 v175, v175
	v_exp_f32_e32 v176, v176
	v_exp_f32_e32 v177, v177
	v_mul_f32_e32 v58, v58, v182
	v_mul_f32_e32 v59, v59, v182
	v_mul_f32_e32 v60, v60, v182
	v_mul_f32_e32 v61, v61, v182
	v_add_f32_e32 v174, 1.0, v174
	v_add_f32_e32 v175, 1.0, v175
	v_add_f32_e32 v176, 1.0, v176
	v_add_f32_e32 v177, 1.0, v177
	v_rcp_f32_e32 v174, v174
	v_rcp_f32_e32 v175, v175
	v_rcp_f32_e32 v176, v176
	v_rcp_f32_e32 v177, v177
	v_mul_f32_e32 v62, v62, v174
	v_mul_f32_e32 v63, v63, v175
	v_mul_f32_e32 v64, v64, v176
	v_mul_f32_e32 v65, v65, v177
	v_mul_f32_e32 v58, v58, v62
	v_mul_f32_e32 v59, v59, v63
	v_mul_f32_e32 v60, v60, v64
	v_mul_f32_e32 v61, v61, v65
	v_cvt_pk_bf16_f32 v58, v58, v59
	v_cvt_pk_bf16_f32 v59, v60, v61
	global_store_dwordx2 v186, v[58:59], s[16:17] offset:128
	s_add_u32 s16, s16, 0x16800
	s_addc_u32 s17, s17, 0
	v_mul_f32_e32 v42, v42, v183
	v_mul_f32_e32 v43, v43, v183
	v_mul_f32_e32 v44, v44, v183
	v_mul_f32_e32 v45, v45, v183
	v_mul_f32_e32 v174, 0xbfb8aa3b, v42
	v_mul_f32_e32 v175, 0xbfb8aa3b, v43
	v_mul_f32_e32 v176, 0xbfb8aa3b, v44
	v_mul_f32_e32 v177, 0xbfb8aa3b, v45
	v_exp_f32_e32 v174, v174
	v_exp_f32_e32 v175, v175
	v_exp_f32_e32 v176, v176
	v_exp_f32_e32 v177, v177
	v_mul_f32_e32 v34, v34, v183
	v_mul_f32_e32 v35, v35, v183
	v_mul_f32_e32 v36, v36, v183
	v_mul_f32_e32 v37, v37, v183
	v_add_f32_e32 v174, 1.0, v174
	v_add_f32_e32 v175, 1.0, v175
	v_add_f32_e32 v176, 1.0, v176
	v_add_f32_e32 v177, 1.0, v177
	v_rcp_f32_e32 v174, v174
	v_rcp_f32_e32 v175, v175
	v_rcp_f32_e32 v176, v176
	v_rcp_f32_e32 v177, v177
	v_mul_f32_e32 v42, v42, v174
	v_mul_f32_e32 v43, v43, v175
	v_mul_f32_e32 v44, v44, v176
	v_mul_f32_e32 v45, v45, v177
	v_mul_f32_e32 v34, v34, v42
	v_mul_f32_e32 v35, v35, v43
	v_mul_f32_e32 v36, v36, v44
	v_mul_f32_e32 v37, v37, v45
	v_cvt_pk_bf16_f32 v34, v34, v35
	v_cvt_pk_bf16_f32 v35, v36, v37
	global_store_dwordx2 v186, v[34:35], s[16:17]
	v_mul_f32_e32 v46, v46, v183
	v_mul_f32_e32 v47, v47, v183
	v_mul_f32_e32 v48, v48, v183
	v_mul_f32_e32 v49, v49, v183
	v_mul_f32_e32 v174, 0xbfb8aa3b, v46
	v_mul_f32_e32 v175, 0xbfb8aa3b, v47
	v_mul_f32_e32 v176, 0xbfb8aa3b, v48
	v_mul_f32_e32 v177, 0xbfb8aa3b, v49
	v_exp_f32_e32 v174, v174
	v_exp_f32_e32 v175, v175
	v_exp_f32_e32 v176, v176
	v_exp_f32_e32 v177, v177
	v_mul_f32_e32 v38, v38, v183
	v_mul_f32_e32 v39, v39, v183
	v_mul_f32_e32 v40, v40, v183
	v_mul_f32_e32 v41, v41, v183
	v_add_f32_e32 v174, 1.0, v174
	v_add_f32_e32 v175, 1.0, v175
	v_add_f32_e32 v176, 1.0, v176
	v_add_f32_e32 v177, 1.0, v177
	v_rcp_f32_e32 v174, v174
	v_rcp_f32_e32 v175, v175
	v_rcp_f32_e32 v176, v176
	v_rcp_f32_e32 v177, v177
	v_mul_f32_e32 v46, v46, v174
	v_mul_f32_e32 v47, v47, v175
	v_mul_f32_e32 v48, v48, v176
	v_mul_f32_e32 v49, v49, v177
	v_mul_f32_e32 v38, v38, v46
	v_mul_f32_e32 v39, v39, v47
	v_mul_f32_e32 v40, v40, v48
	v_mul_f32_e32 v41, v41, v49
	v_cvt_pk_bf16_f32 v38, v38, v39
	v_cvt_pk_bf16_f32 v39, v40, v41
	global_store_dwordx2 v186, v[38:39], s[16:17] offset:128
	s_add_u32 s16, s16, 0x16800
	s_addc_u32 s17, s17, 0
	v_mul_f32_e32 v22, v22, v184
	v_mul_f32_e32 v23, v23, v184
	v_mul_f32_e32 v24, v24, v184
	v_mul_f32_e32 v25, v25, v184
	v_mul_f32_e32 v174, 0xbfb8aa3b, v22
	v_mul_f32_e32 v175, 0xbfb8aa3b, v23
	v_mul_f32_e32 v176, 0xbfb8aa3b, v24
	v_mul_f32_e32 v177, 0xbfb8aa3b, v25
	v_exp_f32_e32 v174, v174
	v_exp_f32_e32 v175, v175
	v_exp_f32_e32 v176, v176
	v_exp_f32_e32 v177, v177
	v_mul_f32_e32 v18, v18, v184
	v_mul_f32_e32 v19, v19, v184
	v_mul_f32_e32 v20, v20, v184
	v_mul_f32_e32 v21, v21, v184
	v_add_f32_e32 v174, 1.0, v174
	v_add_f32_e32 v175, 1.0, v175
	v_add_f32_e32 v176, 1.0, v176
	v_add_f32_e32 v177, 1.0, v177
	v_rcp_f32_e32 v174, v174
	v_rcp_f32_e32 v175, v175
	v_rcp_f32_e32 v176, v176
	v_rcp_f32_e32 v177, v177
	v_mul_f32_e32 v22, v22, v174
	v_mul_f32_e32 v23, v23, v175
	v_mul_f32_e32 v24, v24, v176
	v_mul_f32_e32 v25, v25, v177
	v_mul_f32_e32 v18, v18, v22
	v_mul_f32_e32 v19, v19, v23
	v_mul_f32_e32 v20, v20, v24
	v_mul_f32_e32 v21, v21, v25
	v_cvt_pk_bf16_f32 v18, v18, v19
	v_cvt_pk_bf16_f32 v19, v20, v21
	global_store_dwordx2 v186, v[18:19], s[16:17]
	v_mul_f32_e32 v30, v30, v184
	v_mul_f32_e32 v31, v31, v184
	v_mul_f32_e32 v32, v32, v184
	v_mul_f32_e32 v33, v33, v184
	v_mul_f32_e32 v174, 0xbfb8aa3b, v30
	v_mul_f32_e32 v175, 0xbfb8aa3b, v31
	v_mul_f32_e32 v176, 0xbfb8aa3b, v32
	v_mul_f32_e32 v177, 0xbfb8aa3b, v33
; #define GAS __attribute__((address_space(1)))
; __device__ __forceinline__ unsigned f2bf(float f) { return pk2(f, f) & 0xffffu; }
; __device__ __forceinline__ float sigmoidf_(float v) { return __builtin_amdgcn_rcpf(1.f + __builtin_amdgcn_exp2f(-LOG2E * v)); }
; __device__ __forceinline__ void load_rr(const GAS float* ssq, int brow, int par) {
;     ...
;   if (tx < 256) {
;     const GAS f32x4* s = (const GAS f32x4*)(ssq + (size_t)(brow + tx) * 16);
;     f32x4 a = s[0], b = s[1], c = s[2], d = s[3];
;     float t = ((a.x + a.y) + (a.z + a.w)) + ((b.x + b.y) + (b.z + b.w)) + ((c.x + c.y) + (c.z + c.w)) + ((d.x + d.y) + (d.z + d.w));
;     rr[tx] = rsqrtf(t * (1.f / DM) + EPS);
;   }
; __device__ __forceinline__ void phase_up(int pass) {
;     ...
; #pragma unroll
;     for (int ai = 0; ai < 2; ++ai)
; #pragma unroll
;       for (int m = 0; m < 4; ++m)
; #pragma unroll
;         for (int j = 0; j < 4; ++j) {
;           const int rowl = ai * 128 + wr * 64 + m * 16 + fq * 4 + j;
;           const float r = rr[rowl];
; #pragma unroll
;           for (int bj = 0; bj < 2; ++bj) {
;             const float g = acc[ai][bj][m][0][j] * r, u = acc[ai][bj][m][1][j] * r;
;             const float v = g * sigmoidf_(g) * u;
;             *(GAS unsigned short*)(tb + (off0 + (unsigned)(((ai * 128 + m * 16 + j) * FFP + bj * 64) * 2))) = (unsigned short)f2bf(v);
;           }
;         }
	v_exp_f32_e32 v174, v174
	v_exp_f32_e32 v175, v175
	v_exp_f32_e32 v176, v176
	v_exp_f32_e32 v177, v177
	v_mul_f32_e32 v26, v26, v184
	v_mul_f32_e32 v27, v27, v184
	v_mul_f32_e32 v28, v28, v184
	v_mul_f32_e32 v29, v29, v184
	v_add_f32_e32 v174, 1.0, v174
	v_add_f32_e32 v175, 1.0, v175
	v_add_f32_e32 v176, 1.0, v176
	v_add_f32_e32 v177, 1.0, v177
	v_rcp_f32_e32 v174, v174
	v_rcp_f32_e32 v175, v175
	v_rcp_f32_e32 v176, v176
	v_rcp_f32_e32 v177, v177
	v_mul_f32_e32 v30, v30, v174
	v_mul_f32_e32 v31, v31, v175
	v_mul_f32_e32 v32, v32, v176
	v_mul_f32_e32 v33, v33, v177
	v_mul_f32_e32 v26, v26, v30
	v_mul_f32_e32 v27, v27, v31
	v_mul_f32_e32 v28, v28, v32
	v_mul_f32_e32 v29, v29, v33
	v_cvt_pk_bf16_f32 v26, v26, v27
	v_cvt_pk_bf16_f32 v27, v28, v29
	global_store_dwordx2 v186, v[26:27], s[16:17] offset:128
	s_add_u32 s16, s16, 0x16800
	s_addc_u32 s17, s17, 0
	v_mul_f32_e32 v10, v10, v185
	v_mul_f32_e32 v11, v11, v185
	v_mul_f32_e32 v12, v12, v185
	v_mul_f32_e32 v13, v13, v185
	v_mul_f32_e32 v174, 0xbfb8aa3b, v10
	v_mul_f32_e32 v175, 0xbfb8aa3b, v11
	v_mul_f32_e32 v176, 0xbfb8aa3b, v12
	v_mul_f32_e32 v177, 0xbfb8aa3b, v13
	v_exp_f32_e32 v174, v174
	v_exp_f32_e32 v175, v175
	v_exp_f32_e32 v176, v176
	v_exp_f32_e32 v177, v177
	v_mul_f32_e32 v2, v2, v185
	v_mul_f32_e32 v3, v3, v185
	v_mul_f32_e32 v4, v4, v185
	v_mul_f32_e32 v5, v5, v185
	v_add_f32_e32 v174, 1.0, v174
	v_add_f32_e32 v175, 1.0, v175
	v_add_f32_e32 v176, 1.0, v176
	v_add_f32_e32 v177, 1.0, v177
	v_rcp_f32_e32 v174, v174
	v_rcp_f32_e32 v175, v175
	v_rcp_f32_e32 v176, v176
	v_rcp_f32_e32 v177, v177
	v_mul_f32_e32 v10, v10, v174
	v_mul_f32_e32 v11, v11, v175
	v_mul_f32_e32 v12, v12, v176
	v_mul_f32_e32 v13, v13, v177
	v_mul_f32_e32 v2, v2, v10
	v_mul_f32_e32 v3, v3, v11
	v_mul_f32_e32 v4, v4, v12
	v_mul_f32_e32 v5, v5, v13
	v_cvt_pk_bf16_f32 v2, v2, v3
	v_cvt_pk_bf16_f32 v3, v4, v5
	global_store_dwordx2 v186, v[2:3], s[16:17]
	v_mul_f32_e32 v14, v14, v185
	v_mul_f32_e32 v15, v15, v185
	v_mul_f32_e32 v16, v16, v185
	v_mul_f32_e32 v17, v17, v185
	v_mul_f32_e32 v174, 0xbfb8aa3b, v14
	v_mul_f32_e32 v175, 0xbfb8aa3b, v15
	v_mul_f32_e32 v176, 0xbfb8aa3b, v16
	v_mul_f32_e32 v177, 0xbfb8aa3b, v17
	v_exp_f32_e32 v174, v174
	v_exp_f32_e32 v175, v175
	v_exp_f32_e32 v176, v176
	v_exp_f32_e32 v177, v177
	v_mul_f32_e32 v6, v6, v185
	v_mul_f32_e32 v7, v7, v185
	v_mul_f32_e32 v8, v8, v185
	v_mul_f32_e32 v9, v9, v185
	v_add_f32_e32 v174, 1.0, v174
	v_add_f32_e32 v175, 1.0, v175
	v_add_f32_e32 v176, 1.0, v176
	v_add_f32_e32 v177, 1.0, v177
	v_rcp_f32_e32 v174, v174
	v_rcp_f32_e32 v175, v175
	v_rcp_f32_e32 v176, v176
	v_rcp_f32_e32 v177, v177
	v_mul_f32_e32 v14, v14, v174
	v_mul_f32_e32 v15, v15, v175
	v_mul_f32_e32 v16, v16, v176
	v_mul_f32_e32 v17, v17, v177
	v_mul_f32_e32 v6, v6, v14
	v_mul_f32_e32 v7, v7, v15
	v_mul_f32_e32 v8, v8, v16
	v_mul_f32_e32 v9, v9, v17
	v_cvt_pk_bf16_f32 v6, v6, v7
	v_cvt_pk_bf16_f32 v7, v8, v9
	global_store_dwordx2 v186, v[6:7], s[16:17] offset:128
	s_and_b64 vcc, exec, s[14:15]
	s_cbranch_vccnz .Lup0_rr_skip
	v_cmp_gt_i32_e32 vcc, s34, v170
	s_and_saveexec_b64 s[20:21], vcc
	s_cbranch_execz .Lup0_rr_done
	s_lshl_b32 s17, s37, 10
	s_xor_b32 s17, s17, 0x400
	s_addk_i32 s17, 0x100
	v_lshl_add_u32 v130, v170, 2, s17
	v_add_u32_e32 v130, 0x20000, v130
	s_waitcnt vmcnt(16)
	v_mov_b32_e32 v132, v137
	v_mov_b32_e32 v133, v138
	v_mov_b32_e32 v137, v139
	v_mov_b32_e32 v138, v141
	v_mov_b32_e32 v139, v142
	v_mov_b32_e32 v141, v143
	v_pk_add_f32 v[132:133], v[132:133], v[136:137]
	v_pk_add_f32 v[136:137], v[138:139], v[140:141]
	v_pk_add_f32 v[132:133], v[132:133], v[132:133] op_sel:[0,1] op_sel_hi:[1,0]
	v_pk_add_f32 v[136:137], v[136:137], v[136:137] op_sel:[0,1] op_sel_hi:[1,0]
	v_add_f32_e32 v142, v144, v145
	v_add_f32_e32 v144, v146, v147
	v_mov_b32_e32 v143, v150
	v_mov_b32_e32 v145, v151
	v_mov_b32_e32 v133, v148
	v_mov_b32_e32 v137, v149
	v_pk_add_f32 v[138:139], v[142:143], v[144:145]
	v_pk_add_f32 v[132:133], v[132:133], v[136:137]
	s_nop 0
	v_pk_add_f32 v[132:133], v[132:133], v[138:139]
	s_nop 0
	v_add_f32_e32 v132, v132, v133
	v_fmamk_f32 v132, v132, 0x3a800000, v135
	v_mul_f32_e32 v133, 0x4b800000, v132
	v_cmp_gt_f32_e32 vcc, s39, v132
	s_nop 1
	v_cndmask_b32_e32 v132, v132, v133, vcc
	v_rsq_f32_e32 v132, v132
	s_nop 0
	v_mul_f32_e32 v133, 0x45800000, v132
	v_cndmask_b32_e32 v132, v132, v133, vcc
	ds_write_b32 v130, v132

; __device__ __forceinline__ int ugrid() { return __builtin_amdgcn_readfirstlane((int)gridDim.x); }
; __device__ __forceinline__ void phase_up(int pass) {
;     ...
;     L += ugrid();
;     if (L < NT_) { tile_coords(L, nN, pm, pn); gemm_prefetch<DM>(A, Wgu, pm * 256, pn * 256); load_rr(ssq, pm * 256, par ^ 1); }
;     ...
;     par ^= 1;
.Lup0_rr_skip:
	s_xor_b32 s37, s37, 1
	s_andn2_b64 vcc, exec, s[14:15]
	s_mov_b32 s41, s22
	s_cbranch_vccz .LBB0_95

; #define GAS __attribute__((address_space(1)))
; #define WAIT_V(n) asm volatile("s_waitcnt vmcnt(" #n ")" ::: "memory")
; #define BAR __builtin_amdgcn_s_barrier()
; template <int K, int LD = K>
; __device__ __forceinline__ void gemm_main(const GAS bf16* A, const GAS bf16* Bt, int brow, int bcol, f32x4 (&acc)[2][2][4][2]) {
;     ...
;   const int wid = tid_ >> 6, lane = tid_ & 63, wr = wid >> 2, wc = wid & 3, fr = lane & 15, fq = lane >> 4;
; #pragma unroll
;   for (int a = 0; a < 2; ++a)
; #pragma unroll
;     for (int b = 0; b < 2; ++b)
; #pragma unroll
;       for (int m = 0; m < 4; ++m)
; #pragma unroll
;         for (int n = 0; n < 2; ++n) acc[a][b][m][n] = f32x4{0.f, 0.f, 0.f, 0.f};
;   bf16x8 At[4][2], B0[2][2], B1[2][2];
;   unsigned so0, so1;
;   { int r_, c_; stage_rc(tid_ * 16, r_, c_); so0 = (unsigned)(r_ * LD + c_) * 2u; stage_rc(tid_ * 16 + 8192, r_, c_); so1 = (unsigned)(r_ * LD + c_) * 2u; }
;   const GAS char* pA0 = (const GAS char*)A + (long)brow * LD * 2; const GAS char* pA1 = pA0 + (long)HALF * LD * 2;
;   const GAS char* pB0 = (const GAS char*)Bt + (long)bcol * LD * 2; const GAS char* pB1 = pB0 + (long)HALF * LD * 2;
;   asm volatile("" : "+s"(pA0), "+s"(pA1), "+s"(pB0), "+s"(pB1));
;   constexpr int nt = K / BK;
;   static_assert(K % 128 == 0 && K >= 256, "K");
;   if (wr == 1) BAR;
;   WAIT_V(0); BAR;
;   BAR;
.LBB0_88:
	s_or_b64 exec, exec, s[24:25]
	v_bfe_i32 v7, v136, 27, 1
	v_lshlrev_b32_e32 v5, 4, v136
	v_lshrrev_b32_e32 v7, 22, v7
	v_add_u32_e32 v7, v5, v7
	v_and_b32_e32 v7, 0xfffffc00, v7
	v_sub_u32_e32 v7, v5, v7
	v_lshrrev_b32_e32 v8, 4, v7
	v_bitop3_b32 v8, v8, v7, 32 bitop3:0x6c
	v_ashrrev_i32_e32 v7, 31, v7
	v_ashrrev_i32_e32 v6, 31, v136
	v_lshrrev_b32_e32 v7, 26, v7
	v_lshrrev_b32_e32 v6, 26, v6
	v_add_u32_e32 v7, v8, v7
	v_add_u32_e32 v6, v136, v6
	v_ashrrev_i32_e32 v7, 6, v7
	v_ashrrev_i32_e32 v6, 6, v6
	v_mul_i32_i24_e32 v10, 64, v7
	v_lshlrev_b32_e32 v9, 3, v6
	v_lshlrev_b32_e32 v6, 5, v6
	v_sub_u32_e32 v8, v8, v10
	v_and_b32_e32 v9, 0x1ffff0, v9
	v_and_b32_e32 v6, 32, v6
	v_ashrrev_i16_sdwa v8, v134, sext(v8) dst_sel:DWORD dst_unused:UNUSED_PAD src0_sel:DWORD src1_sel:BYTE_0
	v_add_u32_sdwa v6, v6, sext(v8) dst_sel:DWORD dst_unused:UNUSED_PAD src0_sel:DWORD src1_sel:WORD_0
	v_add_lshl_u32 v7, v7, v9, 11
	v_lshl_add_u32 v130, v6, 1, v7
	v_add_u32_e32 v6, 0x2000, v5
	v_ashrrev_i32_e32 v7, 31, v6
	v_lshrrev_b32_e32 v7, 22, v7
	v_add_u32_e32 v7, v6, v7
	v_ashrrev_i32_e32 v7, 10, v7
	v_mul_i32_i24_e32 v8, 0x400, v7
	v_sub_u32_e32 v6, v6, v8
	v_lshrrev_b32_e32 v8, 4, v6
	v_bitop3_b32 v6, v8, v6, 32 bitop3:0x6c
	v_ashrrev_i32_e32 v9, 31, v6
	v_lshrrev_b32_e32 v9, 26, v9
	v_add_u32_e32 v9, v6, v9
	v_lshrrev_b32_e32 v10, 6, v9
	v_and_b32_e32 v9, 0xc0, v9
	v_lshlrev_b32_e32 v8, 3, v7
	v_lshlrev_b32_e32 v7, 5, v7
	v_sub_u32_e32 v6, v6, v9
	v_and_b32_e32 v8, 0x1ffff0, v8
	v_and_b32_e32 v7, 32, v7
	v_ashrrev_i16_sdwa v6, v134, sext(v6) dst_sel:DWORD dst_unused:UNUSED_PAD src0_sel:DWORD src1_sel:BYTE_0
	v_add_u32_sdwa v6, v7, sext(v6) dst_sel:DWORD dst_unused:UNUSED_PAD src0_sel:DWORD src1_sel:WORD_0
	v_add_lshl_u32 v7, v10, v8, 11
	v_and_b32_e32 v3, 15, v136
	v_lshl_add_u32 v132, v6, 1, v7
	v_lshlrev_b32_e32 v6, 2, v136
	v_and_b32_e32 v4, 48, v136
	v_lshlrev_b32_e32 v3, 6, v3
	v_and_b32_e32 v6, 32, v6
	v_lshlrev_b32_e32 v11, 6, v136
	s_waitcnt vmcnt(16)
	v_bitop3_b32 v3, v3, v6, v4 bitop3:0x36
	v_lshlrev_b32_e32 v13, 13, v2
	v_and_or_b32 v2, v11, s38, v4
	v_add_u32_e32 v7, s29, v3
	v_add_u32_e32 v8, s30, v3
	v_add_u32_e32 v9, s31, v3
	v_add_u32_e32 v10, s33, v3
	v_and_b32_e32 v12, 0x3000, v11
	v_add_u32_e32 v3, 0x100, v3
	v_xad_u32 v4, v2, v6, s34
	v_or_b32_e32 v6, 0x800, v13
	v_or_b32_e32 v11, 0x1000, v13
	v_or_b32_e32 v14, 0x1800, v13
	v_mov_b32_e32 v2, 0
	v_add_u32_e32 v145, 0x100, v5
	v_add_u32_e32 v146, s29, v5
	v_add_u32_e32 v147, s30, v5
	v_add_u32_e32 v148, s31, v5
	v_add_u32_e32 v149, s33, v5
	v_mov_b32_e32 v133, v131
	s_mov_b32 s17, -2
	v_add_u32_e32 v144, v7, v12
	v_add_u32_e32 v140, v3, v13
	v_add_u32_e32 v139, v4, v6
	v_add_u32_e32 v138, v4, v11
	v_add_u32_e32 v137, v4, v14
	v_add_u32_e32 v143, v8, v12
	v_add_u32_e32 v142, v9, v12
	v_add_u32_e32 v141, v10, v12
	v_mov_b32_e32 v3, v2
	v_mov_b32_e32 v4, v2
	v_mov_b32_e32 v5, v2
	v_mov_b32_e32 v6, v2
	v_mov_b32_e32 v7, v2
	v_mov_b32_e32 v8, v2
	v_mov_b32_e32 v9, v2
	v_mov_b32_e32 v10, v2
	v_mov_b32_e32 v11, v2
	v_mov_b32_e32 v12, v2
	v_mov_b32_e32 v13, v2
	v_mov_b32_e32 v14, v2
	v_mov_b32_e32 v15, v2
	v_mov_b32_e32 v16, v2
	v_mov_b32_e32 v17, v2
	v_mov_b32_e32 v18, v2
	v_mov_b32_e32 v19, v2
	v_mov_b32_e32 v20, v2
	v_mov_b32_e32 v21, v2
	v_mov_b32_e32 v22, v2
	v_mov_b32_e32 v23, v2
	v_mov_b32_e32 v24, v2
	v_mov_b32_e32 v25, v2
	v_mov_b32_e32 v26, v2
	v_mov_b32_e32 v27, v2
	v_mov_b32_e32 v28, v2
	v_mov_b32_e32 v29, v2
	v_mov_b32_e32 v30, v2
	v_mov_b32_e32 v31, v2
	v_mov_b32_e32 v32, v2
	v_mov_b32_e32 v33, v2
	v_mov_b32_e32 v34, v2
	v_mov_b32_e32 v35, v2
	v_mov_b32_e32 v36, v2
	v_mov_b32_e32 v37, v2
	v_mov_b32_e32 v38, v2
	v_mov_b32_e32 v39, v2
	v_mov_b32_e32 v40, v2
	v_mov_b32_e32 v41, v2
	v_mov_b32_e32 v42, v2
	v_mov_b32_e32 v43, v2
	v_mov_b32_e32 v44, v2
	v_mov_b32_e32 v45, v2
	v_mov_b32_e32 v46, v2
	v_mov_b32_e32 v47, v2
	v_mov_b32_e32 v48, v2
	v_mov_b32_e32 v49, v2
	v_mov_b32_e32 v50, v2
	v_mov_b32_e32 v51, v2
	v_mov_b32_e32 v52, v2
	v_mov_b32_e32 v53, v2
	v_mov_b32_e32 v54, v2
	v_mov_b32_e32 v55, v2
	v_mov_b32_e32 v56, v2
	v_mov_b32_e32 v57, v2
	v_mov_b32_e32 v58, v2
	v_mov_b32_e32 v59, v2
	v_mov_b32_e32 v60, v2
	v_mov_b32_e32 v61, v2
	v_mov_b32_e32 v62, v2
	v_mov_b32_e32 v63, v2
	v_mov_b32_e32 v64, v2
	v_mov_b32_e32 v65, v2
	v_mov_b32_e32 v66, v2
	v_mov_b32_e32 v67, v2
	v_mov_b32_e32 v68, v2
	v_mov_b32_e32 v69, v2
	v_mov_b32_e32 v70, v2
	v_mov_b32_e32 v71, v2
	v_mov_b32_e32 v72, v2
	v_mov_b32_e32 v73, v2
	v_mov_b32_e32 v74, v2
	v_mov_b32_e32 v75, v2
	v_mov_b32_e32 v76, v2
	v_mov_b32_e32 v77, v2
	v_mov_b32_e32 v78, v2
	v_mov_b32_e32 v79, v2
	v_mov_b32_e32 v80, v2
	v_mov_b32_e32 v81, v2
	v_mov_b32_e32 v82, v2
	v_mov_b32_e32 v83, v2
	v_mov_b32_e32 v84, v2
	v_mov_b32_e32 v85, v2
	v_mov_b32_e32 v86, v2
	v_mov_b32_e32 v87, v2
	v_mov_b32_e32 v88, v2
	v_mov_b32_e32 v89, v2
	v_mov_b32_e32 v90, v2
	v_mov_b32_e32 v91, v2
	v_mov_b32_e32 v92, v2
	v_mov_b32_e32 v93, v2
	v_mov_b32_e32 v94, v2
	v_mov_b32_e32 v95, v2
	v_mov_b32_e32 v96, v2
	v_mov_b32_e32 v97, v2
	v_mov_b32_e32 v98, v2
	v_mov_b32_e32 v99, v2
	v_mov_b32_e32 v100, v2
	v_mov_b32_e32 v101, v2
	v_mov_b32_e32 v102, v2
	v_mov_b32_e32 v103, v2
	v_mov_b32_e32 v104, v2
	v_mov_b32_e32 v105, v2
	v_mov_b32_e32 v106, v2
	v_mov_b32_e32 v107, v2
	v_mov_b32_e32 v108, v2
	v_mov_b32_e32 v109, v2
	v_mov_b32_e32 v110, v2
	v_mov_b32_e32 v111, v2
	v_mov_b32_e32 v112, v2
	v_mov_b32_e32 v113, v2
	v_mov_b32_e32 v114, v2
	v_mov_b32_e32 v115, v2
	v_mov_b32_e32 v116, v2
	v_mov_b32_e32 v117, v2
	v_mov_b32_e32 v118, v2
	v_mov_b32_e32 v119, v2
	v_mov_b32_e32 v120, v2
	v_mov_b32_e32 v121, v2
	v_mov_b32_e32 v122, v2
	v_mov_b32_e32 v123, v2
	v_mov_b32_e32 v124, v2
	v_mov_b32_e32 v125, v2
	v_mov_b32_e32 v126, v2
	v_mov_b32_e32 v127, v2
	v_mov_b32_e32 v128, v2
	v_mov_b32_e32 v129, v2
	v_add_u32_e32 v151, 0xc000, v145
	v_add_u32_e32 v150, 0xe000, v145
	v_add_u32_e32 v152, 0x2000, v145
	v_add_u32_e32 v153, 0x4000, v145
	v_add_u32_e32 v154, 0x6000, v145
	v_add_u32_e32 v155, 0x8000, v145
	v_add_u32_e32 v156, 0xa000, v145
	v_add_u32_e32 v157, 0x2000, v146
	v_add_u32_e32 v158, 0x2000, v147
	v_add_u32_e32 v159, 0x2000, v148
	v_add_u32_e32 v160, 0x2000, v149
	s_barrier
	s_barrier
; #define STAGE(P, GP, ktrel) do { const GAS char* _g = (GP) + (ktrel) * (BK * 2); \
;     __builtin_amdgcn_global_load_lds((const GAS unsigned*)(_g + so0), (unsigned*)((char*)(P) + tid_ * 16), 16, 0, 0); \
;     __builtin_amdgcn_global_load_lds((const GAS unsigned*)(_g + so1), (unsigned*)((char*)(P) + tid_ * 16 + 8192), 16, 0, 0); } while (0)
; #define WAIT_V(n) asm volatile("s_waitcnt vmcnt(" #n ")" ::: "memory")
; #define WAIT_L(n) asm volatile("s_waitcnt lgkmcnt(" #n ")" ::: "memory")
; #define BAR __builtin_amdgcn_s_barrier()
; #define SCHED __builtin_amdgcn_sched_barrier(0)
; #define LDA(dst, b, h) for (int m = 0; m < 4; ++m) for (int k = 0; k < 2; ++k) \
;     dst[m][k] = *reinterpret_cast<const bf16x8*>((char*)SA(b, h) + lds_byte(wr * 64 + m * 16 + fr, k * 32 + fq * 8))
; #define LDB(dst, b, h) for (int n = 0; n < 2; ++n) for (int k = 0; k < 2; ++k) \
;     dst[n][k] = *reinterpret_cast<const bf16x8*>((char*)SB(b, h) + lds_byte(wc * 32 + n * 16 + fr, k * 32 + fq * 8))
; #define MMA(ai, bj, At_, Bt_) do { __builtin_amdgcn_s_setprio(1); \
;     for (int m = 0; m < 4; ++m) for (int n = 0; n < 2; ++n) for (int k = 0; k < 2; ++k) \
;       acc[ai][bj][m][n] = __builtin_amdgcn_mfma_f32_16x16x32_bf16(At_[m][k], Bt_[n][k], acc[ai][bj][m][n], 0, 0, 0); \
;     __builtin_amdgcn_s_setprio(0); } while (0)
; template <int K, int LD = K>
; __device__ __forceinline__ void gemm_main(const GAS bf16* A, const GAS bf16* Bt, int brow, int bcol, f32x4 (&acc)[2][2][4][2]) {
;     ...
;   for (int t = 0; t < nt - 2; t += 2) {
;     LDB(B0, 0, 0); SCHED; LDA(At, 0, 0); STAGE(SA(1, 1), pA1, 1);
;     WAIT_L(8); BAR; WAIT_L(0); MMA(0, 0, At, B0); BAR; SCHED;
;     LDB(B1, 0, 1); STAGE(SB(0, 0), pB0, 2);
;     BAR; WAIT_L(0); MMA(0, 1, At, B1); BAR;
;     LDA(At, 0, 1); STAGE(SA(0, 0), pA0, 2);
;     BAR; WAIT_L(0); MMA(1, 0, At, B0); BAR; SCHED;
;     STAGE(SB(0, 1), pB1, 2);
;     WAIT_V(6); BAR; MMA(1, 1, At, B1); BAR;
;     LDB(B0, 1, 0); SCHED; LDA(At, 1, 0); STAGE(SA(0, 1), pA1, 2);
;     WAIT_L(8); BAR; WAIT_L(0); MMA(0, 0, At, B0); BAR; SCHED;
.LBB0_89:
	ds_read_b128 v[162:165], v144
	ds_read_b128 v[166:169], v144 offset:1024
	ds_read_b128 v[174:177], v144 offset:2048
	ds_read_b128 v[178:181], v144 offset:3072
	v_lshl_add_u64 v[230:231], s[14:15], 0, v[130:131]
	v_readfirstlane_b32 s24, v151
	v_lshl_add_u64 v[214:215], v[230:231], 0, s[8:9]
	s_mov_b32 m0, s24
	v_lshl_add_u64 v[232:233], s[14:15], 0, v[132:133]
	v_readfirstlane_b32 s24, v150
	ds_read_b128 v[182:185], v140
	ds_read_b128 v[186:189], v140 offset:1024
	ds_read_b128 v[190:193], v139
	ds_read_b128 v[194:197], v139 offset:1024
	ds_read_b128 v[198:201], v138
	ds_read_b128 v[202:205], v138 offset:1024
	ds_read_b128 v[206:209], v137
	ds_read_b128 v[210:213], v137 offset:1024
	global_load_lds_dwordx4 v[214:215], off
	v_lshl_add_u64 v[214:215], v[232:233], 0, s[8:9]
	s_mov_b32 m0, s24
	s_nop 0
	global_load_lds_dwordx4 v[214:215], off
	s_waitcnt lgkmcnt(8)
	s_barrier
	s_waitcnt lgkmcnt(0)
	s_setprio 1
	s_waitcnt lgkmcnt(0)
	v_mfma_f32_16x16x32_bf16 v[126:129], v[162:165], v[182:185], v[126:129]
	v_mfma_f32_16x16x32_bf16 v[122:125], v[174:177], v[182:185], v[122:125]
	v_mfma_f32_16x16x32_bf16 v[118:121], v[162:165], v[190:193], v[118:121]
	v_mfma_f32_16x16x32_bf16 v[114:117], v[174:177], v[190:193], v[114:117]
	v_mfma_f32_16x16x32_bf16 v[110:113], v[162:165], v[198:201], v[110:113]
	v_mfma_f32_16x16x32_bf16 v[106:109], v[174:177], v[198:201], v[106:109]
	v_mfma_f32_16x16x32_bf16 v[102:105], v[162:165], v[206:209], v[102:105]
	v_mfma_f32_16x16x32_bf16 v[98:101], v[174:177], v[206:209], v[98:101]
	v_mfma_f32_16x16x32_bf16 v[126:129], v[166:169], v[186:189], v[126:129]
	v_mfma_f32_16x16x32_bf16 v[122:125], v[178:181], v[186:189], v[122:125]
	v_mfma_f32_16x16x32_bf16 v[118:121], v[166:169], v[194:197], v[118:121]
	v_mfma_f32_16x16x32_bf16 v[114:117], v[178:181], v[194:197], v[114:117]
	v_mfma_f32_16x16x32_bf16 v[110:113], v[166:169], v[202:205], v[110:113]
	v_mfma_f32_16x16x32_bf16 v[106:109], v[178:181], v[202:205], v[106:109]
	v_mfma_f32_16x16x32_bf16 v[102:105], v[166:169], v[210:213], v[102:105]
	v_mfma_f32_16x16x32_bf16 v[98:101], v[178:181], v[210:213], v[98:101]
	s_setprio 0
	s_barrier
	v_lshl_add_u64 v[234:235], s[22:23], 0, v[130:131]
	v_readfirstlane_b32 s24, v146
	v_lshl_add_u64 v[236:237], v[234:235], 0, s[10:11]
	s_mov_b32 m0, s24
	ds_read_b128 v[214:217], v143
	ds_read_b128 v[218:221], v143 offset:1024
	ds_read_b128 v[222:225], v143 offset:2048
	ds_read_b128 v[226:229], v143 offset:3072
	global_load_lds_dwordx4 v[236:237], off
	v_lshl_add_u64 v[236:237], s[22:23], 0, v[132:133]
	v_readfirstlane_b32 s24, v157
	v_lshl_add_u64 v[238:239], v[236:237], 0, s[10:11]
	s_mov_b32 m0, s24
	s_add_u32 s22, s22, 0x100
	global_load_lds_dwordx4 v[238:239], off
	s_barrier
	s_waitcnt lgkmcnt(0)
	s_addc_u32 s23, s23, 0
	s_setprio 1
	s_waitcnt lgkmcnt(0)
	v_mfma_f32_16x16x32_bf16 v[94:97], v[214:217], v[182:185], v[94:97]
	v_mfma_f32_16x16x32_bf16 v[90:93], v[222:225], v[182:185], v[90:93]
	v_mfma_f32_16x16x32_bf16 v[86:89], v[214:217], v[190:193], v[86:89]
	v_mfma_f32_16x16x32_bf16 v[82:85], v[222:225], v[190:193], v[82:85]
	v_mfma_f32_16x16x32_bf16 v[78:81], v[214:217], v[198:201], v[78:81]
	v_mfma_f32_16x16x32_bf16 v[74:77], v[222:225], v[198:201], v[74:77]
	v_mfma_f32_16x16x32_bf16 v[70:73], v[214:217], v[206:209], v[70:73]
	v_mfma_f32_16x16x32_bf16 v[66:69], v[222:225], v[206:209], v[66:69]
	v_mfma_f32_16x16x32_bf16 v[94:97], v[218:221], v[186:189], v[94:97]
	v_mfma_f32_16x16x32_bf16 v[90:93], v[226:229], v[186:189], v[90:93]
	v_mfma_f32_16x16x32_bf16 v[86:89], v[218:221], v[194:197], v[86:89]
	v_mfma_f32_16x16x32_bf16 v[82:85], v[226:229], v[194:197], v[82:85]
	v_mfma_f32_16x16x32_bf16 v[78:81], v[218:221], v[202:205], v[78:81]
	v_mfma_f32_16x16x32_bf16 v[74:77], v[226:229], v[202:205], v[74:77]
	v_mfma_f32_16x16x32_bf16 v[70:73], v[218:221], v[210:213], v[70:73]
	v_mfma_f32_16x16x32_bf16 v[66:69], v[226:229], v[210:213], v[66:69]
	s_setprio 0
	v_lshl_add_u64 v[238:239], s[20:21], 0, v[130:131]
	v_readfirstlane_b32 s24, v145
	v_lshl_add_u64 v[240:241], v[238:239], 0, s[10:11]
	s_mov_b32 m0, s24
	s_barrier
	ds_read_b128 v[182:185], v140 offset:16384
	ds_read_b128 v[186:189], v140 offset:17408
	ds_read_b128 v[190:193], v139 offset:16384
	ds_read_b128 v[194:197], v139 offset:17408
	ds_read_b128 v[198:201], v138 offset:16384
	ds_read_b128 v[202:205], v138 offset:17408
	ds_read_b128 v[206:209], v137 offset:16384
	ds_read_b128 v[210:213], v137 offset:17408
	global_load_lds_dwordx4 v[240:241], off
	v_lshl_add_u64 v[240:241], s[20:21], 0, v[132:133]
	v_readfirstlane_b32 s24, v152
	v_lshl_add_u64 v[242:243], v[240:241], 0, s[10:11]
	s_mov_b32 m0, s24
	s_add_u32 s20, s20, 0x100
	global_load_lds_dwordx4 v[242:243], off
	s_barrier
	s_waitcnt lgkmcnt(0)
	s_addc_u32 s21, s21, 0
	s_setprio 1
	s_waitcnt lgkmcnt(0)
	v_mfma_f32_16x16x32_bf16 v[62:65], v[162:165], v[182:185], v[62:65]
	v_mfma_f32_16x16x32_bf16 v[58:61], v[174:177], v[182:185], v[58:61]
	v_mfma_f32_16x16x32_bf16 v[54:57], v[162:165], v[190:193], v[54:57]
	v_mfma_f32_16x16x32_bf16 v[50:53], v[174:177], v[190:193], v[50:53]
	v_mfma_f32_16x16x32_bf16 v[46:49], v[162:165], v[198:201], v[46:49]
	v_mfma_f32_16x16x32_bf16 v[42:45], v[174:177], v[198:201], v[42:45]
	v_mfma_f32_16x16x32_bf16 v[38:41], v[162:165], v[206:209], v[38:41]
	v_mfma_f32_16x16x32_bf16 v[34:37], v[174:177], v[206:209], v[34:37]
	v_mfma_f32_16x16x32_bf16 v[62:65], v[166:169], v[186:189], v[62:65]
	v_mfma_f32_16x16x32_bf16 v[58:61], v[178:181], v[186:189], v[58:61]
	v_mfma_f32_16x16x32_bf16 v[54:57], v[166:169], v[194:197], v[54:57]
	v_mfma_f32_16x16x32_bf16 v[50:53], v[178:181], v[194:197], v[50:53]
	v_mfma_f32_16x16x32_bf16 v[46:49], v[166:169], v[202:205], v[46:49]
	v_mfma_f32_16x16x32_bf16 v[42:45], v[178:181], v[202:205], v[42:45]
	v_mfma_f32_16x16x32_bf16 v[38:41], v[166:169], v[210:213], v[38:41]
	v_mfma_f32_16x16x32_bf16 v[34:37], v[178:181], v[210:213], v[34:37]
	s_setprio 0
	s_barrier
; #define STAGE(P, GP, ktrel) do { const GAS char* _g = (GP) + (ktrel) * (BK * 2); \
;     __builtin_amdgcn_global_load_lds((const GAS unsigned*)(_g + so0), (unsigned*)((char*)(P) + tid_ * 16), 16, 0, 0); \
;     __builtin_amdgcn_global_load_lds((const GAS unsigned*)(_g + so1), (unsigned*)((char*)(P) + tid_ * 16 + 8192), 16, 0, 0); } while (0)
; #define WAIT_V(n) asm volatile("s_waitcnt vmcnt(" #n ")" ::: "memory")
; #define WAIT_L(n) asm volatile("s_waitcnt lgkmcnt(" #n ")" ::: "memory")
; #define BAR __builtin_amdgcn_s_barrier()
; #define SCHED __builtin_amdgcn_sched_barrier(0)
; #define LDA(dst, b, h) for (int m = 0; m < 4; ++m) for (int k = 0; k < 2; ++k) \
;     dst[m][k] = *reinterpret_cast<const bf16x8*>((char*)SA(b, h) + lds_byte(wr * 64 + m * 16 + fr, k * 32 + fq * 8))
; #define LDB(dst, b, h) for (int n = 0; n < 2; ++n) for (int k = 0; k < 2; ++k) \
;     dst[n][k] = *reinterpret_cast<const bf16x8*>((char*)SB(b, h) + lds_byte(wc * 32 + n * 16 + fr, k * 32 + fq * 8))
; #define MMA(ai, bj, At_, Bt_) do { __builtin_amdgcn_s_setprio(1); \
;     for (int m = 0; m < 4; ++m) for (int n = 0; n < 2; ++n) for (int k = 0; k < 2; ++k) \
;       acc[ai][bj][m][n] = __builtin_amdgcn_mfma_f32_16x16x32_bf16(At_[m][k], Bt_[n][k], acc[ai][bj][m][n], 0, 0, 0); \
;     __builtin_amdgcn_s_setprio(0); } while (0)
; template <int K, int LD = K>
; __device__ __forceinline__ void gemm_main(const GAS bf16* A, const GAS bf16* Bt, int brow, int bcol, f32x4 (&acc)[2][2][4][2]) {
;     ...
;     WAIT_V(6); BAR; MMA(1, 1, At, B1); BAR;
;     LDB(B0, 1, 0); SCHED; LDA(At, 1, 0); STAGE(SA(0, 1), pA1, 2);
;     WAIT_L(8); BAR; WAIT_L(0); MMA(0, 0, At, B0); BAR; SCHED;
;     LDB(B1, 1, 1); STAGE(SB(1, 0), pB0, 3);
;     BAR; WAIT_L(0); MMA(0, 1, At, B1); BAR;
;     LDA(At, 1, 1); STAGE(SA(1, 0), pA0, 3);
;     BAR; WAIT_L(0); MMA(1, 0, At, B0); BAR; SCHED;
	v_lshl_add_u64 v[242:243], s[18:19], 0, v[130:131]
	v_readfirstlane_b32 s24, v147
	v_lshl_add_u64 v[162:163], v[242:243], 0, s[10:11]
	s_mov_b32 m0, s24
	v_lshl_add_u64 v[244:245], s[18:19], 0, v[132:133]
	v_readfirstlane_b32 s24, v158
	global_load_lds_dwordx4 v[162:163], off
	v_lshl_add_u64 v[162:163], v[244:245], 0, s[10:11]
	s_mov_b32 m0, s24
	s_add_u32 s18, s18, 0x100
	global_load_lds_dwordx4 v[162:163], off
	s_waitcnt vmcnt(6)
	s_addc_u32 s19, s19, 0
	s_barrier
	s_setprio 1
	v_mfma_f32_16x16x32_bf16 v[30:33], v[214:217], v[182:185], v[30:33]
	v_mfma_f32_16x16x32_bf16 v[26:29], v[222:225], v[182:185], v[26:29]
	v_mfma_f32_16x16x32_bf16 v[22:25], v[214:217], v[190:193], v[22:25]
	v_mfma_f32_16x16x32_bf16 v[18:21], v[222:225], v[190:193], v[18:21]
	v_mfma_f32_16x16x32_bf16 v[14:17], v[214:217], v[198:201], v[14:17]
	v_mfma_f32_16x16x32_bf16 v[10:13], v[222:225], v[198:201], v[10:13]
	v_mfma_f32_16x16x32_bf16 v[6:9], v[214:217], v[206:209], v[6:9]
	v_mfma_f32_16x16x32_bf16 v[2:5], v[222:225], v[206:209], v[2:5]
	v_mfma_f32_16x16x32_bf16 v[30:33], v[218:221], v[186:189], v[30:33]
	v_mfma_f32_16x16x32_bf16 v[26:29], v[226:229], v[186:189], v[26:29]
	v_mfma_f32_16x16x32_bf16 v[22:25], v[218:221], v[194:197], v[22:25]
	v_mfma_f32_16x16x32_bf16 v[18:21], v[226:229], v[194:197], v[18:21]
	v_mfma_f32_16x16x32_bf16 v[14:17], v[218:221], v[202:205], v[14:17]
	v_mfma_f32_16x16x32_bf16 v[10:13], v[226:229], v[202:205], v[10:13]
	v_mfma_f32_16x16x32_bf16 v[6:9], v[218:221], v[210:213], v[6:9]
	v_mfma_f32_16x16x32_bf16 v[2:5], v[226:229], v[210:213], v[2:5]
	s_setprio 0
	s_barrier
	ds_read_b128 v[162:165], v142
	ds_read_b128 v[166:169], v142 offset:1024
	ds_read_b128 v[174:177], v142 offset:2048
	ds_read_b128 v[178:181], v142 offset:3072
	v_readfirstlane_b32 s24, v153
	v_lshl_add_u64 v[214:215], v[230:231], 0, s[10:11]
	s_mov_b32 m0, s24
	v_readfirstlane_b32 s24, v154
	ds_read_b128 v[182:185], v140 offset:32768
	ds_read_b128 v[186:189], v140 offset:33792
	ds_read_b128 v[190:193], v139 offset:32768
	ds_read_b128 v[194:197], v139 offset:33792
	ds_read_b128 v[198:201], v138 offset:32768
	ds_read_b128 v[202:205], v138 offset:33792
	ds_read_b128 v[206:209], v137 offset:32768
	ds_read_b128 v[210:213], v137 offset:33792
	global_load_lds_dwordx4 v[214:215], off
	v_lshl_add_u64 v[214:215], v[232:233], 0, s[10:11]
	s_mov_b32 m0, s24
	s_add_u32 s14, s14, 0x100
	global_load_lds_dwordx4 v[214:215], off
	s_waitcnt lgkmcnt(8)
	s_barrier
	s_waitcnt lgkmcnt(0)
	s_addc_u32 s15, s15, 0
	s_setprio 1
	s_waitcnt lgkmcnt(0)
	v_mfma_f32_16x16x32_bf16 v[126:129], v[162:165], v[182:185], v[126:129]
	v_mfma_f32_16x16x32_bf16 v[122:125], v[174:177], v[182:185], v[122:125]
	v_mfma_f32_16x16x32_bf16 v[118:121], v[162:165], v[190:193], v[118:121]
	v_mfma_f32_16x16x32_bf16 v[114:117], v[174:177], v[190:193], v[114:117]
	v_mfma_f32_16x16x32_bf16 v[110:113], v[162:165], v[198:201], v[110:113]
	v_mfma_f32_16x16x32_bf16 v[106:109], v[174:177], v[198:201], v[106:109]
	v_mfma_f32_16x16x32_bf16 v[102:105], v[162:165], v[206:209], v[102:105]
	v_mfma_f32_16x16x32_bf16 v[98:101], v[174:177], v[206:209], v[98:101]
	v_mfma_f32_16x16x32_bf16 v[126:129], v[166:169], v[186:189], v[126:129]
	v_mfma_f32_16x16x32_bf16 v[122:125], v[178:181], v[186:189], v[122:125]
	v_mfma_f32_16x16x32_bf16 v[118:121], v[166:169], v[194:197], v[118:121]
	v_mfma_f32_16x16x32_bf16 v[114:117], v[178:181], v[194:197], v[114:117]
	v_mfma_f32_16x16x32_bf16 v[110:113], v[166:169], v[202:205], v[110:113]
	v_mfma_f32_16x16x32_bf16 v[106:109], v[178:181], v[202:205], v[106:109]
	v_mfma_f32_16x16x32_bf16 v[102:105], v[166:169], v[210:213], v[102:105]
	v_mfma_f32_16x16x32_bf16 v[98:101], v[178:181], v[210:213], v[98:101]
	s_setprio 0
	s_barrier
	v_readfirstlane_b32 s24, v148
	v_lshl_add_u64 v[230:231], v[234:235], 0, s[12:13]
	s_mov_b32 m0, s24
	v_readfirstlane_b32 s24, v159
	ds_read_b128 v[214:217], v141
	ds_read_b128 v[218:221], v141 offset:1024
	ds_read_b128 v[222:225], v141 offset:2048
	ds_read_b128 v[226:229], v141 offset:3072
	global_load_lds_dwordx4 v[230:231], off
	v_lshl_add_u64 v[230:231], v[236:237], 0, s[12:13]
	s_mov_b32 m0, s24
	s_nop 0
	global_load_lds_dwordx4 v[230:231], off
	s_barrier
	s_waitcnt lgkmcnt(0)
	s_setprio 1
	s_waitcnt lgkmcnt(0)
	v_mfma_f32_16x16x32_bf16 v[94:97], v[214:217], v[182:185], v[94:97]
	v_mfma_f32_16x16x32_bf16 v[90:93], v[222:225], v[182:185], v[90:93]
	v_mfma_f32_16x16x32_bf16 v[86:89], v[214:217], v[190:193], v[86:89]
	v_mfma_f32_16x16x32_bf16 v[82:85], v[222:225], v[190:193], v[82:85]
	v_mfma_f32_16x16x32_bf16 v[78:81], v[214:217], v[198:201], v[78:81]
	v_mfma_f32_16x16x32_bf16 v[74:77], v[222:225], v[198:201], v[74:77]
	v_mfma_f32_16x16x32_bf16 v[70:73], v[214:217], v[206:209], v[70:73]
	v_mfma_f32_16x16x32_bf16 v[66:69], v[222:225], v[206:209], v[66:69]
	v_mfma_f32_16x16x32_bf16 v[94:97], v[218:221], v[186:189], v[94:97]
	v_mfma_f32_16x16x32_bf16 v[90:93], v[226:229], v[186:189], v[90:93]
	v_mfma_f32_16x16x32_bf16 v[86:89], v[218:221], v[194:197], v[86:89]
	v_mfma_f32_16x16x32_bf16 v[82:85], v[226:229], v[194:197], v[82:85]
	v_mfma_f32_16x16x32_bf16 v[78:81], v[218:221], v[202:205], v[78:81]
	v_mfma_f32_16x16x32_bf16 v[74:77], v[226:229], v[202:205], v[74:77]
	v_mfma_f32_16x16x32_bf16 v[70:73], v[218:221], v[210:213], v[70:73]
	v_mfma_f32_16x16x32_bf16 v[66:69], v[226:229], v[210:213], v[66:69]
	s_setprio 0
	v_readfirstlane_b32 s24, v155
	v_lshl_add_u64 v[230:231], v[238:239], 0, s[12:13]
	s_mov_b32 m0, s24
	v_readfirstlane_b32 s24, v156
	s_barrier
; #define STAGE(P, GP, ktrel) do { const GAS char* _g = (GP) + (ktrel) * (BK * 2); \
;     __builtin_amdgcn_global_load_lds((const GAS unsigned*)(_g + so0), (unsigned*)((char*)(P) + tid_ * 16), 16, 0, 0); \
;     __builtin_amdgcn_global_load_lds((const GAS unsigned*)(_g + so1), (unsigned*)((char*)(P) + tid_ * 16 + 8192), 16, 0, 0); } while (0)
; #define WAIT_V(n) asm volatile("s_waitcnt vmcnt(" #n ")" ::: "memory")
; #define WAIT_L(n) asm volatile("s_waitcnt lgkmcnt(" #n ")" ::: "memory")
; #define BAR __builtin_amdgcn_s_barrier()
; #define SCHED __builtin_amdgcn_sched_barrier(0)
; #define LDA(dst, b, h) for (int m = 0; m < 4; ++m) for (int k = 0; k < 2; ++k) \
;     dst[m][k] = *reinterpret_cast<const bf16x8*>((char*)SA(b, h) + lds_byte(wr * 64 + m * 16 + fr, k * 32 + fq * 8))
; #define MMA(ai, bj, At_, Bt_) do { __builtin_amdgcn_s_setprio(1); \
;     for (int m = 0; m < 4; ++m) for (int n = 0; n < 2; ++n) for (int k = 0; k < 2; ++k) \
;       acc[ai][bj][m][n] = __builtin_amdgcn_mfma_f32_16x16x32_bf16(At_[m][k], Bt_[n][k], acc[ai][bj][m][n], 0, 0, 0); \
;     __builtin_amdgcn_s_setprio(0); } while (0)
; __device__ __forceinline__ int ugrid() { return __builtin_amdgcn_readfirstlane((int)gridDim.x); }
; template <int K, int LD = K>
; __device__ __forceinline__ void gemm_main(const GAS bf16* A, const GAS bf16* Bt, int brow, int bcol, f32x4 (&acc)[2][2][4][2]) {
;     ...
;     LDA(At, 1, 1); STAGE(SA(1, 0), pA0, 3);
;     BAR; WAIT_L(0); MMA(1, 0, At, B0); BAR; SCHED;
;     STAGE(SB(1, 1), pB1, 3);
;     WAIT_V(6); BAR; MMA(1, 1, At, B1); BAR;
;     pA0 += 4 * BK; pA1 += 4 * BK; pB0 += 4 * BK; pB1 += 4 * BK;
;     asm volatile("" : "+s"(pA0), "+s"(pA1), "+s"(pB0), "+s"(pB1));
;   }
; __device__ __forceinline__ void phase_up(int pass) {
;     ...
;     L += ugrid();
;     if (L < NT_) { tile_coords(L, nN, pm, pn); gemm_prefetch<DM>(A, Wgu, pm * 256, pn * 256); load_rr(ssq, pm * 256, par ^ 1); }
	ds_read_b128 v[182:185], v140 offset:49152
	ds_read_b128 v[186:189], v140 offset:50176
	ds_read_b128 v[190:193], v139 offset:49152
	ds_read_b128 v[194:197], v139 offset:50176
	ds_read_b128 v[198:201], v138 offset:49152
	ds_read_b128 v[202:205], v138 offset:50176
	ds_read_b128 v[206:209], v137 offset:49152
	ds_read_b128 v[210:213], v137 offset:50176
	global_load_lds_dwordx4 v[230:231], off
	v_lshl_add_u64 v[230:231], v[240:241], 0, s[12:13]
	s_mov_b32 m0, s24
	s_nop 0
	global_load_lds_dwordx4 v[230:231], off
	s_barrier
	s_waitcnt lgkmcnt(0)
	s_setprio 1
	s_waitcnt lgkmcnt(0)
	v_mfma_f32_16x16x32_bf16 v[62:65], v[162:165], v[182:185], v[62:65]
	v_mfma_f32_16x16x32_bf16 v[58:61], v[174:177], v[182:185], v[58:61]
	v_mfma_f32_16x16x32_bf16 v[54:57], v[162:165], v[190:193], v[54:57]
	v_mfma_f32_16x16x32_bf16 v[50:53], v[174:177], v[190:193], v[50:53]
	v_mfma_f32_16x16x32_bf16 v[46:49], v[162:165], v[198:201], v[46:49]
	v_mfma_f32_16x16x32_bf16 v[42:45], v[174:177], v[198:201], v[42:45]
	v_mfma_f32_16x16x32_bf16 v[38:41], v[162:165], v[206:209], v[38:41]
	v_mfma_f32_16x16x32_bf16 v[34:37], v[174:177], v[206:209], v[34:37]
	v_mfma_f32_16x16x32_bf16 v[62:65], v[166:169], v[186:189], v[62:65]
	v_mfma_f32_16x16x32_bf16 v[58:61], v[178:181], v[186:189], v[58:61]
	v_mfma_f32_16x16x32_bf16 v[54:57], v[166:169], v[194:197], v[54:57]
	v_mfma_f32_16x16x32_bf16 v[50:53], v[178:181], v[194:197], v[50:53]
	v_mfma_f32_16x16x32_bf16 v[46:49], v[166:169], v[202:205], v[46:49]
	v_mfma_f32_16x16x32_bf16 v[42:45], v[178:181], v[202:205], v[42:45]
	v_mfma_f32_16x16x32_bf16 v[38:41], v[166:169], v[210:213], v[38:41]
	v_mfma_f32_16x16x32_bf16 v[34:37], v[178:181], v[210:213], v[34:37]
	s_setprio 0
	s_barrier
	v_readfirstlane_b32 s24, v149
	v_lshl_add_u64 v[162:163], v[242:243], 0, s[12:13]
	s_mov_b32 m0, s24
	v_readfirstlane_b32 s24, v160
	global_load_lds_dwordx4 v[162:163], off
	v_lshl_add_u64 v[162:163], v[244:245], 0, s[12:13]
	s_mov_b32 m0, s24
	s_nop 0
	global_load_lds_dwordx4 v[162:163], off
	s_waitcnt vmcnt(6)
	s_barrier
	s_setprio 1
	v_mfma_f32_16x16x32_bf16 v[30:33], v[214:217], v[182:185], v[30:33]
	v_mfma_f32_16x16x32_bf16 v[26:29], v[222:225], v[182:185], v[26:29]
	v_mfma_f32_16x16x32_bf16 v[22:25], v[214:217], v[190:193], v[22:25]
	v_mfma_f32_16x16x32_bf16 v[18:21], v[222:225], v[190:193], v[18:21]
	v_mfma_f32_16x16x32_bf16 v[14:17], v[214:217], v[198:201], v[14:17]
	v_mfma_f32_16x16x32_bf16 v[10:13], v[222:225], v[198:201], v[10:13]
	v_mfma_f32_16x16x32_bf16 v[6:9], v[214:217], v[206:209], v[6:9]
	v_mfma_f32_16x16x32_bf16 v[2:5], v[222:225], v[206:209], v[2:5]
	v_mfma_f32_16x16x32_bf16 v[30:33], v[218:221], v[186:189], v[30:33]
	v_mfma_f32_16x16x32_bf16 v[26:29], v[226:229], v[186:189], v[26:29]
	v_mfma_f32_16x16x32_bf16 v[22:25], v[218:221], v[194:197], v[22:25]
	v_mfma_f32_16x16x32_bf16 v[18:21], v[226:229], v[194:197], v[18:21]
	v_mfma_f32_16x16x32_bf16 v[14:17], v[218:221], v[202:205], v[14:17]
	v_mfma_f32_16x16x32_bf16 v[10:13], v[226:229], v[202:205], v[10:13]
	v_mfma_f32_16x16x32_bf16 v[6:9], v[218:221], v[210:213], v[6:9]
	v_mfma_f32_16x16x32_bf16 v[2:5], v[226:229], v[210:213], v[2:5]
	s_setprio 0
	s_add_i32 s17, s17, 2
	s_cmp_lt_u32 s17, 12
	s_barrier
	s_cbranch_scc1 .LBB0_89
	v_readfirstlane_b32 s42, v170
	v_readfirstlane_b32 s98, v171
	s_mov_b32 s99, 0
	s_nop 1
	s_lshl_b32 s42, s42, 4
	s_add_i32 s98, s98, s3
	s_cmpk_gt_i32 s98, 0x57f
	s_cbranch_scc1 .Lup0_noearly
	s_mul_hi_i32 s43, s98, 0x2e8ba2e9
	s_lshr_b32 s44, s43, 31
	s_ashr_i32 s43, s43, 5
	s_add_i32 s43, s43, s44
	s_mul_i32 s44, s43, 0xb0
	s_sub_i32 s44, s98, s44
	s_lshl_b32 s43, s43, 3
	s_and_b32 s45, s44, 7
	s_or_b32 s43, s45, s43
	s_ashr_i32 s44, s44, 3
	s_lshl_b32 s43, s43, 19
	s_lshl_b32 s44, s44, 19
	s_add_u32 s100, s26, s43
	s_addc_u32 s101, s27, 0
	s_add_u32 s98, s4, s44
	s_addc_u32 s99, s5, 0
.Lup0_noearly:
	ds_read_b128 v[146:149], v144
	ds_read_b128 v[152:155], v144 offset:1024
	ds_read_b128 v[156:159], v144 offset:2048
	ds_read_b128 v[160:163], v144 offset:3072
	ds_read_b128 v[164:167], v140
	ds_read_b128 v[174:177], v140 offset:1024
	ds_read_b128 v[178:181], v139
	ds_read_b128 v[182:185], v139 offset:1024
	ds_read_b128 v[186:189], v138
	ds_read_b128 v[190:193], v138 offset:1024
	ds_read_b128 v[194:197], v137
	ds_read_b128 v[198:201], v137 offset:1024
	v_lshl_add_u64 v[144:145], s[14:15], 0, v[130:131]
	v_readfirstlane_b32 s17, v151
	v_lshl_add_u64 v[144:145], v[144:145], 0, s[8:9]
	s_mov_b32 m0, s17
	v_lshl_add_u64 v[132:133], s[14:15], 0, v[132:133]
	v_readfirstlane_b32 s14, v150
	global_load_lds_dwordx4 v[144:145], off
	v_lshl_add_u64 v[132:133], v[132:133], 0, s[8:9]
	s_mov_b32 m0, s14
	s_nop 0
	global_load_lds_dwordx4 v[132:133], off
	s_barrier
	s_waitcnt lgkmcnt(0)
	s_setprio 1
	s_waitcnt lgkmcnt(0)
	v_mfma_f32_16x16x32_bf16 v[126:129], v[146:149], v[164:167], v[126:129]
	v_mfma_f32_16x16x32_bf16 v[122:125], v[156:159], v[164:167], v[122:125]
	v_mfma_f32_16x16x32_bf16 v[110:113], v[146:149], v[186:189], v[110:113]
	v_mfma_f32_16x16x32_bf16 v[106:109], v[156:159], v[186:189], v[106:109]
	v_mfma_f32_16x16x32_bf16 v[126:129], v[152:155], v[174:177], v[126:129]
	v_mfma_f32_16x16x32_bf16 v[122:125], v[160:163], v[174:177], v[122:125]
	v_mfma_f32_16x16x32_bf16 v[118:121], v[146:149], v[178:181], v[118:121]
	v_mfma_f32_16x16x32_bf16 v[114:117], v[156:159], v[178:181], v[114:117]
	v_mfma_f32_16x16x32_bf16 v[110:113], v[152:155], v[190:193], v[110:113]
	v_mfma_f32_16x16x32_bf16 v[106:109], v[160:163], v[190:193], v[106:109]
	v_mfma_f32_16x16x32_bf16 v[102:105], v[146:149], v[194:197], v[102:105]
	v_mfma_f32_16x16x32_bf16 v[98:101], v[156:159], v[194:197], v[98:101]
	v_mfma_f32_16x16x32_bf16 v[202:205], v[152:155], v[182:185], v[118:121]
	v_mfma_f32_16x16x32_bf16 v[206:209], v[160:163], v[182:185], v[114:117]
	v_mfma_f32_16x16x32_bf16 v[210:213], v[152:155], v[198:201], v[102:105]
	v_mfma_f32_16x16x32_bf16 v[214:217], v[160:163], v[198:201], v[98:101]
	s_setprio 0
	s_barrier
; #define STAGE(P, GP, ktrel) do { const GAS char* _g = (GP) + (ktrel) * (BK * 2); \
;     __builtin_amdgcn_global_load_lds((const GAS unsigned*)(_g + so0), (unsigned*)((char*)(P) + tid_ * 16), 16, 0, 0); \
;     __builtin_amdgcn_global_load_lds((const GAS unsigned*)(_g + so1), (unsigned*)((char*)(P) + tid_ * 16 + 8192), 16, 0, 0); } while (0)
; #define WAIT_V(n) asm volatile("s_waitcnt vmcnt(" #n ")" ::: "memory")
; #define WAIT_L(n) asm volatile("s_waitcnt lgkmcnt(" #n ")" ::: "memory")
; #define BAR __builtin_amdgcn_s_barrier()
; #define LDA(dst, b, h) for (int m = 0; m < 4; ++m) for (int k = 0; k < 2; ++k) \
;     dst[m][k] = *reinterpret_cast<const bf16x8*>((char*)SA(b, h) + lds_byte(wr * 64 + m * 16 + fr, k * 32 + fq * 8))
; #define LDB(dst, b, h) for (int n = 0; n < 2; ++n) for (int k = 0; k < 2; ++k) \
;     dst[n][k] = *reinterpret_cast<const bf16x8*>((char*)SB(b, h) + lds_byte(wc * 32 + n * 16 + fr, k * 32 + fq * 8))
; #define MMA(ai, bj, At_, Bt_) do { __builtin_amdgcn_s_setprio(1); \
;     for (int m = 0; m < 4; ++m) for (int n = 0; n < 2; ++n) for (int k = 0; k < 2; ++k) \
;       acc[ai][bj][m][n] = __builtin_amdgcn_mfma_f32_16x16x32_bf16(At_[m][k], Bt_[n][k], acc[ai][bj][m][n], 0, 0, 0); \
;     __builtin_amdgcn_s_setprio(0); } while (0)
; template <int K, int LD = K>
; __device__ __forceinline__ void gemm_main(const GAS bf16* A, const GAS bf16* Bt, int brow, int bcol, f32x4 (&acc)[2][2][4][2]) {
;     ...
;   { LDB(B0, 0, 0); LDA(At, 0, 0); STAGE(SA(1, 1), pA1, 1);
;     BAR; WAIT_L(0); MMA(0, 0, At, B0); BAR;
;     LDB(B1, 0, 1); BAR; WAIT_L(0); MMA(0, 1, At, B1); BAR;
;     LDA(At, 0, 1); WAIT_V(4); BAR; WAIT_L(0); MMA(1, 0, At, B0); MMA(1, 1, At, B1); BAR; }
;   { LDB(B0, 1, 0); LDA(At, 1, 0); WAIT_V(2); BAR; WAIT_L(0); MMA(0, 0, At, B0); BAR;
;     LDB(B1, 1, 1); WAIT_V(0); BAR; WAIT_L(0); MMA(0, 1, At, B1); BAR;
	s_nop 1
	ds_read_b128 v[98:101], v143
	ds_read_b128 v[102:105], v143 offset:1024
	ds_read_b128 v[114:117], v143 offset:2048
	ds_read_b128 v[118:121], v143 offset:3072
	s_barrier
	s_waitcnt lgkmcnt(0)
	s_setprio 1
	s_waitcnt lgkmcnt(0)
	v_mfma_f32_16x16x32_bf16 v[94:97], v[98:101], v[164:167], v[94:97]
	v_mfma_f32_16x16x32_bf16 v[90:93], v[114:117], v[164:167], v[90:93]
	v_mfma_f32_16x16x32_bf16 v[78:81], v[98:101], v[186:189], v[78:81]
	v_mfma_f32_16x16x32_bf16 v[74:77], v[114:117], v[186:189], v[74:77]
	v_mfma_f32_16x16x32_bf16 v[94:97], v[102:105], v[174:177], v[94:97]
	v_mfma_f32_16x16x32_bf16 v[90:93], v[118:121], v[174:177], v[90:93]
	v_mfma_f32_16x16x32_bf16 v[86:89], v[98:101], v[178:181], v[86:89]
	v_mfma_f32_16x16x32_bf16 v[82:85], v[114:117], v[178:181], v[82:85]
	v_mfma_f32_16x16x32_bf16 v[78:81], v[102:105], v[190:193], v[78:81]
	v_mfma_f32_16x16x32_bf16 v[74:77], v[118:121], v[190:193], v[74:77]
	v_mfma_f32_16x16x32_bf16 v[70:73], v[98:101], v[194:197], v[70:73]
	v_mfma_f32_16x16x32_bf16 v[66:69], v[114:117], v[194:197], v[66:69]
	v_mfma_f32_16x16x32_bf16 v[164:167], v[102:105], v[182:185], v[86:89]
	v_mfma_f32_16x16x32_bf16 v[174:177], v[118:121], v[182:185], v[82:85]
	v_mfma_f32_16x16x32_bf16 v[178:181], v[102:105], v[198:201], v[70:73]
	v_mfma_f32_16x16x32_bf16 v[182:185], v[118:121], v[198:201], v[66:69]
	s_setprio 0
	s_barrier
	s_nop 1
	ds_read_b128 v[66:69], v140 offset:16384
	ds_read_b128 v[70:73], v140 offset:17408
	ds_read_b128 v[82:85], v139 offset:16384
	ds_read_b128 v[86:89], v139 offset:17408
	ds_read_b128 v[186:189], v138 offset:16384
	ds_read_b128 v[190:193], v138 offset:17408
	ds_read_b128 v[194:197], v137 offset:16384
	ds_read_b128 v[198:201], v137 offset:17408
	s_waitcnt vmcnt(4)
	s_barrier
	s_waitcnt lgkmcnt(0)
	s_setprio 1
	s_waitcnt lgkmcnt(0)
	v_mfma_f32_16x16x32_bf16 v[62:65], v[146:149], v[66:69], v[62:65]
	v_mfma_f32_16x16x32_bf16 v[58:61], v[156:159], v[66:69], v[58:61]
	v_mfma_f32_16x16x32_bf16 v[46:49], v[146:149], v[186:189], v[46:49]
	v_mfma_f32_16x16x32_bf16 v[38:41], v[146:149], v[194:197], v[38:41]
	v_mfma_f32_16x16x32_bf16 v[62:65], v[152:155], v[70:73], v[62:65]
	v_mfma_f32_16x16x32_bf16 v[58:61], v[160:163], v[70:73], v[58:61]
	v_mfma_f32_16x16x32_bf16 v[54:57], v[146:149], v[82:85], v[54:57]
	v_mfma_f32_16x16x32_bf16 v[50:53], v[156:159], v[82:85], v[50:53]
	v_mfma_f32_16x16x32_bf16 v[46:49], v[152:155], v[190:193], v[46:49]
	v_mfma_f32_16x16x32_bf16 v[42:45], v[156:159], v[186:189], v[42:45]
	v_mfma_f32_16x16x32_bf16 v[38:41], v[152:155], v[198:201], v[38:41]
	v_mfma_f32_16x16x32_bf16 v[34:37], v[156:159], v[194:197], v[34:37]
	v_mfma_f32_16x16x32_bf16 v[218:221], v[152:155], v[86:89], v[54:57]
	v_mfma_f32_16x16x32_bf16 v[222:225], v[160:163], v[86:89], v[50:53]
	v_mfma_f32_16x16x32_bf16 v[226:229], v[160:163], v[190:193], v[42:45]
	v_mfma_f32_16x16x32_bf16 v[144:147], v[160:163], v[198:201], v[34:37]
	s_setprio 0
	s_setprio 1
	v_mfma_f32_16x16x32_bf16 v[30:33], v[98:101], v[66:69], v[30:33]
	v_mfma_f32_16x16x32_bf16 v[26:29], v[114:117], v[66:69], v[26:29]
	v_mfma_f32_16x16x32_bf16 v[14:17], v[98:101], v[186:189], v[14:17]
	v_mfma_f32_16x16x32_bf16 v[6:9], v[98:101], v[194:197], v[6:9]
	v_mfma_f32_16x16x32_bf16 v[30:33], v[102:105], v[70:73], v[30:33]
	v_mfma_f32_16x16x32_bf16 v[26:29], v[118:121], v[70:73], v[26:29]
	v_mfma_f32_16x16x32_bf16 v[22:25], v[98:101], v[82:85], v[22:25]
	v_mfma_f32_16x16x32_bf16 v[18:21], v[114:117], v[82:85], v[18:21]
	v_mfma_f32_16x16x32_bf16 v[14:17], v[102:105], v[190:193], v[14:17]
	v_mfma_f32_16x16x32_bf16 v[10:13], v[114:117], v[186:189], v[10:13]
	v_mfma_f32_16x16x32_bf16 v[6:9], v[102:105], v[198:201], v[6:9]
	v_mfma_f32_16x16x32_bf16 v[2:5], v[114:117], v[194:197], v[2:5]
	v_mfma_f32_16x16x32_bf16 v[148:151], v[102:105], v[86:89], v[22:25]
	v_mfma_f32_16x16x32_bf16 v[152:155], v[118:121], v[86:89], v[18:21]
	v_mfma_f32_16x16x32_bf16 v[156:159], v[118:121], v[190:193], v[10:13]
	v_mfma_f32_16x16x32_bf16 v[160:163], v[118:121], v[198:201], v[2:5]
	s_setprio 0
	s_barrier
	s_nop 1
	ds_read_b128 v[2:5], v142
	ds_read_b128 v[10:13], v142 offset:1024
	ds_read_b128 v[186:189], v142 offset:2048
	ds_read_b128 v[190:193], v142 offset:3072
	ds_read_b128 v[18:21], v140 offset:32768
	ds_read_b128 v[22:25], v140 offset:33792
	ds_read_b128 v[34:37], v139 offset:32768
	ds_read_b128 v[42:45], v139 offset:33792
	ds_read_b128 v[50:53], v138 offset:32768
	ds_read_b128 v[54:57], v138 offset:33792
	ds_read_b128 v[194:197], v137 offset:32768
	ds_read_b128 v[198:201], v137 offset:33792
	s_waitcnt vmcnt(2)
	s_barrier
	s_waitcnt lgkmcnt(0)
	s_setprio 1
	s_waitcnt lgkmcnt(0)
	v_mfma_f32_16x16x32_bf16 v[66:69], v[2:5], v[18:21], v[126:129]
	v_mfma_f32_16x16x32_bf16 v[118:121], v[10:13], v[22:25], v[66:69]
	v_mfma_f32_16x16x32_bf16 v[66:69], v[186:189], v[18:21], v[122:125]
	v_mfma_f32_16x16x32_bf16 v[114:117], v[190:193], v[22:25], v[66:69]
	v_mfma_f32_16x16x32_bf16 v[66:69], v[2:5], v[34:37], v[202:205]
	v_mfma_f32_16x16x32_bf16 v[102:105], v[10:13], v[42:45], v[66:69]
	v_mfma_f32_16x16x32_bf16 v[66:69], v[186:189], v[34:37], v[206:209]
	v_mfma_f32_16x16x32_bf16 v[98:101], v[190:193], v[42:45], v[66:69]
	v_mfma_f32_16x16x32_bf16 v[66:69], v[2:5], v[50:53], v[110:113]
	v_mfma_f32_16x16x32_bf16 v[86:89], v[10:13], v[54:57], v[66:69]
	v_mfma_f32_16x16x32_bf16 v[66:69], v[186:189], v[50:53], v[106:109]
	v_mfma_f32_16x16x32_bf16 v[82:85], v[190:193], v[54:57], v[66:69]
	v_mfma_f32_16x16x32_bf16 v[66:69], v[2:5], v[194:197], v[210:213]
	v_mfma_f32_16x16x32_bf16 v[70:73], v[10:13], v[198:201], v[66:69]
	v_mfma_f32_16x16x32_bf16 v[66:69], v[186:189], v[194:197], v[214:217]
	v_mfma_f32_16x16x32_bf16 v[66:69], v[190:193], v[198:201], v[66:69]
	s_setprio 0
	s_barrier
	ds_read_b128 v[202:205], v141
	ds_read_b128 v[206:209], v141 offset:1024
	ds_read_b128 v[210:213], v141 offset:2048
	ds_read_b128 v[214:217], v141 offset:3072
	s_waitcnt vmcnt(0)
	s_cmp_eq_u32 s99, 0
	s_cbranch_scc1 .Lup0_early2_skip
	s_add_i32 s43, s42, 0x10100
	s_mov_b32 m0, s43
	s_nop 0
	global_load_lds_dwordx4 v130, s[98:99]
	s_add_u32 s98, s98, 0x20000
	s_addc_u32 s99, s99, 0
	s_add_i32 s43, s42, 0x12100
	s_mov_b32 m0, s43
	s_nop 0
	global_load_lds_dwordx4 v130, s[98:99]
	s_add_i32 s43, s42, 0x100
	s_mov_b32 m0, s43
	s_nop 0
	global_load_lds_dwordx4 v130, s[100:101]
	s_add_u32 s100, s100, 0x20000
	s_addc_u32 s101, s101, 0
	s_add_i32 s43, s42, 0x2100
	s_mov_b32 m0, s43
	s_nop 0
	global_load_lds_dwordx4 v130, s[100:101]
; #define WAIT_V(n) asm volatile("s_waitcnt vmcnt(" #n ")" ::: "memory")
; #define WAIT_L(n) asm volatile("s_waitcnt lgkmcnt(" #n ")" ::: "memory")
; #define BAR __builtin_amdgcn_s_barrier()
; #define LDA(dst, b, h) for (int m = 0; m < 4; ++m) for (int k = 0; k < 2; ++k) \
;     dst[m][k] = *reinterpret_cast<const bf16x8*>((char*)SA(b, h) + lds_byte(wr * 64 + m * 16 + fr, k * 32 + fq * 8))
; #define LDB(dst, b, h) for (int n = 0; n < 2; ++n) for (int k = 0; k < 2; ++k) \
;     dst[n][k] = *reinterpret_cast<const bf16x8*>((char*)SB(b, h) + lds_byte(wc * 32 + n * 16 + fr, k * 32 + fq * 8))
; #define MMA(ai, bj, At_, Bt_) do { __builtin_amdgcn_s_setprio(1); \
;     for (int m = 0; m < 4; ++m) for (int n = 0; n < 2; ++n) for (int k = 0; k < 2; ++k) \
;       acc[ai][bj][m][n] = __builtin_amdgcn_mfma_f32_16x16x32_bf16(At_[m][k], Bt_[n][k], acc[ai][bj][m][n], 0, 0, 0); \
;     __builtin_amdgcn_s_setprio(0); } while (0)
; template <int K, int LD = K>
; __device__ __forceinline__ void gemm_main(const GAS bf16* A, const GAS bf16* Bt, int brow, int bcol, f32x4 (&acc)[2][2][4][2]) {
;     ...
;     LDA(At, 0, 1); WAIT_V(4); BAR; WAIT_L(0); MMA(1, 0, At, B0); MMA(1, 1, At, B1); BAR; }
;   { LDB(B0, 1, 0); LDA(At, 1, 0); WAIT_V(2); BAR; WAIT_L(0); MMA(0, 0, At, B0); BAR;
;     LDB(B1, 1, 1); WAIT_V(0); BAR; WAIT_L(0); MMA(0, 1, At, B1); BAR;
;     LDA(At, 1, 1); BAR; WAIT_L(0); MMA(1, 0, At, B0); MMA(1, 1, At, B1); BAR; }
;   if (wr == 0) BAR;
.Lup0_early2_skip:
	s_barrier
	s_waitcnt lgkmcnt(0)
	s_setprio 1
	s_waitcnt lgkmcnt(0)
	v_mfma_f32_16x16x32_bf16 v[94:97], v[202:205], v[18:21], v[94:97]
	v_mfma_f32_16x16x32_bf16 v[18:21], v[210:213], v[18:21], v[90:93]
	v_mfma_f32_16x16x32_bf16 v[122:125], v[214:217], v[22:25], v[18:21]
	v_mfma_f32_16x16x32_bf16 v[18:21], v[202:205], v[34:37], v[164:167]
	v_mfma_f32_16x16x32_bf16 v[110:113], v[206:209], v[42:45], v[18:21]
	v_mfma_f32_16x16x32_bf16 v[18:21], v[210:213], v[34:37], v[174:177]
	v_mfma_f32_16x16x32_bf16 v[106:109], v[214:217], v[42:45], v[18:21]
	v_mfma_f32_16x16x32_bf16 v[18:21], v[202:205], v[50:53], v[78:81]
	v_mfma_f32_16x16x32_bf16 v[126:129], v[206:209], v[22:25], v[94:97]
	v_mfma_f32_16x16x32_bf16 v[94:97], v[206:209], v[54:57], v[18:21]
	v_mfma_f32_16x16x32_bf16 v[18:21], v[210:213], v[50:53], v[74:77]
	v_mfma_f32_16x16x32_bf16 v[90:93], v[214:217], v[54:57], v[18:21]
	v_mfma_f32_16x16x32_bf16 v[18:21], v[202:205], v[194:197], v[178:181]
	v_mfma_f32_16x16x32_bf16 v[78:81], v[206:209], v[198:201], v[18:21]
	v_mfma_f32_16x16x32_bf16 v[18:21], v[210:213], v[194:197], v[182:185]
	v_mfma_f32_16x16x32_bf16 v[74:77], v[214:217], v[198:201], v[18:21]
	s_setprio 0
	s_barrier
	ds_read_b128 v[164:167], v140 offset:49152
	ds_read_b128 v[140:143], v140 offset:50176
	ds_read_b128 v[174:177], v139 offset:49152
	ds_read_b128 v[178:181], v139 offset:50176
	ds_read_b128 v[182:185], v138 offset:49152
	ds_read_b128 v[194:197], v138 offset:50176
	ds_read_b128 v[198:201], v137 offset:49152
	ds_read_b128 v[230:233], v137 offset:50176
	s_cmp_eq_u32 s99, 0
	s_cbranch_scc1 .Lup0_early3_skip
	s_add_u32 s98, s98, 0x20000
	s_addc_u32 s99, s99, 0
	s_add_i32 s43, s42, 0x14100
	s_mov_b32 m0, s43
	s_nop 0
	global_load_lds_dwordx4 v130, s[98:99]
	s_add_u32 s98, s98, 0x20000
	s_addc_u32 s99, s99, 0
	s_add_i32 s43, s42, 0x16100
	s_mov_b32 m0, s43
	s_nop 0
	global_load_lds_dwordx4 v130, s[98:99]
	s_add_u32 s100, s100, 0x20000
	s_addc_u32 s101, s101, 0
	s_add_i32 s43, s42, 0x4100
	s_mov_b32 m0, s43
	s_nop 0
	global_load_lds_dwordx4 v130, s[100:101]
	s_add_u32 s100, s100, 0x20000
	s_addc_u32 s101, s101, 0
	s_add_i32 s43, s42, 0x6100
	s_mov_b32 m0, s43
	s_nop 0
	global_load_lds_dwordx4 v130, s[100:101]
.Lup0_early3_skip:
	s_barrier
	s_waitcnt lgkmcnt(0)
	s_setprio 1
	s_waitcnt lgkmcnt(0)
	v_mfma_f32_16x16x32_bf16 v[18:21], v[2:5], v[164:167], v[62:65]
	v_mfma_f32_16x16x32_bf16 v[54:57], v[10:13], v[140:143], v[18:21]
	v_mfma_f32_16x16x32_bf16 v[18:21], v[186:189], v[164:167], v[58:61]
	v_mfma_f32_16x16x32_bf16 v[50:53], v[190:193], v[140:143], v[18:21]
	v_mfma_f32_16x16x32_bf16 v[18:21], v[2:5], v[174:177], v[218:221]
	v_mfma_f32_16x16x32_bf16 v[42:45], v[10:13], v[178:181], v[18:21]
	v_mfma_f32_16x16x32_bf16 v[18:21], v[186:189], v[174:177], v[222:225]
	v_mfma_f32_16x16x32_bf16 v[34:37], v[190:193], v[178:181], v[18:21]
	v_mfma_f32_16x16x32_bf16 v[18:21], v[2:5], v[182:185], v[46:49]
	v_mfma_f32_16x16x32_bf16 v[2:5], v[2:5], v[198:201], v[38:41]
	v_mfma_f32_16x16x32_bf16 v[22:25], v[10:13], v[194:197], v[18:21]
	v_mfma_f32_16x16x32_bf16 v[18:21], v[186:189], v[182:185], v[226:229]
	v_mfma_f32_16x16x32_bf16 v[10:13], v[10:13], v[230:233], v[2:5]
	v_mfma_f32_16x16x32_bf16 v[2:5], v[186:189], v[198:201], v[144:147]
	v_mfma_f32_16x16x32_bf16 v[18:21], v[190:193], v[194:197], v[18:21]
	v_mfma_f32_16x16x32_bf16 v[2:5], v[190:193], v[230:233], v[2:5]
	s_setprio 0
	s_setprio 1
	v_mfma_f32_16x16x32_bf16 v[26:29], v[210:213], v[164:167], v[26:29]
	v_mfma_f32_16x16x32_bf16 v[30:33], v[202:205], v[164:167], v[30:33]
	v_mfma_f32_16x16x32_bf16 v[58:61], v[214:217], v[140:143], v[26:29]
	v_mfma_f32_16x16x32_bf16 v[26:29], v[202:205], v[174:177], v[148:151]
	v_mfma_f32_16x16x32_bf16 v[14:17], v[202:205], v[182:185], v[14:17]
	v_mfma_f32_16x16x32_bf16 v[62:65], v[206:209], v[140:143], v[30:33]
	v_mfma_f32_16x16x32_bf16 v[46:49], v[206:209], v[178:181], v[26:29]
	v_mfma_f32_16x16x32_bf16 v[26:29], v[210:213], v[174:177], v[152:155]
	v_mfma_f32_16x16x32_bf16 v[30:33], v[206:209], v[194:197], v[14:17]
	v_mfma_f32_16x16x32_bf16 v[14:17], v[210:213], v[182:185], v[156:159]
	v_mfma_f32_16x16x32_bf16 v[6:9], v[202:205], v[198:201], v[6:9]
	v_mfma_f32_16x16x32_bf16 v[38:41], v[214:217], v[178:181], v[26:29]
	v_mfma_f32_16x16x32_bf16 v[26:29], v[214:217], v[194:197], v[14:17]
	v_mfma_f32_16x16x32_bf16 v[14:17], v[206:209], v[230:233], v[6:9]
	v_mfma_f32_16x16x32_bf16 v[6:9], v[210:213], v[198:201], v[160:163]
	v_mfma_f32_16x16x32_bf16 v[6:9], v[214:217], v[230:233], v[6:9]
	s_setprio 0
	v_cmp_gt_u32_e32 vcc, s34, v136
	s_barrier
	s_and_saveexec_b64 s[14:15], vcc
	s_cbranch_execz .LBB0_92
	s_barrier
; #define GAS __attribute__((address_space(1)))
; __device__ __forceinline__ int otid() { int t = threadIdx.x; asm volatile("" : "+v"(t)); return t; }
; #define STAGE(P, GP, ktrel) do { const GAS char* _g = (GP) + (ktrel) * (BK * 2); \
;     __builtin_amdgcn_global_load_lds((const GAS unsigned*)(_g + so0), (unsigned*)((char*)(P) + tid_ * 16), 16, 0, 0); \
;     __builtin_amdgcn_global_load_lds((const GAS unsigned*)(_g + so1), (unsigned*)((char*)(P) + tid_ * 16 + 8192), 16, 0, 0); } while (0)
; template <int K, int LD = K>
; __device__ __forceinline__ void gemm_prefetch(const GAS bf16* A, const GAS bf16* Bt, int brow, int bcol) {
;   bf16* shm = (bf16*)smem_raw;
;   const int tid_ = otid();
;   unsigned so0, so1;
;   { int r_, c_; stage_rc(tid_ * 16, r_, c_); so0 = (unsigned)(r_ * LD + c_) * 2u; stage_rc(tid_ * 16 + 8192, r_, c_); so1 = (unsigned)(r_ * LD + c_) * 2u; }
;   const GAS char* pA0 = (const GAS char*)A + (long)brow * LD * 2; const GAS char* pA1 = pA0 + (long)HALF * LD * 2;
;   const GAS char* pB0 = (const GAS char*)Bt + (long)bcol * LD * 2; const GAS char* pB1 = pB0 + (long)HALF * LD * 2;
;   asm volatile("" : "+s"(pA0), "+s"(pA1), "+s"(pB0), "+s"(pB1));
;   STAGE(SB(0, 0), pB0, 0); STAGE(SA(0, 0), pA0, 0);
;   STAGE(SB(0, 1), pB1, 0); STAGE(SA(0, 1), pA1, 0);
;   STAGE(SB(1, 0), pB0, 1); STAGE(SA(1, 0), pA0, 1); STAGE(SB(1, 1), pB1, 1);
; }
; __device__ __forceinline__ void load_rr(const GAS float* ssq, int brow, int par) {
;   float* rr = (float*)(smem_raw + LDS_RR) + par * 256;
;   const int tx = otid();
;   if (tx < 256) {
;     const GAS f32x4* s = (const GAS f32x4*)(ssq + (size_t)(brow + tx) * 16);
;     f32x4 a = s[0], b = s[1], c = s[2], d = s[3];
.LBB0_92:
	s_or_b64 exec, exec, s[14:15]
	v_readfirstlane_b32 s14, v171
	s_add_i32 s3, s14, s3
	s_cmpk_gt_i32 s3, 0x57f
	s_cselect_b64 s[14:15], -1, 0
	s_and_b64 vcc, exec, s[14:15]
	s_mov_b32 s22, s41
	s_cbranch_vccnz .LBB0_85
	v_mov_b32_e32 v130, v170
	s_mul_hi_i32 s17, s3, 0x2e8ba2e9
	v_ashrrev_i32_e32 v132, 31, v130
	v_lshrrev_b32_e32 v132, 26, v132
	v_lshlrev_b32_e32 v148, 4, v130
	v_add_u32_e32 v132, v130, v132
	v_bfe_i32 v130, v130, 27, 1
	v_lshrrev_b32_e32 v130, 22, v130
	v_add_u32_e32 v130, v148, v130
	v_and_b32_e32 v130, 0xfffffc00, v130
	v_sub_u32_e32 v130, v148, v130
	v_lshrrev_b32_e32 v133, 4, v130
	v_bitop3_b32 v133, v133, v130, 32 bitop3:0x6c
	v_ashrrev_i32_e32 v130, 31, v130
	v_lshrrev_b32_e32 v130, 26, v130
	v_add_u32_e32 v130, v133, v130
	v_ashrrev_i32_e32 v130, 6, v130
	v_ashrrev_i32_e32 v132, 6, v132
	v_mul_i32_i24_e32 v137, 64, v130
	v_lshlrev_b32_e32 v136, 3, v132
	v_lshlrev_b32_e32 v132, 5, v132
	v_sub_u32_e32 v133, v133, v137
	s_lshr_b32 s18, s17, 31
	s_ashr_i32 s17, s17, 5
	v_and_b32_e32 v136, 0x1ffff0, v136
	v_and_b32_e32 v132, 32, v132
	v_ashrrev_i16_sdwa v133, v134, sext(v133) dst_sel:DWORD dst_unused:UNUSED_PAD src0_sel:DWORD src1_sel:BYTE_0
	s_add_i32 s17, s17, s18
	v_add_u32_sdwa v132, v132, sext(v133) dst_sel:DWORD dst_unused:UNUSED_PAD src0_sel:DWORD src1_sel:WORD_0
	v_add_lshl_u32 v130, v130, v136, 11
	s_mul_i32 s18, s17, 0xb0
	v_lshl_add_u32 v130, v132, 1, v130
	v_add_u32_e32 v132, 0x2000, v148
	s_sub_i32 s18, s3, s18
	v_ashrrev_i32_e32 v133, 31, v132
	s_lshl_b32 s17, s17, 3
	s_and_b32 s19, s18, 7
	v_lshrrev_b32_e32 v133, 22, v133
	s_or_b32 s28, s19, s17
	v_add_u32_e32 v133, v132, v133
	s_ashr_i32 s22, s18, 3
	s_lshl_b32 s18, s28, 8
	v_ashrrev_i32_e32 v133, 10, v133
	v_mul_i32_i24_e32 v136, 0x400, v133
	s_ashr_i32 s19, s18, 31
	s_lshl_b32 s20, s22, 8
	v_sub_u32_e32 v132, v132, v136
	s_lshl_b64 s[24:25], s[18:19], 11
	v_lshrrev_b32_e32 v136, 4, v132
	s_add_u32 s24, s26, s24
	v_bitop3_b32 v132, v136, v132, 32 bitop3:0x6c
	s_addc_u32 s25, s27, s25
	v_ashrrev_i32_e32 v137, 31, v132
	s_add_u32 s42, s24, 0x40000
	v_lshrrev_b32_e32 v137, 26, v137
	s_addc_u32 s43, s25, 0
	s_ashr_i32 s21, s20, 31
	v_add_u32_e32 v137, v132, v137
	s_lshl_b64 s[20:21], s[20:21], 11
	v_lshrrev_b32_e32 v138, 6, v137
	v_and_b32_e32 v137, 0xc0, v137
	s_add_u32 s20, s4, s20
	v_lshlrev_b32_e32 v136, 3, v133
	v_lshlrev_b32_e32 v133, 5, v133
	v_sub_u32_e32 v132, v132, v137
	s_addc_u32 s21, s5, s21
	v_add_u32_e32 v140, s29, v148
	v_and_b32_e32 v136, 0x1ffff0, v136
	v_and_b32_e32 v133, 32, v133
	v_ashrrev_i16_sdwa v132, v134, sext(v132) dst_sel:DWORD dst_unused:UNUSED_PAD src0_sel:DWORD src1_sel:BYTE_0
	s_add_u32 s44, s20, 0x40000
	v_readfirstlane_b32 s17, v140
	v_add_u32_e32 v140, 0x2000, v140
	v_add_u32_sdwa v132, v133, sext(v132) dst_sel:DWORD dst_unused:UNUSED_PAD src0_sel:DWORD src1_sel:WORD_0
	v_add_lshl_u32 v133, v138, v136, 11
	s_addc_u32 s45, s21, 0
	s_mov_b32 m0, s17
	v_readfirstlane_b32 s17, v140
	v_add_u32_e32 v149, 0x100, v148
	v_lshl_add_u32 v132, v132, 1, v133
	v_add_u32_e32 v144, 0x2000, v149
	s_mov_b32 m0, s17
	v_readfirstlane_b32 s17, v149
	v_mov_b32_e32 v133, v131
	s_mov_b32 m0, s17
	v_readfirstlane_b32 s17, v144
	v_add_u32_e32 v150, s30, v148
	v_lshl_add_u64 v[138:139], s[20:21], 0, v[132:133]
	v_lshl_add_u64 v[142:143], s[24:25], 0, v[132:133]
	s_mov_b32 m0, s17
	v_readfirstlane_b32 s17, v150
	v_lshl_add_u64 v[146:147], s[44:45], 0, v[132:133]
	v_add_u32_e32 v133, 0x2000, v150
	s_mov_b32 m0, s17
	v_readfirstlane_b32 s17, v133
	v_add_u32_e32 v133, 0x4000, v149
	s_mov_b32 m0, s17
	v_readfirstlane_b32 s17, v133
	s_mov_b32 m0, s17
	v_lshl_add_u64 v[136:137], s[20:21], 0, v[130:131]
	v_lshl_add_u64 v[140:141], s[24:25], 0, v[130:131]
	v_lshl_add_u64 v[144:145], s[44:45], 0, v[130:131]
	v_add_u32_e32 v130, 0x6000, v149
	s_nop 0
	v_readfirstlane_b32 s17, v130
	v_add_u32_e32 v130, s31, v148
	s_mov_b32 m0, s17
	v_readfirstlane_b32 s17, v130
	v_add_u32_e32 v130, 0x2000, v130
	v_lshl_add_u64 v[132:133], v[136:137], 0, s[8:9]
	s_mov_b32 m0, s17
	v_readfirstlane_b32 s17, v130
	v_add_u32_e32 v130, 0x8000, v149
	global_load_lds_dwordx4 v[132:133], off
	v_lshl_add_u64 v[132:133], v[138:139], 0, s[8:9]
	s_mov_b32 m0, s17
	v_readfirstlane_b32 s17, v130
	v_add_u32_e32 v130, 0xa000, v149
	global_load_lds_dwordx4 v[132:133], off
	v_lshl_add_u64 v[132:133], v[140:141], 0, s[8:9]
	s_mov_b32 m0, s17
	v_readfirstlane_b32 s17, v130
	v_add_u32_e32 v130, s33, v148
	global_load_lds_dwordx4 v[132:133], off
	v_lshl_add_u64 v[132:133], v[142:143], 0, s[8:9]
	s_mov_b32 m0, s17
	v_readfirstlane_b32 s17, v130
	v_add_u32_e32 v130, 0x2000, v130
	global_load_lds_dwordx4 v[132:133], off
	v_lshl_add_u64 v[132:133], v[144:145], 0, s[8:9]
	s_mov_b32 m0, s17
	v_readfirstlane_b32 s17, v130
	global_load_lds_dwordx4 v[132:133], off
	v_lshl_add_u64 v[132:133], v[146:147], 0, s[8:9]
	s_mov_b32 m0, s17
	v_mov_b32_e32 v130, v170
	global_load_lds_dwordx4 v[132:133], off
	s_nop 0
	v_cmp_gt_i32_e32 vcc, s34, v130
	s_and_saveexec_b64 s[20:21], vcc
	s_cbranch_execz .LBB0_84
	v_add_u32_e32 v132, s18, v130
	v_ashrrev_i32_e32 v133, 31, v132
	v_lshlrev_b64 v[132:133], 6, v[132:133]
	v_lshl_add_u64 v[132:133], s[6:7], 0, v[132:133]
	global_load_dwordx4 v[136:139], v[132:133], off
	global_load_dwordx4 v[140:143], v[132:133], off offset:16
	global_load_dwordx4 v[144:147], v[132:133], off offset:32
	global_load_dwordx4 v[148:151], v[132:133], off offset:48
	s_branch .LBB0_84

; #define STAGE(P, GP, ktrel) do { const GAS char* _g = (GP) + (ktrel) * (BK * 2); \
;     __builtin_amdgcn_global_load_lds((const GAS unsigned*)(_g + so0), (unsigned*)((char*)(P) + tid_ * 16), 16, 0, 0); \
;     __builtin_amdgcn_global_load_lds((const GAS unsigned*)(_g + so1), (unsigned*)((char*)(P) + tid_ * 16 + 8192), 16, 0, 0); } while (0)
; #define WAIT_V(n) asm volatile("s_waitcnt vmcnt(" #n ")" ::: "memory")
; #define WAIT_L(n) asm volatile("s_waitcnt lgkmcnt(" #n ")" ::: "memory")
; #define BAR __builtin_amdgcn_s_barrier()
; #define SCHED __builtin_amdgcn_sched_barrier(0)
; #define LDA(dst, b, h) for (int m = 0; m < 4; ++m) for (int k = 0; k < 2; ++k) \
;     dst[m][k] = *reinterpret_cast<const bf16x8*>((char*)SA(b, h) + lds_byte(wr * 64 + m * 16 + fr, k * 32 + fq * 8))
; #define LDB(dst, b, h) for (int n = 0; n < 2; ++n) for (int k = 0; k < 2; ++k) \
;     dst[n][k] = *reinterpret_cast<const bf16x8*>((char*)SB(b, h) + lds_byte(wc * 32 + n * 16 + fr, k * 32 + fq * 8))
; #define MMA(ai, bj, At_, Bt_) do { __builtin_amdgcn_s_setprio(1); \
;     for (int m = 0; m < 4; ++m) for (int n = 0; n < 2; ++n) for (int k = 0; k < 2; ++k) \
;       acc[ai][bj][m][n] = __builtin_amdgcn_mfma_f32_16x16x32_bf16(At_[m][k], Bt_[n][k], acc[ai][bj][m][n], 0, 0, 0); \
;     __builtin_amdgcn_s_setprio(0); } while (0)
; template <int K, int LD = K>
; __device__ __forceinline__ void gemm_main(const GAS bf16* A, const GAS bf16* Bt, int brow, int bcol, f32x4 (&acc)[2][2][4][2]) {
;     ...
;   for (int t = 0; t < nt - 2; t += 2) {
;     LDB(B0, 0, 0); SCHED; LDA(At, 0, 0); STAGE(SA(1, 1), pA1, 1);
;     WAIT_L(8); BAR; WAIT_L(0); MMA(0, 0, At, B0); BAR; SCHED;
;     LDB(B1, 0, 1); STAGE(SB(0, 0), pB0, 2);
;     BAR; WAIT_L(0); MMA(0, 1, At, B1); BAR;
;     LDA(At, 0, 1); STAGE(SA(0, 0), pA0, 2);
;     BAR; WAIT_L(0); MMA(1, 0, At, B0); BAR; SCHED;
;     STAGE(SB(0, 1), pB1, 2);
;     WAIT_V(6); BAR; MMA(1, 1, At, B1); BAR;
;     LDB(B0, 1, 0); SCHED; LDA(At, 1, 0); STAGE(SA(0, 1), pA1, 2);
;     WAIT_L(8); BAR; WAIT_L(0); MMA(0, 0, At, B0); BAR; SCHED;
.LBB0_709:
	ds_read_b128 v[146:149], v143
	ds_read_b128 v[150:153], v143 offset:1024
	ds_read_b128 v[154:157], v143 offset:2048
	ds_read_b128 v[158:161], v143 offset:3072
	v_add_u32_e32 v230, 0x100, v141
	v_add_u32_e32 v144, 0xc000, v230
	v_lshl_add_u64 v[214:215], s[20:21], 0, v[130:131]
	v_readfirstlane_b32 s30, v144
	v_add_u32_e32 v145, 0xe000, v230
	v_lshl_add_u64 v[198:199], v[214:215], 0, s[6:7]
	s_mov_b32 m0, s30
	v_lshl_add_u64 v[216:217], s[20:21], 0, v[132:133]
	v_readfirstlane_b32 s30, v145
	ds_read_b128 v[162:165], v138
	ds_read_b128 v[166:169], v138 offset:1024
	ds_read_b128 v[174:177], v137
	ds_read_b128 v[178:181], v137 offset:1024
	ds_read_b128 v[182:185], v136
	ds_read_b128 v[186:189], v136 offset:1024
	ds_read_b128 v[190:193], v135
	ds_read_b128 v[194:197], v135 offset:1024
	global_load_lds_dwordx4 v[198:199], off
	v_lshl_add_u64 v[198:199], v[216:217], 0, s[6:7]
	s_mov_b32 m0, s30
	s_nop 0
	global_load_lds_dwordx4 v[198:199], off
	s_waitcnt lgkmcnt(8)
	s_barrier
	s_waitcnt lgkmcnt(0)
	s_setprio 1
	s_waitcnt lgkmcnt(0)
	v_mfma_f32_16x16x32_bf16 v[126:129], v[146:149], v[162:165], v[126:129]
	v_mfma_f32_16x16x32_bf16 v[122:125], v[154:157], v[162:165], v[122:125]
	v_mfma_f32_16x16x32_bf16 v[118:121], v[146:149], v[174:177], v[118:121]
	v_mfma_f32_16x16x32_bf16 v[114:117], v[154:157], v[174:177], v[114:117]
	v_mfma_f32_16x16x32_bf16 v[110:113], v[146:149], v[182:185], v[110:113]
	v_mfma_f32_16x16x32_bf16 v[106:109], v[154:157], v[182:185], v[106:109]
	v_mfma_f32_16x16x32_bf16 v[102:105], v[146:149], v[190:193], v[102:105]
	v_mfma_f32_16x16x32_bf16 v[98:101], v[154:157], v[190:193], v[98:101]
	v_mfma_f32_16x16x32_bf16 v[126:129], v[150:153], v[166:169], v[126:129]
	v_mfma_f32_16x16x32_bf16 v[122:125], v[158:161], v[166:169], v[122:125]
	v_mfma_f32_16x16x32_bf16 v[118:121], v[150:153], v[178:181], v[118:121]
	v_mfma_f32_16x16x32_bf16 v[114:117], v[158:161], v[178:181], v[114:117]
	v_mfma_f32_16x16x32_bf16 v[110:113], v[150:153], v[186:189], v[110:113]
	v_mfma_f32_16x16x32_bf16 v[106:109], v[158:161], v[186:189], v[106:109]
	v_mfma_f32_16x16x32_bf16 v[102:105], v[150:153], v[194:197], v[102:105]
	v_mfma_f32_16x16x32_bf16 v[98:101], v[158:161], v[194:197], v[98:101]
	s_setprio 0
	s_barrier
	v_add_u32_e32 v224, s47, v141
	v_lshl_add_u64 v[218:219], s[28:29], 0, v[130:131]
	v_readfirstlane_b32 s30, v224
	v_lshl_add_u64 v[220:221], v[218:219], 0, s[10:11]
	s_mov_b32 m0, s30
	v_add_u32_e32 v224, 0x2000, v224
	ds_read_b128 v[198:201], v142
	ds_read_b128 v[202:205], v142 offset:1024
	ds_read_b128 v[206:209], v142 offset:2048
	ds_read_b128 v[210:213], v142 offset:3072
	global_load_lds_dwordx4 v[220:221], off
	v_lshl_add_u64 v[220:221], s[28:29], 0, v[132:133]
	v_readfirstlane_b32 s30, v224
	v_lshl_add_u64 v[222:223], v[220:221], 0, s[10:11]
	s_mov_b32 m0, s30
	s_add_u32 s28, s28, 0x100
	global_load_lds_dwordx4 v[222:223], off
	s_barrier
	s_waitcnt lgkmcnt(0)
	s_addc_u32 s29, s29, 0
	s_setprio 1
	s_waitcnt lgkmcnt(0)
	v_mfma_f32_16x16x32_bf16 v[94:97], v[198:201], v[162:165], v[94:97]
	v_mfma_f32_16x16x32_bf16 v[90:93], v[206:209], v[162:165], v[90:93]
	v_mfma_f32_16x16x32_bf16 v[86:89], v[198:201], v[174:177], v[86:89]
	v_mfma_f32_16x16x32_bf16 v[82:85], v[206:209], v[174:177], v[82:85]
	v_mfma_f32_16x16x32_bf16 v[78:81], v[198:201], v[182:185], v[78:81]
	v_mfma_f32_16x16x32_bf16 v[74:77], v[206:209], v[182:185], v[74:77]
	v_mfma_f32_16x16x32_bf16 v[70:73], v[198:201], v[190:193], v[70:73]
	v_mfma_f32_16x16x32_bf16 v[66:69], v[206:209], v[190:193], v[66:69]
	v_mfma_f32_16x16x32_bf16 v[94:97], v[202:205], v[166:169], v[94:97]
	v_mfma_f32_16x16x32_bf16 v[90:93], v[210:213], v[166:169], v[90:93]
	v_mfma_f32_16x16x32_bf16 v[86:89], v[202:205], v[178:181], v[86:89]
	v_mfma_f32_16x16x32_bf16 v[82:85], v[210:213], v[178:181], v[82:85]
	v_mfma_f32_16x16x32_bf16 v[78:81], v[202:205], v[186:189], v[78:81]
	v_mfma_f32_16x16x32_bf16 v[74:77], v[210:213], v[186:189], v[74:77]
	v_mfma_f32_16x16x32_bf16 v[70:73], v[202:205], v[194:197], v[70:73]
	v_mfma_f32_16x16x32_bf16 v[66:69], v[210:213], v[194:197], v[66:69]
	s_setprio 0
	v_lshl_add_u64 v[222:223], s[26:27], 0, v[130:131]
	v_readfirstlane_b32 s30, v230
	v_lshl_add_u64 v[224:225], v[222:223], 0, s[10:11]
	s_mov_b32 m0, s30
	v_add_u32_e32 v228, 0x2000, v230
	s_barrier
	ds_read_b128 v[162:165], v138 offset:16384
	ds_read_b128 v[166:169], v138 offset:17408
	ds_read_b128 v[174:177], v137 offset:16384
	ds_read_b128 v[178:181], v137 offset:17408
	ds_read_b128 v[182:185], v136 offset:16384
	ds_read_b128 v[186:189], v136 offset:17408
	ds_read_b128 v[190:193], v135 offset:16384
	ds_read_b128 v[194:197], v135 offset:17408
	global_load_lds_dwordx4 v[224:225], off
	v_lshl_add_u64 v[224:225], s[26:27], 0, v[132:133]
	v_readfirstlane_b32 s30, v228
	v_lshl_add_u64 v[226:227], v[224:225], 0, s[10:11]
	s_mov_b32 m0, s30
	s_add_u32 s26, s26, 0x100
	global_load_lds_dwordx4 v[226:227], off
	s_barrier
	s_waitcnt lgkmcnt(0)
	s_addc_u32 s27, s27, 0
	s_setprio 1
	s_waitcnt lgkmcnt(0)
	v_mfma_f32_16x16x32_bf16 v[62:65], v[146:149], v[162:165], v[62:65]
	v_mfma_f32_16x16x32_bf16 v[58:61], v[154:157], v[162:165], v[58:61]
	v_mfma_f32_16x16x32_bf16 v[54:57], v[146:149], v[174:177], v[54:57]
	v_mfma_f32_16x16x32_bf16 v[50:53], v[154:157], v[174:177], v[50:53]
	v_mfma_f32_16x16x32_bf16 v[46:49], v[146:149], v[182:185], v[46:49]
	v_mfma_f32_16x16x32_bf16 v[42:45], v[154:157], v[182:185], v[42:45]
	v_mfma_f32_16x16x32_bf16 v[38:41], v[146:149], v[190:193], v[38:41]
	v_mfma_f32_16x16x32_bf16 v[34:37], v[154:157], v[190:193], v[34:37]
	v_mfma_f32_16x16x32_bf16 v[62:65], v[150:153], v[166:169], v[62:65]
	v_mfma_f32_16x16x32_bf16 v[58:61], v[158:161], v[166:169], v[58:61]
	v_mfma_f32_16x16x32_bf16 v[54:57], v[150:153], v[178:181], v[54:57]
	v_mfma_f32_16x16x32_bf16 v[50:53], v[158:161], v[178:181], v[50:53]
	v_mfma_f32_16x16x32_bf16 v[46:49], v[150:153], v[186:189], v[46:49]
	v_mfma_f32_16x16x32_bf16 v[42:45], v[158:161], v[186:189], v[42:45]
	v_mfma_f32_16x16x32_bf16 v[38:41], v[150:153], v[194:197], v[38:41]
	v_mfma_f32_16x16x32_bf16 v[34:37], v[158:161], v[194:197], v[34:37]
	s_setprio 0
	s_barrier
; #define STAGE(P, GP, ktrel) do { const GAS char* _g = (GP) + (ktrel) * (BK * 2); \
;     __builtin_amdgcn_global_load_lds((const GAS unsigned*)(_g + so0), (unsigned*)((char*)(P) + tid_ * 16), 16, 0, 0); \
;     __builtin_amdgcn_global_load_lds((const GAS unsigned*)(_g + so1), (unsigned*)((char*)(P) + tid_ * 16 + 8192), 16, 0, 0); } while (0)
; #define WAIT_V(n) asm volatile("s_waitcnt vmcnt(" #n ")" ::: "memory")
; #define WAIT_L(n) asm volatile("s_waitcnt lgkmcnt(" #n ")" ::: "memory")
; #define BAR __builtin_amdgcn_s_barrier()
; #define SCHED __builtin_amdgcn_sched_barrier(0)
; #define LDA(dst, b, h) for (int m = 0; m < 4; ++m) for (int k = 0; k < 2; ++k) \
;     dst[m][k] = *reinterpret_cast<const bf16x8*>((char*)SA(b, h) + lds_byte(wr * 64 + m * 16 + fr, k * 32 + fq * 8))
; #define LDB(dst, b, h) for (int n = 0; n < 2; ++n) for (int k = 0; k < 2; ++k) \
;     dst[n][k] = *reinterpret_cast<const bf16x8*>((char*)SB(b, h) + lds_byte(wc * 32 + n * 16 + fr, k * 32 + fq * 8))
; #define MMA(ai, bj, At_, Bt_) do { __builtin_amdgcn_s_setprio(1); \
;     for (int m = 0; m < 4; ++m) for (int n = 0; n < 2; ++n) for (int k = 0; k < 2; ++k) \
;       acc[ai][bj][m][n] = __builtin_amdgcn_mfma_f32_16x16x32_bf16(At_[m][k], Bt_[n][k], acc[ai][bj][m][n], 0, 0, 0); \
;     __builtin_amdgcn_s_setprio(0); } while (0)
; template <int K, int LD = K>
; __device__ __forceinline__ void gemm_main(const GAS bf16* A, const GAS bf16* Bt, int brow, int bcol, f32x4 (&acc)[2][2][4][2]) {
;     ...
;     WAIT_V(6); BAR; MMA(1, 1, At, B1); BAR;
;     LDB(B0, 1, 0); SCHED; LDA(At, 1, 0); STAGE(SA(0, 1), pA1, 2);
;     WAIT_L(8); BAR; WAIT_L(0); MMA(0, 0, At, B0); BAR; SCHED;
;     LDB(B1, 1, 1); STAGE(SB(1, 0), pB0, 3);
;     BAR; WAIT_L(0); MMA(0, 1, At, B1); BAR;
;     LDA(At, 1, 1); STAGE(SA(1, 0), pA0, 3);
;     BAR; WAIT_L(0); MMA(1, 0, At, B0); BAR; SCHED;
	v_add_u32_e32 v148, s48, v141
	v_lshl_add_u64 v[226:227], s[24:25], 0, v[130:131]
	v_readfirstlane_b32 s30, v148
	v_add_u32_e32 v148, 0x2000, v148
	v_lshl_add_u64 v[146:147], v[226:227], 0, s[10:11]
	s_mov_b32 m0, s30
	v_lshl_add_u64 v[228:229], s[24:25], 0, v[132:133]
	v_readfirstlane_b32 s30, v148
	global_load_lds_dwordx4 v[146:147], off
	v_lshl_add_u64 v[146:147], v[228:229], 0, s[10:11]
	s_mov_b32 m0, s30
	s_add_u32 s24, s24, 0x100
	global_load_lds_dwordx4 v[146:147], off
	s_waitcnt vmcnt(6)
	s_addc_u32 s25, s25, 0
	s_barrier
	s_setprio 1
	v_mfma_f32_16x16x32_bf16 v[30:33], v[198:201], v[162:165], v[30:33]
	v_mfma_f32_16x16x32_bf16 v[26:29], v[206:209], v[162:165], v[26:29]
	v_mfma_f32_16x16x32_bf16 v[22:25], v[198:201], v[174:177], v[22:25]
	v_mfma_f32_16x16x32_bf16 v[18:21], v[206:209], v[174:177], v[18:21]
	v_mfma_f32_16x16x32_bf16 v[14:17], v[198:201], v[182:185], v[14:17]
	v_mfma_f32_16x16x32_bf16 v[10:13], v[206:209], v[182:185], v[10:13]
	v_mfma_f32_16x16x32_bf16 v[6:9], v[198:201], v[190:193], v[6:9]
	v_mfma_f32_16x16x32_bf16 v[2:5], v[206:209], v[190:193], v[2:5]
	v_mfma_f32_16x16x32_bf16 v[30:33], v[202:205], v[166:169], v[30:33]
	v_mfma_f32_16x16x32_bf16 v[26:29], v[210:213], v[166:169], v[26:29]
	v_mfma_f32_16x16x32_bf16 v[22:25], v[202:205], v[178:181], v[22:25]
	v_mfma_f32_16x16x32_bf16 v[18:21], v[210:213], v[178:181], v[18:21]
	v_mfma_f32_16x16x32_bf16 v[14:17], v[202:205], v[186:189], v[14:17]
	v_mfma_f32_16x16x32_bf16 v[10:13], v[210:213], v[186:189], v[10:13]
	v_mfma_f32_16x16x32_bf16 v[6:9], v[202:205], v[194:197], v[6:9]
	v_mfma_f32_16x16x32_bf16 v[2:5], v[210:213], v[194:197], v[2:5]
	s_setprio 0
	s_barrier
	ds_read_b128 v[146:149], v140
	ds_read_b128 v[150:153], v140 offset:1024
	ds_read_b128 v[154:157], v140 offset:2048
	ds_read_b128 v[158:161], v140 offset:3072
	v_add_u32_e32 v200, 0x4000, v230
	v_lshl_add_u64 v[198:199], v[214:215], 0, s[10:11]
	v_readfirstlane_b32 s30, v200
	v_add_u32_e32 v200, 0x6000, v230
	s_mov_b32 m0, s30
	v_readfirstlane_b32 s30, v200
	ds_read_b128 v[162:165], v138 offset:32768
	ds_read_b128 v[166:169], v138 offset:33792
	ds_read_b128 v[174:177], v137 offset:32768
	ds_read_b128 v[178:181], v137 offset:33792
	ds_read_b128 v[182:185], v136 offset:32768
	ds_read_b128 v[186:189], v136 offset:33792
	ds_read_b128 v[190:193], v135 offset:32768
	ds_read_b128 v[194:197], v135 offset:33792
	global_load_lds_dwordx4 v[198:199], off
	v_lshl_add_u64 v[198:199], v[216:217], 0, s[10:11]
	s_mov_b32 m0, s30
	s_add_u32 s20, s20, 0x100
	global_load_lds_dwordx4 v[198:199], off
	s_waitcnt lgkmcnt(8)
	s_barrier
	s_waitcnt lgkmcnt(0)
	s_addc_u32 s21, s21, 0
	s_setprio 1
	s_waitcnt lgkmcnt(0)
	v_mfma_f32_16x16x32_bf16 v[126:129], v[146:149], v[162:165], v[126:129]
	v_mfma_f32_16x16x32_bf16 v[122:125], v[154:157], v[162:165], v[122:125]
	v_mfma_f32_16x16x32_bf16 v[118:121], v[146:149], v[174:177], v[118:121]
	v_mfma_f32_16x16x32_bf16 v[114:117], v[154:157], v[174:177], v[114:117]
	v_mfma_f32_16x16x32_bf16 v[110:113], v[146:149], v[182:185], v[110:113]
	v_mfma_f32_16x16x32_bf16 v[106:109], v[154:157], v[182:185], v[106:109]
	v_mfma_f32_16x16x32_bf16 v[102:105], v[146:149], v[190:193], v[102:105]
	v_mfma_f32_16x16x32_bf16 v[98:101], v[154:157], v[190:193], v[98:101]
	v_mfma_f32_16x16x32_bf16 v[126:129], v[150:153], v[166:169], v[126:129]
	v_mfma_f32_16x16x32_bf16 v[122:125], v[158:161], v[166:169], v[122:125]
	v_mfma_f32_16x16x32_bf16 v[118:121], v[150:153], v[178:181], v[118:121]
	v_mfma_f32_16x16x32_bf16 v[114:117], v[158:161], v[178:181], v[114:117]
	v_mfma_f32_16x16x32_bf16 v[110:113], v[150:153], v[186:189], v[110:113]
	v_mfma_f32_16x16x32_bf16 v[106:109], v[158:161], v[186:189], v[106:109]
	v_mfma_f32_16x16x32_bf16 v[102:105], v[150:153], v[194:197], v[102:105]
	v_mfma_f32_16x16x32_bf16 v[98:101], v[158:161], v[194:197], v[98:101]
	s_setprio 0
	s_barrier
	v_add_u32_e32 v216, s49, v141
	v_lshl_add_u64 v[214:215], v[218:219], 0, s[12:13]
	v_readfirstlane_b32 s30, v216
	v_add_u32_e32 v216, 0x2000, v216
	s_mov_b32 m0, s30
	v_readfirstlane_b32 s30, v216
	ds_read_b128 v[198:201], v139
	ds_read_b128 v[202:205], v139 offset:1024
	ds_read_b128 v[206:209], v139 offset:2048
	ds_read_b128 v[210:213], v139 offset:3072
	global_load_lds_dwordx4 v[214:215], off
	v_lshl_add_u64 v[214:215], v[220:221], 0, s[12:13]
	s_mov_b32 m0, s30
	s_nop 0
	global_load_lds_dwordx4 v[214:215], off
	s_barrier
	s_waitcnt lgkmcnt(0)
	s_setprio 1
	s_waitcnt lgkmcnt(0)
	v_mfma_f32_16x16x32_bf16 v[94:97], v[198:201], v[162:165], v[94:97]
	v_mfma_f32_16x16x32_bf16 v[90:93], v[206:209], v[162:165], v[90:93]
	v_mfma_f32_16x16x32_bf16 v[86:89], v[198:201], v[174:177], v[86:89]
	v_mfma_f32_16x16x32_bf16 v[82:85], v[206:209], v[174:177], v[82:85]
	v_mfma_f32_16x16x32_bf16 v[78:81], v[198:201], v[182:185], v[78:81]
	v_mfma_f32_16x16x32_bf16 v[74:77], v[206:209], v[182:185], v[74:77]
	v_mfma_f32_16x16x32_bf16 v[70:73], v[198:201], v[190:193], v[70:73]
	v_mfma_f32_16x16x32_bf16 v[66:69], v[206:209], v[190:193], v[66:69]
	v_mfma_f32_16x16x32_bf16 v[94:97], v[202:205], v[166:169], v[94:97]
	v_mfma_f32_16x16x32_bf16 v[90:93], v[210:213], v[166:169], v[90:93]
	v_mfma_f32_16x16x32_bf16 v[86:89], v[202:205], v[178:181], v[86:89]
	v_mfma_f32_16x16x32_bf16 v[82:85], v[210:213], v[178:181], v[82:85]
	v_mfma_f32_16x16x32_bf16 v[78:81], v[202:205], v[186:189], v[78:81]
	v_mfma_f32_16x16x32_bf16 v[74:77], v[210:213], v[186:189], v[74:77]
	v_mfma_f32_16x16x32_bf16 v[70:73], v[202:205], v[194:197], v[70:73]
	v_mfma_f32_16x16x32_bf16 v[66:69], v[210:213], v[194:197], v[66:69]
	s_setprio 0
	v_add_u32_e32 v216, 0x8000, v230
	v_lshl_add_u64 v[214:215], v[222:223], 0, s[12:13]
	v_readfirstlane_b32 s30, v216
	v_add_u32_e32 v216, 0xa000, v230
	s_mov_b32 m0, s30
	v_readfirstlane_b32 s30, v216
	s_barrier
; #define STAGE(P, GP, ktrel) do { const GAS char* _g = (GP) + (ktrel) * (BK * 2); \
;     __builtin_amdgcn_global_load_lds((const GAS unsigned*)(_g + so0), (unsigned*)((char*)(P) + tid_ * 16), 16, 0, 0); \
;     __builtin_amdgcn_global_load_lds((const GAS unsigned*)(_g + so1), (unsigned*)((char*)(P) + tid_ * 16 + 8192), 16, 0, 0); } while (0)
; #define WAIT_V(n) asm volatile("s_waitcnt vmcnt(" #n ")" ::: "memory")
; #define WAIT_L(n) asm volatile("s_waitcnt lgkmcnt(" #n ")" ::: "memory")
; #define BAR __builtin_amdgcn_s_barrier()
; #define SCHED __builtin_amdgcn_sched_barrier(0)
; #define LDA(dst, b, h) for (int m = 0; m < 4; ++m) for (int k = 0; k < 2; ++k) \
;     dst[m][k] = *reinterpret_cast<const bf16x8*>((char*)SA(b, h) + lds_byte(wr * 64 + m * 16 + fr, k * 32 + fq * 8))
; #define MMA(ai, bj, At_, Bt_) do { __builtin_amdgcn_s_setprio(1); \
;     for (int m = 0; m < 4; ++m) for (int n = 0; n < 2; ++n) for (int k = 0; k < 2; ++k) \
;       acc[ai][bj][m][n] = __builtin_amdgcn_mfma_f32_16x16x32_bf16(At_[m][k], Bt_[n][k], acc[ai][bj][m][n], 0, 0, 0); \
;     __builtin_amdgcn_s_setprio(0); } while (0)
; template <int K, int LD = K>
; __device__ __forceinline__ void gemm_main(const GAS bf16* A, const GAS bf16* Bt, int brow, int bcol, f32x4 (&acc)[2][2][4][2]) {
;     ...
;     LDA(At, 1, 1); STAGE(SA(1, 0), pA0, 3);
;     BAR; WAIT_L(0); MMA(1, 0, At, B0); BAR; SCHED;
;     STAGE(SB(1, 1), pB1, 3);
;     WAIT_V(6); BAR; MMA(1, 1, At, B1); BAR;
;     pA0 += 4 * BK; pA1 += 4 * BK; pB0 += 4 * BK; pB1 += 4 * BK;
;     asm volatile("" : "+s"(pA0), "+s"(pA1), "+s"(pB0), "+s"(pB1));
;   }
	ds_read_b128 v[162:165], v138 offset:49152
	ds_read_b128 v[166:169], v138 offset:50176
	ds_read_b128 v[174:177], v137 offset:49152
	ds_read_b128 v[178:181], v137 offset:50176
	ds_read_b128 v[182:185], v136 offset:49152
	ds_read_b128 v[186:189], v136 offset:50176
	ds_read_b128 v[190:193], v135 offset:49152
	ds_read_b128 v[194:197], v135 offset:50176
	global_load_lds_dwordx4 v[214:215], off
	v_lshl_add_u64 v[214:215], v[224:225], 0, s[12:13]
	s_mov_b32 m0, s30
	s_nop 0
	global_load_lds_dwordx4 v[214:215], off
	s_barrier
	s_waitcnt lgkmcnt(0)
	s_setprio 1
	s_waitcnt lgkmcnt(0)
	v_mfma_f32_16x16x32_bf16 v[62:65], v[146:149], v[162:165], v[62:65]
	v_mfma_f32_16x16x32_bf16 v[58:61], v[154:157], v[162:165], v[58:61]
	v_mfma_f32_16x16x32_bf16 v[54:57], v[146:149], v[174:177], v[54:57]
	v_mfma_f32_16x16x32_bf16 v[50:53], v[154:157], v[174:177], v[50:53]
	v_mfma_f32_16x16x32_bf16 v[46:49], v[146:149], v[182:185], v[46:49]
	v_mfma_f32_16x16x32_bf16 v[42:45], v[154:157], v[182:185], v[42:45]
	v_mfma_f32_16x16x32_bf16 v[38:41], v[146:149], v[190:193], v[38:41]
	v_mfma_f32_16x16x32_bf16 v[34:37], v[154:157], v[190:193], v[34:37]
	v_mfma_f32_16x16x32_bf16 v[62:65], v[150:153], v[166:169], v[62:65]
	v_mfma_f32_16x16x32_bf16 v[58:61], v[158:161], v[166:169], v[58:61]
	v_mfma_f32_16x16x32_bf16 v[54:57], v[150:153], v[178:181], v[54:57]
	v_mfma_f32_16x16x32_bf16 v[50:53], v[158:161], v[178:181], v[50:53]
	v_mfma_f32_16x16x32_bf16 v[46:49], v[150:153], v[186:189], v[46:49]
	v_mfma_f32_16x16x32_bf16 v[42:45], v[158:161], v[186:189], v[42:45]
	v_mfma_f32_16x16x32_bf16 v[38:41], v[150:153], v[194:197], v[38:41]
	v_mfma_f32_16x16x32_bf16 v[34:37], v[158:161], v[194:197], v[34:37]
	s_setprio 0
	s_barrier
	v_add_u32_e32 v148, s50, v141
	v_lshl_add_u64 v[146:147], v[226:227], 0, s[12:13]
	v_readfirstlane_b32 s30, v148
	v_add_u32_e32 v148, 0x2000, v148
	s_mov_b32 m0, s30
	v_readfirstlane_b32 s30, v148
	global_load_lds_dwordx4 v[146:147], off
	v_lshl_add_u64 v[146:147], v[228:229], 0, s[12:13]
	s_mov_b32 m0, s30
	s_nop 0
	global_load_lds_dwordx4 v[146:147], off
	s_waitcnt vmcnt(6)
	s_barrier
	s_setprio 1
	v_mfma_f32_16x16x32_bf16 v[30:33], v[198:201], v[162:165], v[30:33]
	v_mfma_f32_16x16x32_bf16 v[26:29], v[206:209], v[162:165], v[26:29]
	v_mfma_f32_16x16x32_bf16 v[22:25], v[198:201], v[174:177], v[22:25]
	v_mfma_f32_16x16x32_bf16 v[18:21], v[206:209], v[174:177], v[18:21]
	v_mfma_f32_16x16x32_bf16 v[14:17], v[198:201], v[182:185], v[14:17]
	v_mfma_f32_16x16x32_bf16 v[10:13], v[206:209], v[182:185], v[10:13]
	v_mfma_f32_16x16x32_bf16 v[6:9], v[198:201], v[190:193], v[6:9]
	v_mfma_f32_16x16x32_bf16 v[2:5], v[206:209], v[190:193], v[2:5]
	v_mfma_f32_16x16x32_bf16 v[30:33], v[202:205], v[166:169], v[30:33]
	v_mfma_f32_16x16x32_bf16 v[26:29], v[210:213], v[166:169], v[26:29]
	v_mfma_f32_16x16x32_bf16 v[22:25], v[202:205], v[178:181], v[22:25]
	v_mfma_f32_16x16x32_bf16 v[18:21], v[210:213], v[178:181], v[18:21]
	v_mfma_f32_16x16x32_bf16 v[14:17], v[202:205], v[186:189], v[14:17]
	v_mfma_f32_16x16x32_bf16 v[10:13], v[210:213], v[186:189], v[10:13]
	v_mfma_f32_16x16x32_bf16 v[6:9], v[202:205], v[194:197], v[6:9]
	v_mfma_f32_16x16x32_bf16 v[2:5], v[210:213], v[194:197], v[2:5]
	s_setprio 0
	s_add_i32 s17, s17, 2
	s_cmp_lt_u32 s17, 4
	s_barrier
	s_cbranch_scc1 .LBB0_709
	v_lshl_add_u64 v[198:199], s[20:21], 0, v[130:131]
	v_readfirstlane_b32 s17, v144
	v_lshl_add_u64 v[198:199], v[198:199], 0, s[6:7]
	s_mov_b32 m0, s17
	v_lshl_add_u64 v[132:133], s[20:21], 0, v[132:133]
	v_readfirstlane_b32 s17, v145
	ds_read_b128 v[146:149], v143
	ds_read_b128 v[150:153], v143 offset:1024
	ds_read_b128 v[154:157], v143 offset:2048
	ds_read_b128 v[158:161], v143 offset:3072
	ds_read_b128 v[162:165], v138
	ds_read_b128 v[166:169], v138 offset:1024
	ds_read_b128 v[174:177], v137
	ds_read_b128 v[178:181], v137 offset:1024
	ds_read_b128 v[182:185], v136
	ds_read_b128 v[186:189], v136 offset:1024
	ds_read_b128 v[190:193], v135
	ds_read_b128 v[194:197], v135 offset:1024
	global_load_lds_dwordx4 v[198:199], off
	v_lshl_add_u64 v[132:133], v[132:133], 0, s[6:7]
	s_mov_b32 m0, s17
	s_nop 0
	global_load_lds_dwordx4 v[132:133], off
	s_barrier
	s_waitcnt lgkmcnt(0)
	s_setprio 1
	s_waitcnt lgkmcnt(0)
	v_mfma_f32_16x16x32_bf16 v[126:129], v[146:149], v[162:165], v[126:129]
	v_mfma_f32_16x16x32_bf16 v[122:125], v[154:157], v[162:165], v[122:125]
	v_mfma_f32_16x16x32_bf16 v[110:113], v[146:149], v[182:185], v[110:113]
	v_mfma_f32_16x16x32_bf16 v[106:109], v[154:157], v[182:185], v[106:109]
	v_mfma_f32_16x16x32_bf16 v[126:129], v[150:153], v[166:169], v[126:129]
	v_mfma_f32_16x16x32_bf16 v[122:125], v[158:161], v[166:169], v[122:125]
	v_mfma_f32_16x16x32_bf16 v[118:121], v[146:149], v[174:177], v[118:121]
	v_mfma_f32_16x16x32_bf16 v[114:117], v[154:157], v[174:177], v[114:117]
	v_mfma_f32_16x16x32_bf16 v[110:113], v[150:153], v[186:189], v[110:113]
	v_mfma_f32_16x16x32_bf16 v[106:109], v[158:161], v[186:189], v[106:109]
	v_mfma_f32_16x16x32_bf16 v[102:105], v[146:149], v[190:193], v[102:105]
	v_mfma_f32_16x16x32_bf16 v[98:101], v[154:157], v[190:193], v[98:101]
	v_mfma_f32_16x16x32_bf16 v[198:201], v[150:153], v[178:181], v[118:121]
	v_mfma_f32_16x16x32_bf16 v[202:205], v[158:161], v[178:181], v[114:117]
	v_mfma_f32_16x16x32_bf16 v[206:209], v[150:153], v[194:197], v[102:105]
	v_mfma_f32_16x16x32_bf16 v[210:213], v[158:161], v[194:197], v[98:101]
	s_setprio 0
	s_barrier
	s_nop 1
	ds_read_b128 v[98:101], v142
	ds_read_b128 v[102:105], v142 offset:1024
	ds_read_b128 v[114:117], v142 offset:2048
	ds_read_b128 v[118:121], v142 offset:3072
	s_barrier
; #define STAGE(P, GP, ktrel) do { const GAS char* _g = (GP) + (ktrel) * (BK * 2); \
;     __builtin_amdgcn_global_load_lds((const GAS unsigned*)(_g + so0), (unsigned*)((char*)(P) + tid_ * 16), 16, 0, 0); \
;     __builtin_amdgcn_global_load_lds((const GAS unsigned*)(_g + so1), (unsigned*)((char*)(P) + tid_ * 16 + 8192), 16, 0, 0); } while (0)
; #define WAIT_V(n) asm volatile("s_waitcnt vmcnt(" #n ")" ::: "memory")
; #define WAIT_L(n) asm volatile("s_waitcnt lgkmcnt(" #n ")" ::: "memory")
; #define BAR __builtin_amdgcn_s_barrier()
; #define LDA(dst, b, h) for (int m = 0; m < 4; ++m) for (int k = 0; k < 2; ++k) \
;     dst[m][k] = *reinterpret_cast<const bf16x8*>((char*)SA(b, h) + lds_byte(wr * 64 + m * 16 + fr, k * 32 + fq * 8))
; #define LDB(dst, b, h) for (int n = 0; n < 2; ++n) for (int k = 0; k < 2; ++k) \
;     dst[n][k] = *reinterpret_cast<const bf16x8*>((char*)SB(b, h) + lds_byte(wc * 32 + n * 16 + fr, k * 32 + fq * 8))
; #define MMA(ai, bj, At_, Bt_) do { __builtin_amdgcn_s_setprio(1); \
;     for (int m = 0; m < 4; ++m) for (int n = 0; n < 2; ++n) for (int k = 0; k < 2; ++k) \
;       acc[ai][bj][m][n] = __builtin_amdgcn_mfma_f32_16x16x32_bf16(At_[m][k], Bt_[n][k], acc[ai][bj][m][n], 0, 0, 0); \
;     __builtin_amdgcn_s_setprio(0); } while (0)
; template <int K, int LD = K>
; __device__ __forceinline__ void gemm_main(const GAS bf16* A, const GAS bf16* Bt, int brow, int bcol, f32x4 (&acc)[2][2][4][2]) {
;     ...
;   { LDB(B0, 0, 0); LDA(At, 0, 0); STAGE(SA(1, 1), pA1, 1);
;     BAR; WAIT_L(0); MMA(0, 0, At, B0); BAR;
;     LDB(B1, 0, 1); BAR; WAIT_L(0); MMA(0, 1, At, B1); BAR;
;     LDA(At, 0, 1); WAIT_V(4); BAR; WAIT_L(0); MMA(1, 0, At, B0); MMA(1, 1, At, B1); BAR; }
;   { LDB(B0, 1, 0); LDA(At, 1, 0); WAIT_V(2); BAR; WAIT_L(0); MMA(0, 0, At, B0); BAR;
;     LDB(B1, 1, 1); WAIT_V(0); BAR; WAIT_L(0); MMA(0, 1, At, B1); BAR;
	s_waitcnt lgkmcnt(0)
	s_setprio 1
	s_waitcnt lgkmcnt(0)
	v_mfma_f32_16x16x32_bf16 v[94:97], v[98:101], v[162:165], v[94:97]
	v_mfma_f32_16x16x32_bf16 v[90:93], v[114:117], v[162:165], v[90:93]
	v_mfma_f32_16x16x32_bf16 v[70:73], v[98:101], v[190:193], v[70:73]
	v_mfma_f32_16x16x32_bf16 v[66:69], v[114:117], v[190:193], v[66:69]
	v_mfma_f32_16x16x32_bf16 v[94:97], v[102:105], v[166:169], v[94:97]
	v_mfma_f32_16x16x32_bf16 v[90:93], v[118:121], v[166:169], v[90:93]
	v_mfma_f32_16x16x32_bf16 v[86:89], v[98:101], v[174:177], v[86:89]
	v_mfma_f32_16x16x32_bf16 v[82:85], v[114:117], v[174:177], v[82:85]
	v_mfma_f32_16x16x32_bf16 v[78:81], v[98:101], v[182:185], v[78:81]
	v_mfma_f32_16x16x32_bf16 v[74:77], v[114:117], v[182:185], v[74:77]
	v_mfma_f32_16x16x32_bf16 v[70:73], v[102:105], v[194:197], v[70:73]
	v_mfma_f32_16x16x32_bf16 v[66:69], v[118:121], v[194:197], v[66:69]
	v_mfma_f32_16x16x32_bf16 v[142:145], v[102:105], v[178:181], v[86:89]
	v_mfma_f32_16x16x32_bf16 v[162:165], v[118:121], v[178:181], v[82:85]
	v_mfma_f32_16x16x32_bf16 v[166:169], v[102:105], v[186:189], v[78:81]
	v_mfma_f32_16x16x32_bf16 v[174:177], v[118:121], v[186:189], v[74:77]
	s_setprio 0
	s_barrier
	s_nop 0
	ds_read_b128 v[74:77], v138 offset:16384
	ds_read_b128 v[78:81], v138 offset:17408
	ds_read_b128 v[82:85], v137 offset:16384
	ds_read_b128 v[86:89], v137 offset:17408
	ds_read_b128 v[178:181], v136 offset:16384
	ds_read_b128 v[182:185], v136 offset:17408
	ds_read_b128 v[186:189], v135 offset:16384
	ds_read_b128 v[190:193], v135 offset:17408
	s_waitcnt vmcnt(4)
	s_barrier
	s_waitcnt lgkmcnt(0)
	s_setprio 1
	s_waitcnt lgkmcnt(0)
	v_mfma_f32_16x16x32_bf16 v[62:65], v[146:149], v[74:77], v[62:65]
	v_mfma_f32_16x16x32_bf16 v[58:61], v[154:157], v[74:77], v[58:61]
	v_mfma_f32_16x16x32_bf16 v[54:57], v[146:149], v[82:85], v[54:57]
	v_mfma_f32_16x16x32_bf16 v[50:53], v[154:157], v[82:85], v[50:53]
	v_mfma_f32_16x16x32_bf16 v[38:41], v[146:149], v[186:189], v[38:41]
	v_mfma_f32_16x16x32_bf16 v[34:37], v[154:157], v[186:189], v[34:37]
	v_mfma_f32_16x16x32_bf16 v[62:65], v[150:153], v[78:81], v[62:65]
	v_mfma_f32_16x16x32_bf16 v[58:61], v[158:161], v[78:81], v[58:61]
	v_mfma_f32_16x16x32_bf16 v[54:57], v[150:153], v[86:89], v[54:57]
	v_mfma_f32_16x16x32_bf16 v[50:53], v[158:161], v[86:89], v[50:53]
	v_mfma_f32_16x16x32_bf16 v[46:49], v[146:149], v[178:181], v[46:49]
	v_mfma_f32_16x16x32_bf16 v[42:45], v[154:157], v[178:181], v[42:45]
	v_mfma_f32_16x16x32_bf16 v[38:41], v[150:153], v[190:193], v[38:41]
	v_mfma_f32_16x16x32_bf16 v[34:37], v[158:161], v[190:193], v[34:37]
	v_mfma_f32_16x16x32_bf16 v[194:197], v[150:153], v[182:185], v[46:49]
	v_mfma_f32_16x16x32_bf16 v[214:217], v[158:161], v[182:185], v[42:45]
	s_setprio 0
	s_setprio 1
	v_mfma_f32_16x16x32_bf16 v[22:25], v[98:101], v[82:85], v[22:25]
	v_mfma_f32_16x16x32_bf16 v[18:21], v[114:117], v[82:85], v[18:21]
	v_mfma_f32_16x16x32_bf16 v[14:17], v[98:101], v[178:181], v[14:17]
	v_mfma_f32_16x16x32_bf16 v[10:13], v[114:117], v[178:181], v[10:13]
	v_mfma_f32_16x16x32_bf16 v[30:33], v[98:101], v[74:77], v[30:33]
	v_mfma_f32_16x16x32_bf16 v[26:29], v[114:117], v[74:77], v[26:29]
	v_mfma_f32_16x16x32_bf16 v[22:25], v[102:105], v[86:89], v[22:25]
	v_mfma_f32_16x16x32_bf16 v[18:21], v[118:121], v[86:89], v[18:21]
	v_mfma_f32_16x16x32_bf16 v[14:17], v[102:105], v[182:185], v[14:17]
	v_mfma_f32_16x16x32_bf16 v[10:13], v[118:121], v[182:185], v[10:13]
	v_mfma_f32_16x16x32_bf16 v[6:9], v[98:101], v[186:189], v[6:9]
	v_mfma_f32_16x16x32_bf16 v[2:5], v[114:117], v[186:189], v[2:5]
	v_mfma_f32_16x16x32_bf16 v[146:149], v[102:105], v[78:81], v[30:33]
	v_mfma_f32_16x16x32_bf16 v[150:153], v[118:121], v[78:81], v[26:29]
	v_mfma_f32_16x16x32_bf16 v[154:157], v[102:105], v[190:193], v[6:9]
	v_mfma_f32_16x16x32_bf16 v[158:161], v[118:121], v[190:193], v[2:5]
	s_setprio 0
	s_barrier
	s_nop 1
	ds_read_b128 v[2:5], v140
	ds_read_b128 v[6:9], v140 offset:1024
	ds_read_b128 v[178:181], v140 offset:2048
	ds_read_b128 v[182:185], v140 offset:3072
	ds_read_b128 v[26:29], v138 offset:32768
	ds_read_b128 v[30:33], v138 offset:33792
	ds_read_b128 v[42:45], v137 offset:32768
	ds_read_b128 v[46:49], v137 offset:33792
	ds_read_b128 v[186:189], v136 offset:32768
	ds_read_b128 v[190:193], v136 offset:33792
	ds_read_b128 v[218:221], v135 offset:32768
	ds_read_b128 v[222:225], v135 offset:33792
	s_waitcnt vmcnt(2)
	s_barrier
	s_waitcnt lgkmcnt(0)
	s_setprio 1
	s_waitcnt lgkmcnt(0)
	v_mfma_f32_16x16x32_bf16 v[74:77], v[2:5], v[26:29], v[126:129]
	v_mfma_f32_16x16x32_bf16 v[118:121], v[6:9], v[30:33], v[74:77]
	v_mfma_f32_16x16x32_bf16 v[74:77], v[178:181], v[26:29], v[122:125]
	v_mfma_f32_16x16x32_bf16 v[114:117], v[182:185], v[30:33], v[74:77]
	v_mfma_f32_16x16x32_bf16 v[74:77], v[2:5], v[42:45], v[198:201]
	v_mfma_f32_16x16x32_bf16 v[102:105], v[6:9], v[46:49], v[74:77]
	v_mfma_f32_16x16x32_bf16 v[74:77], v[178:181], v[42:45], v[202:205]
	v_mfma_f32_16x16x32_bf16 v[98:101], v[182:185], v[46:49], v[74:77]
	v_mfma_f32_16x16x32_bf16 v[74:77], v[2:5], v[186:189], v[110:113]
	v_mfma_f32_16x16x32_bf16 v[86:89], v[6:9], v[190:193], v[74:77]
	v_mfma_f32_16x16x32_bf16 v[74:77], v[178:181], v[186:189], v[106:109]
	v_mfma_f32_16x16x32_bf16 v[82:85], v[182:185], v[190:193], v[74:77]
	v_mfma_f32_16x16x32_bf16 v[74:77], v[2:5], v[218:221], v[206:209]
	v_mfma_f32_16x16x32_bf16 v[78:81], v[6:9], v[222:225], v[74:77]
	v_mfma_f32_16x16x32_bf16 v[74:77], v[178:181], v[218:221], v[210:213]
	v_mfma_f32_16x16x32_bf16 v[74:77], v[182:185], v[222:225], v[74:77]
	s_setprio 0
	s_barrier
; #define GAS __attribute__((address_space(1)))
; __device__ __forceinline__ int otid() { int t = threadIdx.x; asm volatile("" : "+v"(t)); return t; }
; #define WAIT_V(n) asm volatile("s_waitcnt vmcnt(" #n ")" ::: "memory")
; #define WAIT_L(n) asm volatile("s_waitcnt lgkmcnt(" #n ")" ::: "memory")
; #define BAR __builtin_amdgcn_s_barrier()
; #define LDA(dst, b, h) for (int m = 0; m < 4; ++m) for (int k = 0; k < 2; ++k) \
;     dst[m][k] = *reinterpret_cast<const bf16x8*>((char*)SA(b, h) + lds_byte(wr * 64 + m * 16 + fr, k * 32 + fq * 8))
; #define LDB(dst, b, h) for (int n = 0; n < 2; ++n) for (int k = 0; k < 2; ++k) \
;     dst[n][k] = *reinterpret_cast<const bf16x8*>((char*)SB(b, h) + lds_byte(wc * 32 + n * 16 + fr, k * 32 + fq * 8))
; #define MMA(ai, bj, At_, Bt_) do { __builtin_amdgcn_s_setprio(1); \
;     for (int m = 0; m < 4; ++m) for (int n = 0; n < 2; ++n) for (int k = 0; k < 2; ++k) \
;       acc[ai][bj][m][n] = __builtin_amdgcn_mfma_f32_16x16x32_bf16(At_[m][k], Bt_[n][k], acc[ai][bj][m][n], 0, 0, 0); \
;     __builtin_amdgcn_s_setprio(0); } while (0)
; template <int K, int LD = K>
; __device__ __forceinline__ void gemm_prefetch(const GAS bf16* A, const GAS bf16* Bt, int brow, int bcol) {
;   bf16* shm = (bf16*)smem_raw;
;   const int tid_ = otid();
;   unsigned so0, so1;
;   { int r_, c_; stage_rc(tid_ * 16, r_, c_); so0 = (unsigned)(r_ * LD + c_) * 2u; stage_rc(tid_ * 16 + 8192, r_, c_); so1 = (unsigned)(r_ * LD + c_) * 2u; }
; template <int K, int LD = K>
; __device__ __forceinline__ void gemm_main(const GAS bf16* A, const GAS bf16* Bt, int brow, int bcol, f32x4 (&acc)[2][2][4][2]) {
;     ...
;   { LDB(B0, 1, 0); LDA(At, 1, 0); WAIT_V(2); BAR; WAIT_L(0); MMA(0, 0, At, B0); BAR;
;     LDB(B1, 1, 1); WAIT_V(0); BAR; WAIT_L(0); MMA(0, 1, At, B1); BAR;
;     LDA(At, 1, 1); BAR; WAIT_L(0); MMA(1, 0, At, B0); MMA(1, 1, At, B1); BAR; }
;   if (wr == 0) BAR;
	ds_read_b128 v[198:201], v139
	ds_read_b128 v[202:205], v139 offset:1024
	ds_read_b128 v[206:209], v139 offset:2048
	ds_read_b128 v[210:213], v139 offset:3072
	s_waitcnt vmcnt(0)
	s_barrier
	s_waitcnt lgkmcnt(0)
	s_setprio 1
	s_waitcnt lgkmcnt(0)
	v_mfma_f32_16x16x32_bf16 v[94:97], v[198:201], v[26:29], v[94:97]
	v_mfma_f32_16x16x32_bf16 v[26:29], v[206:209], v[26:29], v[90:93]
	v_mfma_f32_16x16x32_bf16 v[122:125], v[210:213], v[30:33], v[26:29]
	v_mfma_f32_16x16x32_bf16 v[26:29], v[198:201], v[42:45], v[142:145]
	v_mfma_f32_16x16x32_bf16 v[110:113], v[202:205], v[46:49], v[26:29]
	v_mfma_f32_16x16x32_bf16 v[26:29], v[206:209], v[42:45], v[162:165]
	v_mfma_f32_16x16x32_bf16 v[106:109], v[210:213], v[46:49], v[26:29]
	v_mfma_f32_16x16x32_bf16 v[26:29], v[198:201], v[186:189], v[166:169]
	v_mfma_f32_16x16x32_bf16 v[126:129], v[202:205], v[30:33], v[94:97]
	v_mfma_f32_16x16x32_bf16 v[94:97], v[202:205], v[190:193], v[26:29]
	v_mfma_f32_16x16x32_bf16 v[26:29], v[206:209], v[186:189], v[174:177]
	v_mfma_f32_16x16x32_bf16 v[90:93], v[210:213], v[190:193], v[26:29]
	v_mfma_f32_16x16x32_bf16 v[26:29], v[198:201], v[218:221], v[70:73]
	v_mfma_f32_16x16x32_bf16 v[70:73], v[202:205], v[222:225], v[26:29]
	v_mfma_f32_16x16x32_bf16 v[26:29], v[206:209], v[218:221], v[66:69]
	v_mfma_f32_16x16x32_bf16 v[66:69], v[210:213], v[222:225], v[26:29]
	s_setprio 0
	s_barrier
	ds_read_b128 v[140:143], v138 offset:49152
	ds_read_b128 v[162:165], v138 offset:50176
	ds_read_b128 v[166:169], v137 offset:49152
	ds_read_b128 v[174:177], v137 offset:50176
	ds_read_b128 v[186:189], v136 offset:49152
	ds_read_b128 v[136:139], v136 offset:50176
	ds_read_b128 v[190:193], v135 offset:49152
	ds_read_b128 v[218:221], v135 offset:50176
	s_barrier
	s_waitcnt lgkmcnt(0)
	s_setprio 1
	s_waitcnt lgkmcnt(0)
	v_mfma_f32_16x16x32_bf16 v[26:29], v[2:5], v[140:143], v[62:65]
	v_mfma_f32_16x16x32_bf16 v[62:65], v[6:9], v[162:165], v[26:29]
	v_mfma_f32_16x16x32_bf16 v[26:29], v[178:181], v[140:143], v[58:61]
	v_mfma_f32_16x16x32_bf16 v[58:61], v[182:185], v[162:165], v[26:29]
	v_mfma_f32_16x16x32_bf16 v[26:29], v[2:5], v[166:169], v[54:57]
	v_mfma_f32_16x16x32_bf16 v[46:49], v[6:9], v[174:177], v[26:29]
	v_mfma_f32_16x16x32_bf16 v[26:29], v[178:181], v[166:169], v[50:53]
	v_mfma_f32_16x16x32_bf16 v[42:45], v[182:185], v[174:177], v[26:29]
	v_mfma_f32_16x16x32_bf16 v[26:29], v[2:5], v[186:189], v[194:197]
	v_mfma_f32_16x16x32_bf16 v[2:5], v[2:5], v[190:193], v[38:41]
	v_mfma_f32_16x16x32_bf16 v[30:33], v[6:9], v[136:139], v[26:29]
	v_mfma_f32_16x16x32_bf16 v[26:29], v[178:181], v[186:189], v[214:217]
	v_mfma_f32_16x16x32_bf16 v[6:9], v[6:9], v[218:221], v[2:5]
	v_mfma_f32_16x16x32_bf16 v[2:5], v[178:181], v[190:193], v[34:37]
	v_mfma_f32_16x16x32_bf16 v[26:29], v[182:185], v[136:139], v[26:29]
	v_mfma_f32_16x16x32_bf16 v[2:5], v[182:185], v[218:221], v[2:5]
	s_setprio 0
	s_setprio 1
	v_mfma_f32_16x16x32_bf16 v[34:37], v[198:201], v[140:143], v[146:149]
	v_mfma_f32_16x16x32_bf16 v[54:57], v[202:205], v[162:165], v[34:37]
	v_mfma_f32_16x16x32_bf16 v[34:37], v[206:209], v[140:143], v[150:153]
	v_mfma_f32_16x16x32_bf16 v[18:21], v[206:209], v[166:169], v[18:21]
	v_mfma_f32_16x16x32_bf16 v[10:13], v[206:209], v[186:189], v[10:13]
	v_mfma_f32_16x16x32_bf16 v[50:53], v[210:213], v[162:165], v[34:37]
	v_mfma_f32_16x16x32_bf16 v[22:25], v[198:201], v[166:169], v[22:25]
	v_mfma_f32_16x16x32_bf16 v[34:37], v[210:213], v[174:177], v[18:21]
	v_mfma_f32_16x16x32_bf16 v[14:17], v[198:201], v[186:189], v[14:17]
	v_mfma_f32_16x16x32_bf16 v[18:21], v[210:213], v[136:139], v[10:13]
	v_mfma_f32_16x16x32_bf16 v[10:13], v[198:201], v[190:193], v[154:157]
	v_mfma_f32_16x16x32_bf16 v[38:41], v[202:205], v[174:177], v[22:25]
	v_mfma_f32_16x16x32_bf16 v[22:25], v[202:205], v[136:139], v[14:17]
	v_mfma_f32_16x16x32_bf16 v[14:17], v[202:205], v[218:221], v[10:13]
	v_mfma_f32_16x16x32_bf16 v[10:13], v[206:209], v[190:193], v[158:161]
	v_mfma_f32_16x16x32_bf16 v[10:13], v[210:213], v[218:221], v[10:13]
	s_setprio 0
	v_cmp_gt_u32_e32 vcc, s51, v134
	s_barrier
	s_and_saveexec_b64 s[20:21], vcc
	s_cbranch_execz .LBB0_712
	s_barrier
.LBB0_712:
	s_or_b64 exec, exec, s[20:21]
	v_mov_b32_e32 v130, v170
	s_add_u32 s24, s39, s18
	v_ashrrev_i32_e32 v132, 31, v130
	v_lshrrev_b32_e32 v132, 26, v132
	v_lshlrev_b32_e32 v146, 4, v130
	v_add_u32_e32 v132, v130, v132
	v_bfe_i32 v130, v130, 27, 1
	v_lshrrev_b32_e32 v130, 22, v130
	v_add_u32_e32 v130, v146, v130
	v_and_b32_e32 v130, 0xfffffc00, v130
	v_sub_u32_e32 v130, v146, v130
	v_lshrrev_b32_e32 v133, 4, v130
	v_bitop3_b32 v133, v133, v130, 32 bitop3:0x6c
	v_ashrrev_i32_e32 v130, 31, v130
	v_lshrrev_b32_e32 v130, 26, v130
	v_add_u32_e32 v130, v133, v130
	v_ashrrev_i32_e32 v130, 6, v130
	v_ashrrev_i32_e32 v132, 6, v132
	v_mul_i32_i24_e32 v135, 64, v130
	v_lshlrev_b32_e32 v134, 3, v132
	v_lshlrev_b32_e32 v132, 5, v132
	v_sub_u32_e32 v133, v133, v135
	v_and_b32_e32 v134, 0x3ffff0, v134
	v_and_b32_e32 v132, 32, v132
	v_ashrrev_i16_sdwa v133, v1, sext(v133) dst_sel:DWORD dst_unused:UNUSED_PAD src0_sel:DWORD src1_sel:BYTE_0
	v_add_u32_sdwa v132, v132, sext(v133) dst_sel:DWORD dst_unused:UNUSED_PAD src0_sel:DWORD src1_sel:WORD_0
	v_add_lshl_u32 v130, v130, v134, 10
	v_lshl_add_u32 v130, v132, 1, v130
	v_add_u32_e32 v132, 0x2000, v146
	v_ashrrev_i32_e32 v133, 31, v132
	v_lshrrev_b32_e32 v133, 22, v133
	v_add_u32_e32 v133, v132, v133
	v_ashrrev_i32_e32 v133, 10, v133
	v_mul_i32_i24_e32 v134, 0x400, v133
	v_sub_u32_e32 v132, v132, v134
	v_lshrrev_b32_e32 v134, 4, v132
	v_bitop3_b32 v132, v134, v132, 32 bitop3:0x6c
	s_addc_u32 s25, s40, s19
	v_ashrrev_i32_e32 v135, 31, v132
; #define GAS __attribute__((address_space(1)))
; __device__ __forceinline__ int otid() { int t = threadIdx.x; asm volatile("" : "+v"(t)); return t; }
; #define STAGE(P, GP, ktrel) do { const GAS char* _g = (GP) + (ktrel) * (BK * 2); \
;     __builtin_amdgcn_global_load_lds((const GAS unsigned*)(_g + so0), (unsigned*)((char*)(P) + tid_ * 16), 16, 0, 0); \
;     __builtin_amdgcn_global_load_lds((const GAS unsigned*)(_g + so1), (unsigned*)((char*)(P) + tid_ * 16 + 8192), 16, 0, 0); } while (0)
; template <int K, int LD = K>
; __device__ __forceinline__ void gemm_prefetch(const GAS bf16* A, const GAS bf16* Bt, int brow, int bcol) {
;   bf16* shm = (bf16*)smem_raw;
;   const int tid_ = otid();
;   unsigned so0, so1;
;   { int r_, c_; stage_rc(tid_ * 16, r_, c_); so0 = (unsigned)(r_ * LD + c_) * 2u; stage_rc(tid_ * 16 + 8192, r_, c_); so1 = (unsigned)(r_ * LD + c_) * 2u; }
;   const GAS char* pA0 = (const GAS char*)A + (long)brow * LD * 2; const GAS char* pA1 = pA0 + (long)HALF * LD * 2;
;   const GAS char* pB0 = (const GAS char*)Bt + (long)bcol * LD * 2; const GAS char* pB1 = pB0 + (long)HALF * LD * 2;
;   asm volatile("" : "+s"(pA0), "+s"(pA1), "+s"(pB0), "+s"(pB1));
;   STAGE(SB(0, 0), pB0, 0); STAGE(SA(0, 0), pA0, 0);
;   STAGE(SB(0, 1), pB1, 0); STAGE(SA(0, 1), pA1, 0);
;   STAGE(SB(1, 0), pB0, 1); STAGE(SA(1, 0), pA0, 1); STAGE(SB(1, 1), pB1, 1);
; }
; __device__ __forceinline__ void phase_branch() {
;     ...
;       const GAS unsigned short* sg = (const GAS unsigned short*)(ws + OFF_SGF);
; #pragma unroll
;       for (int ai = 0; ai < 2; ++ai)
; #pragma unroll
;         for (int m = 0; m < 4; ++m) {
;           unsigned short gv[4][2][2];
; #pragma unroll
;           for (int j = 0; j < 4; ++j)
; #pragma unroll
;             for (int bj = 0; bj < 2; ++bj)
; #pragma unroll
;               for (int n = 0; n < 2; ++n)
;                 gv[j][bj][n] = sg[(size_t)(brow + ai * 128 + wr * 64 + m * 16 + fq * 4 + j) * DM + bcol + bj * 128 + wc * 32 + n * 16 + fr];
	s_add_u32 s20, s24, 0x20000
	v_lshrrev_b32_e32 v135, 26, v135
	s_addc_u32 s21, s25, 0
	v_add_u32_e32 v135, v132, v135
	s_add_u32 s26, s41, s22
	v_lshrrev_b32_e32 v136, 6, v135
	v_and_b32_e32 v135, 0xc0, v135
	s_addc_u32 s27, s42, s23
	v_lshlrev_b32_e32 v134, 3, v133
	v_lshlrev_b32_e32 v133, 5, v133
	v_sub_u32_e32 v132, v132, v135
	s_add_u32 s22, s26, 0x20000
	v_add_u32_e32 v138, s47, v146
	v_and_b32_e32 v134, 0x3ffff0, v134
	v_and_b32_e32 v133, 32, v133
	v_ashrrev_i16_sdwa v132, v1, sext(v132) dst_sel:DWORD dst_unused:UNUSED_PAD src0_sel:DWORD src1_sel:BYTE_0
	s_addc_u32 s23, s27, 0
	v_readfirstlane_b32 s17, v138
	v_add_u32_e32 v138, 0x2000, v138
	v_add_u32_sdwa v132, v133, sext(v132) dst_sel:DWORD dst_unused:UNUSED_PAD src0_sel:DWORD src1_sel:WORD_0
	v_add_lshl_u32 v133, v136, v134, 10
	s_mov_b64 s[18:19], s[22:23]
	s_mov_b64 s[28:29], s[24:25]
	s_mov_b64 s[30:31], s[26:27]
	s_mov_b64 s[44:45], s[20:21]
	s_mov_b32 m0, s17
	v_readfirstlane_b32 s17, v138
	v_add_u32_e32 v147, 0x100, v146
	v_lshl_add_u32 v132, v132, 1, v133
	v_add_u32_e32 v142, 0x2000, v147
	global_load_lds_dwordx4 v130, s[30:31]
	s_mov_b32 m0, s17
	v_readfirstlane_b32 s17, v147
	v_mov_b32_e32 v133, v131
	global_load_lds_dwordx4 v132, s[30:31]
	s_mov_b32 m0, s17
	v_readfirstlane_b32 s17, v142
	v_add_u32_e32 v148, s48, v146
	v_lshl_add_u64 v[136:137], s[30:31], 0, v[132:133]
	global_load_lds_dwordx4 v130, s[28:29]
	v_lshl_add_u64 v[140:141], s[28:29], 0, v[132:133]
	s_mov_b32 m0, s17
	v_readfirstlane_b32 s17, v148
	v_lshl_add_u64 v[144:145], s[18:19], 0, v[132:133]
	v_add_u32_e32 v133, 0x2000, v148
	global_load_lds_dwordx4 v132, s[28:29]
	s_mov_b32 m0, s17
	v_readfirstlane_b32 s17, v133
	v_add_u32_e32 v133, 0x4000, v147
	global_load_lds_dwordx4 v130, s[18:19]
	s_mov_b32 m0, s17
	v_readfirstlane_b32 s17, v133
	global_load_lds_dwordx4 v132, s[18:19]
	s_mov_b32 m0, s17
	v_lshl_add_u64 v[134:135], s[30:31], 0, v[130:131]
	v_lshl_add_u64 v[138:139], s[28:29], 0, v[130:131]
	v_lshl_add_u64 v[142:143], s[18:19], 0, v[130:131]
	global_load_lds_dwordx4 v130, s[44:45]
	v_add_u32_e32 v130, 0x6000, v147
	s_lshl_b64 s[18:19], s[14:15], 1
	v_readfirstlane_b32 s17, v130
	v_add_u32_e32 v130, s49, v146
	s_mov_b32 m0, s17
	v_readfirstlane_b32 s17, v130
	v_add_u32_e32 v130, 0x2000, v130
	global_load_lds_dwordx4 v132, s[44:45]
	v_lshl_add_u64 v[132:133], v[134:135], 0, s[6:7]
	s_mov_b32 m0, s17
	v_readfirstlane_b32 s17, v130
	v_add_u32_e32 v130, 0x8000, v147
	global_load_lds_dwordx4 v[132:133], off
	v_lshl_add_u64 v[132:133], v[136:137], 0, s[6:7]
	s_mov_b32 m0, s17
	v_readfirstlane_b32 s17, v130
	v_add_u32_e32 v130, 0xa000, v147
	global_load_lds_dwordx4 v[132:133], off
	v_lshl_add_u64 v[132:133], v[138:139], 0, s[6:7]
	s_mov_b32 m0, s17
	v_readfirstlane_b32 s17, v130
	v_add_u32_e32 v130, s50, v146
	global_load_lds_dwordx4 v[132:133], off
	v_lshl_add_u64 v[132:133], v[140:141], 0, s[6:7]
	s_mov_b32 m0, s17
	v_readfirstlane_b32 s17, v130
	v_add_u32_e32 v130, 0x2000, v130
	global_load_lds_dwordx4 v[132:133], off
	v_lshl_add_u64 v[132:133], v[142:143], 0, s[6:7]
	s_mov_b32 m0, s17
	v_readfirstlane_b32 s17, v130
	global_load_lds_dwordx4 v[132:133], off
	v_lshl_add_u64 v[132:133], v[144:145], 0, s[6:7]
	s_mov_b32 m0, s17
	v_mov_b32_e32 v130, v170
	global_load_lds_dwordx4 v[132:133], off
	v_and_b32_e32 v141, 15, v170
	v_lshrrev_b32_e32 v142, 8, v170
	v_lshl_or_b32 v141, v142, 6, v141
	v_add_u32_e32 v141, s16, v141
	v_bfe_u32 v142, v170, 4, 2
	v_bfe_u32 v143, v170, 6, 2
	v_lshlrev_b32_e32 v142, 3, v142
	v_lshl_or_b32 v142, v143, 6, v142
	v_lshl_add_u32 v140, v141, 11, v142
	s_add_u32 s28, s52, s18
	s_addc_u32 s29, s53, s19
	global_load_dwordx2 v[174:175], v140, s[28:29]
	global_load_dwordx2 v[176:177], v140, s[28:29] offset:32
	global_load_dwordx2 v[178:179], v140, s[28:29] offset:256
	global_load_dwordx2 v[180:181], v140, s[28:29] offset:288
	s_add_u32 s28, s28, 0x8000
	s_addc_u32 s29, s29, 0
	global_load_dwordx2 v[182:183], v140, s[28:29]
	global_load_dwordx2 v[184:185], v140, s[28:29] offset:32
	global_load_dwordx2 v[186:187], v140, s[28:29] offset:256
	global_load_dwordx2 v[188:189], v140, s[28:29] offset:288
	s_add_u32 s28, s28, 0x8000
	s_addc_u32 s29, s29, 0
	global_load_dwordx2 v[190:191], v140, s[28:29]
	global_load_dwordx2 v[192:193], v140, s[28:29] offset:32
	global_load_dwordx2 v[194:195], v140, s[28:29] offset:256
	global_load_dwordx2 v[196:197], v140, s[28:29] offset:288
	s_add_u32 s28, s28, 0x8000
	s_addc_u32 s29, s29, 0
	global_load_dwordx2 v[198:199], v140, s[28:29]
	global_load_dwordx2 v[200:201], v140, s[28:29] offset:32
	global_load_dwordx2 v[202:203], v140, s[28:29] offset:256
	global_load_dwordx2 v[204:205], v140, s[28:29] offset:288
	s_add_u32 s28, s28, 0x28000
	s_addc_u32 s29, s29, 0
	global_load_dwordx2 v[206:207], v140, s[28:29]
	global_load_dwordx2 v[208:209], v140, s[28:29] offset:32
	global_load_dwordx2 v[210:211], v140, s[28:29] offset:256
	global_load_dwordx2 v[212:213], v140, s[28:29] offset:288
	s_add_u32 s28, s28, 0x8000
	s_addc_u32 s29, s29, 0
	global_load_dwordx2 v[214:215], v140, s[28:29]
	global_load_dwordx2 v[216:217], v140, s[28:29] offset:32
	global_load_dwordx2 v[218:219], v140, s[28:29] offset:256
	global_load_dwordx2 v[220:221], v140, s[28:29] offset:288
	s_add_u32 s28, s28, 0x8000
	s_addc_u32 s29, s29, 0
	global_load_dwordx2 v[222:223], v140, s[28:29]
	global_load_dwordx2 v[224:225], v140, s[28:29] offset:32
	global_load_dwordx2 v[226:227], v140, s[28:29] offset:256
	global_load_dwordx2 v[228:229], v140, s[28:29] offset:288
	s_add_u32 s28, s28, 0x8000
	s_addc_u32 s29, s29, 0
	global_load_dwordx2 v[132:133], v140, s[28:29]
	global_load_dwordx2 v[134:135], v140, s[28:29] offset:32
	global_load_dwordx2 v[136:137], v140, s[28:29] offset:256
	global_load_dwordx2 v[138:139], v140, s[28:29] offset:288
	s_add_u32 s28, s4, s18
	s_addc_u32 s29, s5, s19
	s_waitcnt vmcnt(0)
; __device__ __forceinline__ unsigned f2bf(float f) { return pk2(f, f) & 0xffffu; }
; __device__ __forceinline__ void phase_branch() {
;     ...
; #pragma unroll
;           for (int j = 0; j < 4; ++j) {
;             const int row = brow + ai * 128 + wr * 64 + m * 16 + fq * 4 + j;
; #pragma unroll
;             for (int bj = 0; bj < 2; ++bj)
; #pragma unroll
;               for (int n = 0; n < 2; ++n) {
;                 const size_t idx = (size_t)row * DM + bcol + bj * 128 + wc * 32 + n * 16 + fr;
;                 tmpb[idx] = (unsigned short)f2bf(bf2f(gv[j][bj][n]) * acc[ai][bj][m][n][j]);
;               }
;           }
	v_lshlrev_b32_e32 v141, 16, v174
	v_and_b32_e32 v142, 0xffff0000, v174
	v_lshlrev_b32_e32 v143, 16, v175
	v_and_b32_e32 v144, 0xffff0000, v175
	v_mul_f32_e32 v118, v118, v141
	v_mul_f32_e32 v119, v119, v142
	v_mul_f32_e32 v120, v120, v143
	v_mul_f32_e32 v121, v121, v144
	v_cvt_pk_bf16_f32 v174, v118, v119
	v_cvt_pk_bf16_f32 v175, v120, v121
	global_store_dwordx2 v140, v[174:175], s[28:29]
	v_lshlrev_b32_e32 v141, 16, v176
	v_and_b32_e32 v142, 0xffff0000, v176
	v_lshlrev_b32_e32 v143, 16, v177
	v_and_b32_e32 v144, 0xffff0000, v177
	v_mul_f32_e32 v114, v114, v141
	v_mul_f32_e32 v115, v115, v142
	v_mul_f32_e32 v116, v116, v143
	v_mul_f32_e32 v117, v117, v144
	v_cvt_pk_bf16_f32 v176, v114, v115
	v_cvt_pk_bf16_f32 v177, v116, v117
	global_store_dwordx2 v140, v[176:177], s[28:29] offset:32
	v_lshlrev_b32_e32 v141, 16, v178
	v_and_b32_e32 v142, 0xffff0000, v178
	v_lshlrev_b32_e32 v143, 16, v179
	v_and_b32_e32 v144, 0xffff0000, v179
	v_mul_f32_e32 v126, v126, v141
	v_mul_f32_e32 v127, v127, v142
	v_mul_f32_e32 v128, v128, v143
	v_mul_f32_e32 v129, v129, v144
	v_cvt_pk_bf16_f32 v178, v126, v127
	v_cvt_pk_bf16_f32 v179, v128, v129
	global_store_dwordx2 v140, v[178:179], s[28:29] offset:256
	v_lshlrev_b32_e32 v141, 16, v180
	v_and_b32_e32 v142, 0xffff0000, v180
	v_lshlrev_b32_e32 v143, 16, v181
	v_and_b32_e32 v144, 0xffff0000, v181
	v_mul_f32_e32 v122, v122, v141
	v_mul_f32_e32 v123, v123, v142
	v_mul_f32_e32 v124, v124, v143
	v_mul_f32_e32 v125, v125, v144
	v_cvt_pk_bf16_f32 v180, v122, v123
	v_cvt_pk_bf16_f32 v181, v124, v125
	global_store_dwordx2 v140, v[180:181], s[28:29] offset:288
	s_add_u32 s28, s28, 0x8000
	s_addc_u32 s29, s29, 0
	v_lshlrev_b32_e32 v141, 16, v182
	v_and_b32_e32 v142, 0xffff0000, v182
	v_lshlrev_b32_e32 v143, 16, v183
	v_and_b32_e32 v144, 0xffff0000, v183
	v_mul_f32_e32 v102, v102, v141
	v_mul_f32_e32 v103, v103, v142
	v_mul_f32_e32 v104, v104, v143
	v_mul_f32_e32 v105, v105, v144
	v_cvt_pk_bf16_f32 v182, v102, v103
	v_cvt_pk_bf16_f32 v183, v104, v105
	global_store_dwordx2 v140, v[182:183], s[28:29]
	v_lshlrev_b32_e32 v141, 16, v184
	v_and_b32_e32 v142, 0xffff0000, v184
	v_lshlrev_b32_e32 v143, 16, v185
	v_and_b32_e32 v144, 0xffff0000, v185
	v_mul_f32_e32 v98, v98, v141
	v_mul_f32_e32 v99, v99, v142
	v_mul_f32_e32 v100, v100, v143
	v_mul_f32_e32 v101, v101, v144
	v_cvt_pk_bf16_f32 v184, v98, v99
	v_cvt_pk_bf16_f32 v185, v100, v101
	global_store_dwordx2 v140, v[184:185], s[28:29] offset:32
	v_lshlrev_b32_e32 v141, 16, v186
	v_and_b32_e32 v142, 0xffff0000, v186
	v_lshlrev_b32_e32 v143, 16, v187
	v_and_b32_e32 v144, 0xffff0000, v187
	v_mul_f32_e32 v110, v110, v141
	v_mul_f32_e32 v111, v111, v142
	v_mul_f32_e32 v112, v112, v143
	v_mul_f32_e32 v113, v113, v144
	v_cvt_pk_bf16_f32 v186, v110, v111
	v_cvt_pk_bf16_f32 v187, v112, v113
	global_store_dwordx2 v140, v[186:187], s[28:29] offset:256
	v_lshlrev_b32_e32 v141, 16, v188
	v_and_b32_e32 v142, 0xffff0000, v188
	v_lshlrev_b32_e32 v143, 16, v189
	v_and_b32_e32 v144, 0xffff0000, v189
	v_mul_f32_e32 v106, v106, v141
	v_mul_f32_e32 v107, v107, v142
	v_mul_f32_e32 v108, v108, v143
	v_mul_f32_e32 v109, v109, v144
	v_cvt_pk_bf16_f32 v188, v106, v107
	v_cvt_pk_bf16_f32 v189, v108, v109
	global_store_dwordx2 v140, v[188:189], s[28:29] offset:288
	s_add_u32 s28, s28, 0x8000
	s_addc_u32 s29, s29, 0
	v_lshlrev_b32_e32 v141, 16, v190
	v_and_b32_e32 v142, 0xffff0000, v190
	v_lshlrev_b32_e32 v143, 16, v191
	v_and_b32_e32 v144, 0xffff0000, v191
	v_mul_f32_e32 v86, v86, v141
	v_mul_f32_e32 v87, v87, v142
	v_mul_f32_e32 v88, v88, v143
	v_mul_f32_e32 v89, v89, v144
	v_cvt_pk_bf16_f32 v190, v86, v87
	v_cvt_pk_bf16_f32 v191, v88, v89
	global_store_dwordx2 v140, v[190:191], s[28:29]
	v_lshlrev_b32_e32 v141, 16, v192
	v_and_b32_e32 v142, 0xffff0000, v192
	v_lshlrev_b32_e32 v143, 16, v193
	v_and_b32_e32 v144, 0xffff0000, v193
	v_mul_f32_e32 v82, v82, v141
	v_mul_f32_e32 v83, v83, v142
	v_mul_f32_e32 v84, v84, v143
	v_mul_f32_e32 v85, v85, v144
	v_cvt_pk_bf16_f32 v192, v82, v83
	v_cvt_pk_bf16_f32 v193, v84, v85
	global_store_dwordx2 v140, v[192:193], s[28:29] offset:32
	v_lshlrev_b32_e32 v141, 16, v194
	v_and_b32_e32 v142, 0xffff0000, v194
	v_lshlrev_b32_e32 v143, 16, v195
	v_and_b32_e32 v144, 0xffff0000, v195
	v_mul_f32_e32 v94, v94, v141
	v_mul_f32_e32 v95, v95, v142
	v_mul_f32_e32 v96, v96, v143
	v_mul_f32_e32 v97, v97, v144
	v_cvt_pk_bf16_f32 v194, v94, v95
	v_cvt_pk_bf16_f32 v195, v96, v97
	global_store_dwordx2 v140, v[194:195], s[28:29] offset:256
	v_lshlrev_b32_e32 v141, 16, v196
	v_and_b32_e32 v142, 0xffff0000, v196
	v_lshlrev_b32_e32 v143, 16, v197
	v_and_b32_e32 v144, 0xffff0000, v197
	v_mul_f32_e32 v90, v90, v141
	v_mul_f32_e32 v91, v91, v142
	v_mul_f32_e32 v92, v92, v143
	v_mul_f32_e32 v93, v93, v144
	v_cvt_pk_bf16_f32 v196, v90, v91
	v_cvt_pk_bf16_f32 v197, v92, v93
	global_store_dwordx2 v140, v[196:197], s[28:29] offset:288
	s_add_u32 s28, s28, 0x8000
	s_addc_u32 s29, s29, 0
	v_lshlrev_b32_e32 v141, 16, v198
	v_and_b32_e32 v142, 0xffff0000, v198
	v_lshlrev_b32_e32 v143, 16, v199
	v_and_b32_e32 v144, 0xffff0000, v199
	v_mul_f32_e32 v78, v78, v141
	v_mul_f32_e32 v79, v79, v142
	v_mul_f32_e32 v80, v80, v143
	v_mul_f32_e32 v81, v81, v144
	v_cvt_pk_bf16_f32 v198, v78, v79
	v_cvt_pk_bf16_f32 v199, v80, v81
	global_store_dwordx2 v140, v[198:199], s[28:29]
	v_lshlrev_b32_e32 v141, 16, v200
	v_and_b32_e32 v142, 0xffff0000, v200
	v_lshlrev_b32_e32 v143, 16, v201
	v_and_b32_e32 v144, 0xffff0000, v201
	v_mul_f32_e32 v74, v74, v141
	v_mul_f32_e32 v75, v75, v142
	v_mul_f32_e32 v76, v76, v143
	v_mul_f32_e32 v77, v77, v144
	v_cvt_pk_bf16_f32 v200, v74, v75
	v_cvt_pk_bf16_f32 v201, v76, v77
; __device__ __forceinline__ unsigned f2bf(float f) { return pk2(f, f) & 0xffffu; }
; __device__ __forceinline__ void phase_branch() {
;     ...
; #pragma unroll
;           for (int j = 0; j < 4; ++j) {
;             const int row = brow + ai * 128 + wr * 64 + m * 16 + fq * 4 + j;
; #pragma unroll
;             for (int bj = 0; bj < 2; ++bj)
; #pragma unroll
;               for (int n = 0; n < 2; ++n) {
;                 const size_t idx = (size_t)row * DM + bcol + bj * 128 + wc * 32 + n * 16 + fr;
;                 tmpb[idx] = (unsigned short)f2bf(bf2f(gv[j][bj][n]) * acc[ai][bj][m][n][j]);
;               }
;           }
	global_store_dwordx2 v140, v[200:201], s[28:29] offset:32
	v_lshlrev_b32_e32 v141, 16, v202
	v_and_b32_e32 v142, 0xffff0000, v202
	v_lshlrev_b32_e32 v143, 16, v203
	v_and_b32_e32 v144, 0xffff0000, v203
	v_mul_f32_e32 v70, v70, v141
	v_mul_f32_e32 v71, v71, v142
	v_mul_f32_e32 v72, v72, v143
	v_mul_f32_e32 v73, v73, v144
	v_cvt_pk_bf16_f32 v202, v70, v71
	v_cvt_pk_bf16_f32 v203, v72, v73
	global_store_dwordx2 v140, v[202:203], s[28:29] offset:256
	v_lshlrev_b32_e32 v141, 16, v204
	v_and_b32_e32 v142, 0xffff0000, v204
	v_lshlrev_b32_e32 v143, 16, v205
	v_and_b32_e32 v144, 0xffff0000, v205
	v_mul_f32_e32 v66, v66, v141
	v_mul_f32_e32 v67, v67, v142
	v_mul_f32_e32 v68, v68, v143
	v_mul_f32_e32 v69, v69, v144
	v_cvt_pk_bf16_f32 v204, v66, v67
	v_cvt_pk_bf16_f32 v205, v68, v69
	global_store_dwordx2 v140, v[204:205], s[28:29] offset:288
	s_add_u32 s28, s28, 0x28000
	s_addc_u32 s29, s29, 0
	v_lshlrev_b32_e32 v141, 16, v206
	v_and_b32_e32 v142, 0xffff0000, v206
	v_lshlrev_b32_e32 v143, 16, v207
	v_and_b32_e32 v144, 0xffff0000, v207
	v_mul_f32_e32 v62, v62, v141
	v_mul_f32_e32 v63, v63, v142
	v_mul_f32_e32 v64, v64, v143
	v_mul_f32_e32 v65, v65, v144
	v_cvt_pk_bf16_f32 v206, v62, v63
	v_cvt_pk_bf16_f32 v207, v64, v65
	global_store_dwordx2 v140, v[206:207], s[28:29]
	v_lshlrev_b32_e32 v141, 16, v208
	v_and_b32_e32 v142, 0xffff0000, v208
	v_lshlrev_b32_e32 v143, 16, v209
	v_and_b32_e32 v144, 0xffff0000, v209
	v_mul_f32_e32 v58, v58, v141
	v_mul_f32_e32 v59, v59, v142
	v_mul_f32_e32 v60, v60, v143
	v_mul_f32_e32 v61, v61, v144
	v_cvt_pk_bf16_f32 v208, v58, v59
	v_cvt_pk_bf16_f32 v209, v60, v61
	global_store_dwordx2 v140, v[208:209], s[28:29] offset:32
	v_lshlrev_b32_e32 v141, 16, v210
	v_and_b32_e32 v142, 0xffff0000, v210
	v_lshlrev_b32_e32 v143, 16, v211
	v_and_b32_e32 v144, 0xffff0000, v211
	v_mul_f32_e32 v54, v54, v141
	v_mul_f32_e32 v55, v55, v142
	v_mul_f32_e32 v56, v56, v143
	v_mul_f32_e32 v57, v57, v144
	v_cvt_pk_bf16_f32 v210, v54, v55
	v_cvt_pk_bf16_f32 v211, v56, v57
	global_store_dwordx2 v140, v[210:211], s[28:29] offset:256
	v_lshlrev_b32_e32 v141, 16, v212
	v_and_b32_e32 v142, 0xffff0000, v212
	v_lshlrev_b32_e32 v143, 16, v213
	v_and_b32_e32 v144, 0xffff0000, v213
	v_mul_f32_e32 v50, v50, v141
	v_mul_f32_e32 v51, v51, v142
	v_mul_f32_e32 v52, v52, v143
	v_mul_f32_e32 v53, v53, v144
	v_cvt_pk_bf16_f32 v212, v50, v51
	v_cvt_pk_bf16_f32 v213, v52, v53
	global_store_dwordx2 v140, v[212:213], s[28:29] offset:288
	s_add_u32 s28, s28, 0x8000
	s_addc_u32 s29, s29, 0
	v_lshlrev_b32_e32 v141, 16, v214
	v_and_b32_e32 v142, 0xffff0000, v214
	v_lshlrev_b32_e32 v143, 16, v215
	v_and_b32_e32 v144, 0xffff0000, v215
	v_mul_f32_e32 v46, v46, v141
	v_mul_f32_e32 v47, v47, v142
	v_mul_f32_e32 v48, v48, v143
	v_mul_f32_e32 v49, v49, v144
	v_cvt_pk_bf16_f32 v214, v46, v47
	v_cvt_pk_bf16_f32 v215, v48, v49
	global_store_dwordx2 v140, v[214:215], s[28:29]
	v_lshlrev_b32_e32 v141, 16, v216
	v_and_b32_e32 v142, 0xffff0000, v216
	v_lshlrev_b32_e32 v143, 16, v217
	v_and_b32_e32 v144, 0xffff0000, v217
	v_mul_f32_e32 v42, v42, v141
	v_mul_f32_e32 v43, v43, v142
	v_mul_f32_e32 v44, v44, v143
	v_mul_f32_e32 v45, v45, v144
	v_cvt_pk_bf16_f32 v216, v42, v43
	v_cvt_pk_bf16_f32 v217, v44, v45
	global_store_dwordx2 v140, v[216:217], s[28:29] offset:32
	v_lshlrev_b32_e32 v141, 16, v218
	v_and_b32_e32 v142, 0xffff0000, v218
	v_lshlrev_b32_e32 v143, 16, v219
	v_and_b32_e32 v144, 0xffff0000, v219
	v_mul_f32_e32 v38, v38, v141
	v_mul_f32_e32 v39, v39, v142
	v_mul_f32_e32 v40, v40, v143
	v_mul_f32_e32 v41, v41, v144
	v_cvt_pk_bf16_f32 v218, v38, v39
	v_cvt_pk_bf16_f32 v219, v40, v41
	global_store_dwordx2 v140, v[218:219], s[28:29] offset:256
	v_lshlrev_b32_e32 v141, 16, v220
; __device__ __forceinline__ unsigned f2bf(float f) { return pk2(f, f) & 0xffffu; }
; #define BAR __builtin_amdgcn_s_barrier()
; template <int K, int LD = K>
; __device__ __forceinline__ void gemm_main(const GAS bf16* A, const GAS bf16* Bt, int brow, int bcol, f32x4 (&acc)[2][2][4][2]) {
;     ...
;   if (wr == 1) BAR;
; __device__ __forceinline__ void phase_branch() {
;     ...
;           for (int j = 0; j < 4; ++j) {
;             const int row = brow + ai * 128 + wr * 64 + m * 16 + fq * 4 + j;
; #pragma unroll
;             for (int bj = 0; bj < 2; ++bj)
; #pragma unroll
;               for (int n = 0; n < 2; ++n) {
;                 const size_t idx = (size_t)row * DM + bcol + bj * 128 + wc * 32 + n * 16 + fr;
;                 tmpb[idx] = (unsigned short)f2bf(bf2f(gv[j][bj][n]) * acc[ai][bj][m][n][j]);
;               }
;           }
	v_and_b32_e32 v142, 0xffff0000, v220
	v_lshlrev_b32_e32 v143, 16, v221
	v_and_b32_e32 v144, 0xffff0000, v221
	v_mul_f32_e32 v34, v34, v141
	v_mul_f32_e32 v35, v35, v142
	v_mul_f32_e32 v36, v36, v143
	v_mul_f32_e32 v37, v37, v144
	v_cvt_pk_bf16_f32 v220, v34, v35
	v_cvt_pk_bf16_f32 v221, v36, v37
	global_store_dwordx2 v140, v[220:221], s[28:29] offset:288
	s_add_u32 s28, s28, 0x8000
	s_addc_u32 s29, s29, 0
	v_lshlrev_b32_e32 v141, 16, v222
	v_and_b32_e32 v142, 0xffff0000, v222
	v_lshlrev_b32_e32 v143, 16, v223
	v_and_b32_e32 v144, 0xffff0000, v223
	v_mul_f32_e32 v30, v30, v141
	v_mul_f32_e32 v31, v31, v142
	v_mul_f32_e32 v32, v32, v143
	v_mul_f32_e32 v33, v33, v144
	v_cvt_pk_bf16_f32 v222, v30, v31
	v_cvt_pk_bf16_f32 v223, v32, v33
	global_store_dwordx2 v140, v[222:223], s[28:29]
	v_lshlrev_b32_e32 v141, 16, v224
	v_and_b32_e32 v142, 0xffff0000, v224
	v_lshlrev_b32_e32 v143, 16, v225
	v_and_b32_e32 v144, 0xffff0000, v225
	v_mul_f32_e32 v26, v26, v141
	v_mul_f32_e32 v27, v27, v142
	v_mul_f32_e32 v28, v28, v143
	v_mul_f32_e32 v29, v29, v144
	v_cvt_pk_bf16_f32 v224, v26, v27
	v_cvt_pk_bf16_f32 v225, v28, v29
	global_store_dwordx2 v140, v[224:225], s[28:29] offset:32
	v_lshlrev_b32_e32 v141, 16, v226
	v_and_b32_e32 v142, 0xffff0000, v226
	v_lshlrev_b32_e32 v143, 16, v227
	v_and_b32_e32 v144, 0xffff0000, v227
	v_mul_f32_e32 v22, v22, v141
	v_mul_f32_e32 v23, v23, v142
	v_mul_f32_e32 v24, v24, v143
	v_mul_f32_e32 v25, v25, v144
	v_cvt_pk_bf16_f32 v226, v22, v23
	v_cvt_pk_bf16_f32 v227, v24, v25
	global_store_dwordx2 v140, v[226:227], s[28:29] offset:256
	v_lshlrev_b32_e32 v141, 16, v228
	v_and_b32_e32 v142, 0xffff0000, v228
	v_lshlrev_b32_e32 v143, 16, v229
	v_and_b32_e32 v144, 0xffff0000, v229
	v_mul_f32_e32 v18, v18, v141
	v_mul_f32_e32 v19, v19, v142
	v_mul_f32_e32 v20, v20, v143
	v_mul_f32_e32 v21, v21, v144
	v_cvt_pk_bf16_f32 v228, v18, v19
	v_cvt_pk_bf16_f32 v229, v20, v21
	global_store_dwordx2 v140, v[228:229], s[28:29] offset:288
	s_add_u32 s28, s28, 0x8000
	s_addc_u32 s29, s29, 0
	v_lshlrev_b32_e32 v141, 16, v132
	v_and_b32_e32 v142, 0xffff0000, v132
	v_lshlrev_b32_e32 v143, 16, v133
	v_and_b32_e32 v144, 0xffff0000, v133
	v_mul_f32_e32 v6, v6, v141
	v_mul_f32_e32 v7, v7, v142
	v_mul_f32_e32 v8, v8, v143
	v_mul_f32_e32 v9, v9, v144
	v_cvt_pk_bf16_f32 v132, v6, v7
	v_cvt_pk_bf16_f32 v133, v8, v9
	global_store_dwordx2 v140, v[132:133], s[28:29]
	v_lshlrev_b32_e32 v141, 16, v134
	v_and_b32_e32 v142, 0xffff0000, v134
	v_lshlrev_b32_e32 v143, 16, v135
	v_and_b32_e32 v144, 0xffff0000, v135
	v_mul_f32_e32 v2, v2, v141
	v_mul_f32_e32 v3, v3, v142
	v_mul_f32_e32 v4, v4, v143
	v_mul_f32_e32 v5, v5, v144
	v_cvt_pk_bf16_f32 v134, v2, v3
	v_cvt_pk_bf16_f32 v135, v4, v5
	global_store_dwordx2 v140, v[134:135], s[28:29] offset:32
	v_lshlrev_b32_e32 v141, 16, v136
	v_and_b32_e32 v142, 0xffff0000, v136
	v_lshlrev_b32_e32 v143, 16, v137
	v_and_b32_e32 v144, 0xffff0000, v137
	v_mul_f32_e32 v14, v14, v141
	v_mul_f32_e32 v15, v15, v142
	v_mul_f32_e32 v16, v16, v143
	v_mul_f32_e32 v17, v17, v144
	v_cvt_pk_bf16_f32 v136, v14, v15
	v_cvt_pk_bf16_f32 v137, v16, v17
	global_store_dwordx2 v140, v[136:137], s[28:29] offset:256
	v_lshlrev_b32_e32 v141, 16, v138
	v_and_b32_e32 v142, 0xffff0000, v138
	v_lshlrev_b32_e32 v143, 16, v139
	v_and_b32_e32 v144, 0xffff0000, v139
	v_mul_f32_e32 v10, v10, v141
	v_mul_f32_e32 v11, v11, v142
	v_mul_f32_e32 v12, v12, v143
	v_mul_f32_e32 v13, v13, v144
	v_cvt_pk_bf16_f32 v138, v10, v11
	v_cvt_pk_bf16_f32 v139, v12, v13
	global_store_dwordx2 v140, v[138:139], s[28:29] offset:288
	v_mov_b32_e32 v134, v170
	s_nop 0
	v_ashrrev_i32_e32 v2, 8, v134
	v_cmp_eq_u32_e32 vcc, 1, v2
	s_and_saveexec_b64 s[28:29], vcc
	s_cbranch_execz .LBB0_714
	s_barrier

; __device__ __forceinline__ void phase_up(int pass) {
;     ...
;   int L = tile_first(), par = 0, pm, pn;
;   if (L < NT_) { tile_coords(L, nN, pm, pn); gemm_prefetch<DM>(A, Wgu, pm * 256, pn * 256); load_rr(ssq, pm * 256, 0); }
;   while (L < NT_) {
.LBB0_878:
	s_or_b64 exec, exec, s[12:13]
	s_add_u32 s35, s8, 0x5200000
	s_addc_u32 s36, s9, 0
	s_mov_b32 s37, 0
	s_movk_i32 s38, 0x3c0
	s_mov_b64 s[8:9], 0x100
	s_mov_b64 s[10:11], 0x180
	v_mov_b32_e32 v134, 0x358637bd
	s_mov_b32 s39, 0x800000
	s_movk_i32 s40, 0xb40
	s_waitcnt vmcnt(0)
	s_branch .LBB0_881

; #define GAS __attribute__((address_space(1)))
; __device__ __forceinline__ unsigned f2bf(float f) { return pk2(f, f) & 0xffffu; }
; __device__ __forceinline__ float sigmoidf_(float v) { return __builtin_amdgcn_rcpf(1.f + __builtin_amdgcn_exp2f(-LOG2E * v)); }
; __device__ __forceinline__ void phase_up(int pass) {
;     ...
;     EPI_IDS
;     const float* rr = (const float*)(smem_raw + LDS_RR) + par * 256;
;     GAS char* tb = (GAS char*)act + ((size_t)brow * FFP + (bcol >> 1)) * 2;
;     const unsigned off0 = (unsigned)((wr * 64 + fq * 4) * FFP + wc * 16 + fr) * 2u;
; #pragma unroll
;     for (int ai = 0; ai < 2; ++ai)
; #pragma unroll
;       for (int m = 0; m < 4; ++m)
; #pragma unroll
;         for (int j = 0; j < 4; ++j) {
;           const int rowl = ai * 128 + wr * 64 + m * 16 + fq * 4 + j;
;           const float r = rr[rowl];
; #pragma unroll
;           for (int bj = 0; bj < 2; ++bj) {
;             const float g = acc[ai][bj][m][0][j] * r, u = acc[ai][bj][m][1][j] * r;
;             const float v = g * sigmoidf_(g) * u;
;             *(GAS unsigned short*)(tb + (off0 + (unsigned)(((ai * 128 + m * 16 + j) * FFP + bj * 64) * 2))) = (unsigned short)f2bf(v);
;           }
;         }
;     par ^= 1;
.LBB0_880:
	v_and_b32_e32 v174, 15, v170
	v_lshrrev_b32_e32 v175, 8, v170
	v_lshl_or_b32 v175, v175, 6, v174
	v_bfe_u32 v176, v170, 4, 2
	v_bfe_u32 v177, v170, 6, 2
	v_lshlrev_b32_e32 v176, 2, v176
	v_lshl_or_b32 v176, v177, 4, v176
	v_mul_u32_u24_e32 v186, 0xb40, v175
	v_add_lshl_u32 v186, v186, v176, 1
	s_lshl_b32 s16, s37, 10
	s_add_i32 s16, s16, 0x20100
	v_lshl_add_u32 v174, v175, 2, s16
	ds_read_b32 v178, v174
	ds_read_b32 v179, v174 offset:64
	ds_read_b32 v180, v174 offset:128
	ds_read_b32 v181, v174 offset:192
	ds_read_b32 v182, v174 offset:512
	ds_read_b32 v183, v174 offset:576
	ds_read_b32 v184, v174 offset:640
	ds_read_b32 v185, v174 offset:704
	s_lshl_b32 s17, s41, 7
	s_mul_hi_i32 s15, s14, 0xb40
	s_mulk_i32 s14, 0xb40
	s_ashr_i32 s18, s17, 31
	s_add_u32 s14, s14, s17
	s_addc_u32 s15, s15, s18
	s_lshl_b64 s[14:15], s[14:15], 1
	s_add_u32 s14, s35, s14
	s_addc_u32 s15, s36, s15
	s_waitcnt lgkmcnt(0)
	v_mul_f32_e32 v118, v118, v178
	v_mul_f32_e32 v119, v119, v178
	v_mul_f32_e32 v120, v120, v178
	v_mul_f32_e32 v121, v121, v178
	v_mul_f32_e32 v174, 0xbfb8aa3b, v118
	v_mul_f32_e32 v175, 0xbfb8aa3b, v119
	v_mul_f32_e32 v176, 0xbfb8aa3b, v120
	v_mul_f32_e32 v177, 0xbfb8aa3b, v121
	v_exp_f32_e32 v174, v174
	v_exp_f32_e32 v175, v175
	v_exp_f32_e32 v176, v176
	v_exp_f32_e32 v177, v177
	v_mul_f32_e32 v114, v114, v178
	v_mul_f32_e32 v115, v115, v178
	v_mul_f32_e32 v116, v116, v178
	v_mul_f32_e32 v117, v117, v178
	v_add_f32_e32 v174, 1.0, v174
	v_add_f32_e32 v175, 1.0, v175
	v_add_f32_e32 v176, 1.0, v176
	v_add_f32_e32 v177, 1.0, v177
	v_rcp_f32_e32 v174, v174
	v_rcp_f32_e32 v175, v175
	v_rcp_f32_e32 v176, v176
	v_rcp_f32_e32 v177, v177
	v_mul_f32_e32 v118, v118, v174
	v_mul_f32_e32 v119, v119, v175
	v_mul_f32_e32 v120, v120, v176
	v_mul_f32_e32 v121, v121, v177
	v_mul_f32_e32 v114, v114, v118
	v_mul_f32_e32 v115, v115, v119
	v_mul_f32_e32 v116, v116, v120
	v_mul_f32_e32 v117, v117, v121
	v_cvt_pk_bf16_f32 v114, v114, v115
	v_cvt_pk_bf16_f32 v115, v116, v117
	global_store_dwordx2 v186, v[114:115], s[14:15]
	v_mul_f32_e32 v126, v126, v178
	v_mul_f32_e32 v127, v127, v178
	v_mul_f32_e32 v128, v128, v178
	v_mul_f32_e32 v129, v129, v178
	v_mul_f32_e32 v174, 0xbfb8aa3b, v126
	v_mul_f32_e32 v175, 0xbfb8aa3b, v127
	v_mul_f32_e32 v176, 0xbfb8aa3b, v128
	v_mul_f32_e32 v177, 0xbfb8aa3b, v129
	v_exp_f32_e32 v174, v174
	v_exp_f32_e32 v175, v175
	v_exp_f32_e32 v176, v176
	v_exp_f32_e32 v177, v177
	v_mul_f32_e32 v122, v122, v178
	v_mul_f32_e32 v123, v123, v178
	v_mul_f32_e32 v124, v124, v178
	v_mul_f32_e32 v125, v125, v178
	v_add_f32_e32 v174, 1.0, v174
	v_add_f32_e32 v175, 1.0, v175
	v_add_f32_e32 v176, 1.0, v176
	v_add_f32_e32 v177, 1.0, v177
	v_rcp_f32_e32 v174, v174
	v_rcp_f32_e32 v175, v175
	v_rcp_f32_e32 v176, v176
	v_rcp_f32_e32 v177, v177
	v_mul_f32_e32 v126, v126, v174
	v_mul_f32_e32 v127, v127, v175
	v_mul_f32_e32 v128, v128, v176
	v_mul_f32_e32 v129, v129, v177
	v_mul_f32_e32 v122, v122, v126
	v_mul_f32_e32 v123, v123, v127
	v_mul_f32_e32 v124, v124, v128
	v_mul_f32_e32 v125, v125, v129
	v_cvt_pk_bf16_f32 v122, v122, v123
	v_cvt_pk_bf16_f32 v123, v124, v125
	global_store_dwordx2 v186, v[122:123], s[14:15] offset:128
	s_add_u32 s14, s14, 0x16800
	s_addc_u32 s15, s15, 0
	v_mul_f32_e32 v102, v102, v179
	v_mul_f32_e32 v103, v103, v179
	v_mul_f32_e32 v104, v104, v179
	v_mul_f32_e32 v105, v105, v179
	v_mul_f32_e32 v174, 0xbfb8aa3b, v102
	v_mul_f32_e32 v175, 0xbfb8aa3b, v103
	v_mul_f32_e32 v176, 0xbfb8aa3b, v104
	v_mul_f32_e32 v177, 0xbfb8aa3b, v105
	v_exp_f32_e32 v174, v174
	v_exp_f32_e32 v175, v175
	v_exp_f32_e32 v176, v176
	v_exp_f32_e32 v177, v177
	v_mul_f32_e32 v98, v98, v179
	v_mul_f32_e32 v99, v99, v179
	v_mul_f32_e32 v100, v100, v179
	v_mul_f32_e32 v101, v101, v179
	v_add_f32_e32 v174, 1.0, v174
	v_add_f32_e32 v175, 1.0, v175
	v_add_f32_e32 v176, 1.0, v176
	v_add_f32_e32 v177, 1.0, v177
	v_rcp_f32_e32 v174, v174
	v_rcp_f32_e32 v175, v175
	v_rcp_f32_e32 v176, v176
	v_rcp_f32_e32 v177, v177
	v_mul_f32_e32 v102, v102, v174
	v_mul_f32_e32 v103, v103, v175
	v_mul_f32_e32 v104, v104, v176
	v_mul_f32_e32 v105, v105, v177
	v_mul_f32_e32 v98, v98, v102
	v_mul_f32_e32 v99, v99, v103
	v_mul_f32_e32 v100, v100, v104
	v_mul_f32_e32 v101, v101, v105
	v_cvt_pk_bf16_f32 v98, v98, v99
	v_cvt_pk_bf16_f32 v99, v100, v101
	global_store_dwordx2 v186, v[98:99], s[14:15]
	v_mul_f32_e32 v110, v110, v179
	v_mul_f32_e32 v111, v111, v179
	v_mul_f32_e32 v112, v112, v179
	v_mul_f32_e32 v113, v113, v179
	v_mul_f32_e32 v174, 0xbfb8aa3b, v110
	v_mul_f32_e32 v175, 0xbfb8aa3b, v111
	v_mul_f32_e32 v176, 0xbfb8aa3b, v112
	v_mul_f32_e32 v177, 0xbfb8aa3b, v113
	v_exp_f32_e32 v174, v174
	v_exp_f32_e32 v175, v175
	v_exp_f32_e32 v176, v176
	v_exp_f32_e32 v177, v177
	v_mul_f32_e32 v106, v106, v179
	v_mul_f32_e32 v107, v107, v179
	v_mul_f32_e32 v108, v108, v179
	v_mul_f32_e32 v109, v109, v179
	v_add_f32_e32 v174, 1.0, v174
	v_add_f32_e32 v175, 1.0, v175
	v_add_f32_e32 v176, 1.0, v176
	v_add_f32_e32 v177, 1.0, v177
	v_rcp_f32_e32 v174, v174
	v_rcp_f32_e32 v175, v175
	v_rcp_f32_e32 v176, v176
	v_rcp_f32_e32 v177, v177
	v_mul_f32_e32 v110, v110, v174
	v_mul_f32_e32 v111, v111, v175
	v_mul_f32_e32 v112, v112, v176
	v_mul_f32_e32 v113, v113, v177
	v_mul_f32_e32 v106, v106, v110
	v_mul_f32_e32 v107, v107, v111
	v_mul_f32_e32 v108, v108, v112
	v_mul_f32_e32 v109, v109, v113
	v_cvt_pk_bf16_f32 v106, v106, v107
	v_cvt_pk_bf16_f32 v107, v108, v109
	global_store_dwordx2 v186, v[106:107], s[14:15] offset:128
	s_add_u32 s14, s14, 0x16800
	s_addc_u32 s15, s15, 0
	v_mul_f32_e32 v86, v86, v180
	v_mul_f32_e32 v87, v87, v180
	v_mul_f32_e32 v88, v88, v180
	v_mul_f32_e32 v89, v89, v180
; #define GAS __attribute__((address_space(1)))
; __device__ __forceinline__ unsigned f2bf(float f) { return pk2(f, f) & 0xffffu; }
; __device__ __forceinline__ float sigmoidf_(float v) { return __builtin_amdgcn_rcpf(1.f + __builtin_amdgcn_exp2f(-LOG2E * v)); }
; __device__ __forceinline__ void phase_up(int pass) {
;     ...
;     EPI_IDS
;     const float* rr = (const float*)(smem_raw + LDS_RR) + par * 256;
;     GAS char* tb = (GAS char*)act + ((size_t)brow * FFP + (bcol >> 1)) * 2;
;     const unsigned off0 = (unsigned)((wr * 64 + fq * 4) * FFP + wc * 16 + fr) * 2u;
; #pragma unroll
;     for (int ai = 0; ai < 2; ++ai)
; #pragma unroll
;       for (int m = 0; m < 4; ++m)
; #pragma unroll
;         for (int j = 0; j < 4; ++j) {
;           const int rowl = ai * 128 + wr * 64 + m * 16 + fq * 4 + j;
;           const float r = rr[rowl];
; #pragma unroll
;           for (int bj = 0; bj < 2; ++bj) {
;             const float g = acc[ai][bj][m][0][j] * r, u = acc[ai][bj][m][1][j] * r;
;             const float v = g * sigmoidf_(g) * u;
;             *(GAS unsigned short*)(tb + (off0 + (unsigned)(((ai * 128 + m * 16 + j) * FFP + bj * 64) * 2))) = (unsigned short)f2bf(v);
;           }
;         }
;     par ^= 1;
	v_mul_f32_e32 v174, 0xbfb8aa3b, v86
	v_mul_f32_e32 v175, 0xbfb8aa3b, v87
	v_mul_f32_e32 v176, 0xbfb8aa3b, v88
	v_mul_f32_e32 v177, 0xbfb8aa3b, v89
	v_exp_f32_e32 v174, v174
	v_exp_f32_e32 v175, v175
	v_exp_f32_e32 v176, v176
	v_exp_f32_e32 v177, v177
	v_mul_f32_e32 v82, v82, v180
	v_mul_f32_e32 v83, v83, v180
	v_mul_f32_e32 v84, v84, v180
	v_mul_f32_e32 v85, v85, v180
	v_add_f32_e32 v174, 1.0, v174
	v_add_f32_e32 v175, 1.0, v175
	v_add_f32_e32 v176, 1.0, v176
	v_add_f32_e32 v177, 1.0, v177
	v_rcp_f32_e32 v174, v174
	v_rcp_f32_e32 v175, v175
	v_rcp_f32_e32 v176, v176
	v_rcp_f32_e32 v177, v177
	v_mul_f32_e32 v86, v86, v174
	v_mul_f32_e32 v87, v87, v175
	v_mul_f32_e32 v88, v88, v176
	v_mul_f32_e32 v89, v89, v177
	v_mul_f32_e32 v82, v82, v86
	v_mul_f32_e32 v83, v83, v87
	v_mul_f32_e32 v84, v84, v88
	v_mul_f32_e32 v85, v85, v89
	v_cvt_pk_bf16_f32 v82, v82, v83
	v_cvt_pk_bf16_f32 v83, v84, v85
	global_store_dwordx2 v186, v[82:83], s[14:15]
	v_mul_f32_e32 v94, v94, v180
	v_mul_f32_e32 v95, v95, v180
	v_mul_f32_e32 v96, v96, v180
	v_mul_f32_e32 v97, v97, v180
	v_mul_f32_e32 v174, 0xbfb8aa3b, v94
	v_mul_f32_e32 v175, 0xbfb8aa3b, v95
	v_mul_f32_e32 v176, 0xbfb8aa3b, v96
	v_mul_f32_e32 v177, 0xbfb8aa3b, v97
	v_exp_f32_e32 v174, v174
	v_exp_f32_e32 v175, v175
	v_exp_f32_e32 v176, v176
	v_exp_f32_e32 v177, v177
	v_mul_f32_e32 v90, v90, v180
	v_mul_f32_e32 v91, v91, v180
	v_mul_f32_e32 v92, v92, v180
	v_mul_f32_e32 v93, v93, v180
	v_add_f32_e32 v174, 1.0, v174
	v_add_f32_e32 v175, 1.0, v175
	v_add_f32_e32 v176, 1.0, v176
	v_add_f32_e32 v177, 1.0, v177
	v_rcp_f32_e32 v174, v174
	v_rcp_f32_e32 v175, v175
	v_rcp_f32_e32 v176, v176
	v_rcp_f32_e32 v177, v177
	v_mul_f32_e32 v94, v94, v174
	v_mul_f32_e32 v95, v95, v175
	v_mul_f32_e32 v96, v96, v176
	v_mul_f32_e32 v97, v97, v177
	v_mul_f32_e32 v90, v90, v94
	v_mul_f32_e32 v91, v91, v95
	v_mul_f32_e32 v92, v92, v96
	v_mul_f32_e32 v93, v93, v97
	v_cvt_pk_bf16_f32 v90, v90, v91
	v_cvt_pk_bf16_f32 v91, v92, v93
	global_store_dwordx2 v186, v[90:91], s[14:15] offset:128
	s_add_u32 s14, s14, 0x16800
	s_addc_u32 s15, s15, 0
	v_mul_f32_e32 v70, v70, v181
	v_mul_f32_e32 v71, v71, v181
	v_mul_f32_e32 v72, v72, v181
	v_mul_f32_e32 v73, v73, v181
	v_mul_f32_e32 v174, 0xbfb8aa3b, v70
	v_mul_f32_e32 v175, 0xbfb8aa3b, v71
	v_mul_f32_e32 v176, 0xbfb8aa3b, v72
	v_mul_f32_e32 v177, 0xbfb8aa3b, v73
	v_exp_f32_e32 v174, v174
	v_exp_f32_e32 v175, v175
	v_exp_f32_e32 v176, v176
	v_exp_f32_e32 v177, v177
	v_mul_f32_e32 v66, v66, v181
	v_mul_f32_e32 v67, v67, v181
	v_mul_f32_e32 v68, v68, v181
	v_mul_f32_e32 v69, v69, v181
	v_add_f32_e32 v174, 1.0, v174
	v_add_f32_e32 v175, 1.0, v175
	v_add_f32_e32 v176, 1.0, v176
	v_add_f32_e32 v177, 1.0, v177
	v_rcp_f32_e32 v174, v174
	v_rcp_f32_e32 v175, v175
	v_rcp_f32_e32 v176, v176
	v_rcp_f32_e32 v177, v177
	v_mul_f32_e32 v70, v70, v174
	v_mul_f32_e32 v71, v71, v175
	v_mul_f32_e32 v72, v72, v176
	v_mul_f32_e32 v73, v73, v177
	v_mul_f32_e32 v66, v66, v70
	v_mul_f32_e32 v67, v67, v71
	v_mul_f32_e32 v68, v68, v72
	v_mul_f32_e32 v69, v69, v73
	v_cvt_pk_bf16_f32 v66, v66, v67
	v_cvt_pk_bf16_f32 v67, v68, v69
	global_store_dwordx2 v186, v[66:67], s[14:15]
	v_mul_f32_e32 v78, v78, v181
	v_mul_f32_e32 v79, v79, v181
	v_mul_f32_e32 v80, v80, v181
	v_mul_f32_e32 v81, v81, v181
	v_mul_f32_e32 v174, 0xbfb8aa3b, v78
	v_mul_f32_e32 v175, 0xbfb8aa3b, v79
	v_mul_f32_e32 v176, 0xbfb8aa3b, v80
	v_mul_f32_e32 v177, 0xbfb8aa3b, v81
	v_exp_f32_e32 v174, v174
	v_exp_f32_e32 v175, v175
	v_exp_f32_e32 v176, v176
	v_exp_f32_e32 v177, v177
	v_mul_f32_e32 v74, v74, v181
	v_mul_f32_e32 v75, v75, v181
	v_mul_f32_e32 v76, v76, v181
	v_mul_f32_e32 v77, v77, v181
	v_add_f32_e32 v174, 1.0, v174
	v_add_f32_e32 v175, 1.0, v175
	v_add_f32_e32 v176, 1.0, v176
	v_add_f32_e32 v177, 1.0, v177
	v_rcp_f32_e32 v174, v174
	v_rcp_f32_e32 v175, v175
	v_rcp_f32_e32 v176, v176
	v_rcp_f32_e32 v177, v177
	v_mul_f32_e32 v78, v78, v174
	v_mul_f32_e32 v79, v79, v175
	v_mul_f32_e32 v80, v80, v176
	v_mul_f32_e32 v81, v81, v177
	v_mul_f32_e32 v74, v74, v78
	v_mul_f32_e32 v75, v75, v79
	v_mul_f32_e32 v76, v76, v80
	v_mul_f32_e32 v77, v77, v81
	v_cvt_pk_bf16_f32 v74, v74, v75
	v_cvt_pk_bf16_f32 v75, v76, v77
	global_store_dwordx2 v186, v[74:75], s[14:15] offset:128
	s_add_u32 s14, s14, 0x70800
	s_addc_u32 s15, s15, 0
	v_mul_f32_e32 v54, v54, v182
	v_mul_f32_e32 v55, v55, v182
	v_mul_f32_e32 v56, v56, v182
	v_mul_f32_e32 v57, v57, v182
	v_mul_f32_e32 v174, 0xbfb8aa3b, v54
	v_mul_f32_e32 v175, 0xbfb8aa3b, v55
	v_mul_f32_e32 v176, 0xbfb8aa3b, v56
	v_mul_f32_e32 v177, 0xbfb8aa3b, v57
	v_exp_f32_e32 v174, v174
	v_exp_f32_e32 v175, v175
	v_exp_f32_e32 v176, v176
	v_exp_f32_e32 v177, v177
	v_mul_f32_e32 v50, v50, v182
	v_mul_f32_e32 v51, v51, v182
	v_mul_f32_e32 v52, v52, v182
	v_mul_f32_e32 v53, v53, v182
	v_add_f32_e32 v174, 1.0, v174
	v_add_f32_e32 v175, 1.0, v175
	v_add_f32_e32 v176, 1.0, v176
	v_add_f32_e32 v177, 1.0, v177
	v_rcp_f32_e32 v174, v174
	v_rcp_f32_e32 v175, v175
	v_rcp_f32_e32 v176, v176
	v_rcp_f32_e32 v177, v177
	v_mul_f32_e32 v54, v54, v174
	v_mul_f32_e32 v55, v55, v175
	v_mul_f32_e32 v56, v56, v176
	v_mul_f32_e32 v57, v57, v177
	v_mul_f32_e32 v50, v50, v54
	v_mul_f32_e32 v51, v51, v55
	v_mul_f32_e32 v52, v52, v56
	v_mul_f32_e32 v53, v53, v57
	v_cvt_pk_bf16_f32 v50, v50, v51
	v_cvt_pk_bf16_f32 v51, v52, v53
	global_store_dwordx2 v186, v[50:51], s[14:15]
	v_mul_f32_e32 v62, v62, v182
	v_mul_f32_e32 v63, v63, v182
	v_mul_f32_e32 v64, v64, v182
	v_mul_f32_e32 v65, v65, v182
	v_mul_f32_e32 v174, 0xbfb8aa3b, v62
	v_mul_f32_e32 v175, 0xbfb8aa3b, v63
	v_mul_f32_e32 v176, 0xbfb8aa3b, v64
	v_mul_f32_e32 v177, 0xbfb8aa3b, v65
	v_exp_f32_e32 v174, v174
; #define GAS __attribute__((address_space(1)))
; __device__ __forceinline__ unsigned f2bf(float f) { return pk2(f, f) & 0xffffu; }
; __device__ __forceinline__ float sigmoidf_(float v) { return __builtin_amdgcn_rcpf(1.f + __builtin_amdgcn_exp2f(-LOG2E * v)); }
; __device__ __forceinline__ void phase_up(int pass) {
;     ...
;     EPI_IDS
;     const float* rr = (const float*)(smem_raw + LDS_RR) + par * 256;
;     GAS char* tb = (GAS char*)act + ((size_t)brow * FFP + (bcol >> 1)) * 2;
;     const unsigned off0 = (unsigned)((wr * 64 + fq * 4) * FFP + wc * 16 + fr) * 2u;
; #pragma unroll
;     for (int ai = 0; ai < 2; ++ai)
; #pragma unroll
;       for (int m = 0; m < 4; ++m)
; #pragma unroll
;         for (int j = 0; j < 4; ++j) {
;           const int rowl = ai * 128 + wr * 64 + m * 16 + fq * 4 + j;
;           const float r = rr[rowl];
; #pragma unroll
;           for (int bj = 0; bj < 2; ++bj) {
;             const float g = acc[ai][bj][m][0][j] * r, u = acc[ai][bj][m][1][j] * r;
;             const float v = g * sigmoidf_(g) * u;
;             *(GAS unsigned short*)(tb + (off0 + (unsigned)(((ai * 128 + m * 16 + j) * FFP + bj * 64) * 2))) = (unsigned short)f2bf(v);
;           }
;         }
;     par ^= 1;
	v_exp_f32_e32 v175, v175
	v_exp_f32_e32 v176, v176
	v_exp_f32_e32 v177, v177
	v_mul_f32_e32 v58, v58, v182
	v_mul_f32_e32 v59, v59, v182
	v_mul_f32_e32 v60, v60, v182
	v_mul_f32_e32 v61, v61, v182
	v_add_f32_e32 v174, 1.0, v174
	v_add_f32_e32 v175, 1.0, v175
	v_add_f32_e32 v176, 1.0, v176
	v_add_f32_e32 v177, 1.0, v177
	v_rcp_f32_e32 v174, v174
	v_rcp_f32_e32 v175, v175
	v_rcp_f32_e32 v176, v176
	v_rcp_f32_e32 v177, v177
	v_mul_f32_e32 v62, v62, v174
	v_mul_f32_e32 v63, v63, v175
	v_mul_f32_e32 v64, v64, v176
	v_mul_f32_e32 v65, v65, v177
	v_mul_f32_e32 v58, v58, v62
	v_mul_f32_e32 v59, v59, v63
	v_mul_f32_e32 v60, v60, v64
	v_mul_f32_e32 v61, v61, v65
	v_cvt_pk_bf16_f32 v58, v58, v59
	v_cvt_pk_bf16_f32 v59, v60, v61
	global_store_dwordx2 v186, v[58:59], s[14:15] offset:128
	s_add_u32 s14, s14, 0x16800
	s_addc_u32 s15, s15, 0
	v_mul_f32_e32 v42, v42, v183
	v_mul_f32_e32 v43, v43, v183
	v_mul_f32_e32 v44, v44, v183
	v_mul_f32_e32 v45, v45, v183
	v_mul_f32_e32 v174, 0xbfb8aa3b, v42
	v_mul_f32_e32 v175, 0xbfb8aa3b, v43
	v_mul_f32_e32 v176, 0xbfb8aa3b, v44
	v_mul_f32_e32 v177, 0xbfb8aa3b, v45
	v_exp_f32_e32 v174, v174
	v_exp_f32_e32 v175, v175
	v_exp_f32_e32 v176, v176
	v_exp_f32_e32 v177, v177
	v_mul_f32_e32 v34, v34, v183
	v_mul_f32_e32 v35, v35, v183
	v_mul_f32_e32 v36, v36, v183
	v_mul_f32_e32 v37, v37, v183
	v_add_f32_e32 v174, 1.0, v174
	v_add_f32_e32 v175, 1.0, v175
	v_add_f32_e32 v176, 1.0, v176
	v_add_f32_e32 v177, 1.0, v177
	v_rcp_f32_e32 v174, v174
	v_rcp_f32_e32 v175, v175
	v_rcp_f32_e32 v176, v176
	v_rcp_f32_e32 v177, v177
	v_mul_f32_e32 v42, v42, v174
	v_mul_f32_e32 v43, v43, v175
	v_mul_f32_e32 v44, v44, v176
	v_mul_f32_e32 v45, v45, v177
	v_mul_f32_e32 v34, v34, v42
	v_mul_f32_e32 v35, v35, v43
	v_mul_f32_e32 v36, v36, v44
	v_mul_f32_e32 v37, v37, v45
	v_cvt_pk_bf16_f32 v34, v34, v35
	v_cvt_pk_bf16_f32 v35, v36, v37
	global_store_dwordx2 v186, v[34:35], s[14:15]
	v_mul_f32_e32 v46, v46, v183
	v_mul_f32_e32 v47, v47, v183
	v_mul_f32_e32 v48, v48, v183
	v_mul_f32_e32 v49, v49, v183
	v_mul_f32_e32 v174, 0xbfb8aa3b, v46
	v_mul_f32_e32 v175, 0xbfb8aa3b, v47
	v_mul_f32_e32 v176, 0xbfb8aa3b, v48
	v_mul_f32_e32 v177, 0xbfb8aa3b, v49
	v_exp_f32_e32 v174, v174
	v_exp_f32_e32 v175, v175
	v_exp_f32_e32 v176, v176
	v_exp_f32_e32 v177, v177
	v_mul_f32_e32 v38, v38, v183
	v_mul_f32_e32 v39, v39, v183
	v_mul_f32_e32 v40, v40, v183
	v_mul_f32_e32 v41, v41, v183
	v_add_f32_e32 v174, 1.0, v174
	v_add_f32_e32 v175, 1.0, v175
	v_add_f32_e32 v176, 1.0, v176
	v_add_f32_e32 v177, 1.0, v177
	v_rcp_f32_e32 v174, v174
	v_rcp_f32_e32 v175, v175
	v_rcp_f32_e32 v176, v176
	v_rcp_f32_e32 v177, v177
	v_mul_f32_e32 v46, v46, v174
	v_mul_f32_e32 v47, v47, v175
	v_mul_f32_e32 v48, v48, v176
	v_mul_f32_e32 v49, v49, v177
	v_mul_f32_e32 v38, v38, v46
	v_mul_f32_e32 v39, v39, v47
	v_mul_f32_e32 v40, v40, v48
	v_mul_f32_e32 v41, v41, v49
	v_cvt_pk_bf16_f32 v38, v38, v39
	v_cvt_pk_bf16_f32 v39, v40, v41
	global_store_dwordx2 v186, v[38:39], s[14:15] offset:128
	s_add_u32 s14, s14, 0x16800
	s_addc_u32 s15, s15, 0
	v_mul_f32_e32 v22, v22, v184
	v_mul_f32_e32 v23, v23, v184
	v_mul_f32_e32 v24, v24, v184
	v_mul_f32_e32 v25, v25, v184
	v_mul_f32_e32 v174, 0xbfb8aa3b, v22
	v_mul_f32_e32 v175, 0xbfb8aa3b, v23
	v_mul_f32_e32 v176, 0xbfb8aa3b, v24
	v_mul_f32_e32 v177, 0xbfb8aa3b, v25
	v_exp_f32_e32 v174, v174
	v_exp_f32_e32 v175, v175
	v_exp_f32_e32 v176, v176
	v_exp_f32_e32 v177, v177
	v_mul_f32_e32 v18, v18, v184
	v_mul_f32_e32 v19, v19, v184
	v_mul_f32_e32 v20, v20, v184
	v_mul_f32_e32 v21, v21, v184
	v_add_f32_e32 v174, 1.0, v174
	v_add_f32_e32 v175, 1.0, v175
	v_add_f32_e32 v176, 1.0, v176
	v_add_f32_e32 v177, 1.0, v177
	v_rcp_f32_e32 v174, v174
	v_rcp_f32_e32 v175, v175
	v_rcp_f32_e32 v176, v176
	v_rcp_f32_e32 v177, v177
	v_mul_f32_e32 v22, v22, v174
	v_mul_f32_e32 v23, v23, v175
	v_mul_f32_e32 v24, v24, v176
	v_mul_f32_e32 v25, v25, v177
	v_mul_f32_e32 v18, v18, v22
	v_mul_f32_e32 v19, v19, v23
	v_mul_f32_e32 v20, v20, v24
	v_mul_f32_e32 v21, v21, v25
	v_cvt_pk_bf16_f32 v18, v18, v19
	v_cvt_pk_bf16_f32 v19, v20, v21
	global_store_dwordx2 v186, v[18:19], s[14:15]
	v_mul_f32_e32 v30, v30, v184
	v_mul_f32_e32 v31, v31, v184
	v_mul_f32_e32 v32, v32, v184
	v_mul_f32_e32 v33, v33, v184
	v_mul_f32_e32 v174, 0xbfb8aa3b, v30
	v_mul_f32_e32 v175, 0xbfb8aa3b, v31
	v_mul_f32_e32 v176, 0xbfb8aa3b, v32
	v_mul_f32_e32 v177, 0xbfb8aa3b, v33
; #define GAS __attribute__((address_space(1)))
; __device__ __forceinline__ int otid() { int t = threadIdx.x; asm volatile("" : "+v"(t)); return t; }
; __device__ __forceinline__ unsigned f2bf(float f) { return pk2(f, f) & 0xffffu; }
; __device__ __forceinline__ float sigmoidf_(float v) { return __builtin_amdgcn_rcpf(1.f + __builtin_amdgcn_exp2f(-LOG2E * v)); }
; __device__ __forceinline__ void load_rr(const GAS float* ssq, int brow, int par) {
;   float* rr = (float*)(smem_raw + LDS_RR) + par * 256;
;   const int tx = otid();
;   if (tx < 256) {
;     const GAS f32x4* s = (const GAS f32x4*)(ssq + (size_t)(brow + tx) * 16);
;     f32x4 a = s[0], b = s[1], c = s[2], d = s[3];
;     float t = ((a.x + a.y) + (a.z + a.w)) + ((b.x + b.y) + (b.z + b.w)) + ((c.x + c.y) + (c.z + c.w)) + ((d.x + d.y) + (d.z + d.w));
;     rr[tx] = rsqrtf(t * (1.f / DM) + EPS);
;   }
; __device__ __forceinline__ void phase_up(int pass) {
;     ...
;     EPI_IDS
;     const float* rr = (const float*)(smem_raw + LDS_RR) + par * 256;
;     GAS char* tb = (GAS char*)act + ((size_t)brow * FFP + (bcol >> 1)) * 2;
;     const unsigned off0 = (unsigned)((wr * 64 + fq * 4) * FFP + wc * 16 + fr) * 2u;
; #pragma unroll
;     for (int ai = 0; ai < 2; ++ai)
; #pragma unroll
;       for (int m = 0; m < 4; ++m)
; #pragma unroll
;         for (int j = 0; j < 4; ++j) {
;           const int rowl = ai * 128 + wr * 64 + m * 16 + fq * 4 + j;
;           const float r = rr[rowl];
; #pragma unroll
;           for (int bj = 0; bj < 2; ++bj) {
;             const float g = acc[ai][bj][m][0][j] * r, u = acc[ai][bj][m][1][j] * r;
;             const float v = g * sigmoidf_(g) * u;
;             *(GAS unsigned short*)(tb + (off0 + (unsigned)(((ai * 128 + m * 16 + j) * FFP + bj * 64) * 2))) = (unsigned short)f2bf(v);
;           }
;         }
;     par ^= 1;
	v_exp_f32_e32 v174, v174
	v_exp_f32_e32 v175, v175
	v_exp_f32_e32 v176, v176
	v_exp_f32_e32 v177, v177
	v_mul_f32_e32 v26, v26, v184
	v_mul_f32_e32 v27, v27, v184
	v_mul_f32_e32 v28, v28, v184
	v_mul_f32_e32 v29, v29, v184
	v_add_f32_e32 v174, 1.0, v174
	v_add_f32_e32 v175, 1.0, v175
	v_add_f32_e32 v176, 1.0, v176
	v_add_f32_e32 v177, 1.0, v177
	v_rcp_f32_e32 v174, v174
	v_rcp_f32_e32 v175, v175
	v_rcp_f32_e32 v176, v176
	v_rcp_f32_e32 v177, v177
	v_mul_f32_e32 v30, v30, v174
	v_mul_f32_e32 v31, v31, v175
	v_mul_f32_e32 v32, v32, v176
	v_mul_f32_e32 v33, v33, v177
	v_mul_f32_e32 v26, v26, v30
	v_mul_f32_e32 v27, v27, v31
	v_mul_f32_e32 v28, v28, v32
	v_mul_f32_e32 v29, v29, v33
	v_cvt_pk_bf16_f32 v26, v26, v27
	v_cvt_pk_bf16_f32 v27, v28, v29
	global_store_dwordx2 v186, v[26:27], s[14:15] offset:128
	s_add_u32 s14, s14, 0x16800
	s_addc_u32 s15, s15, 0
	v_mul_f32_e32 v10, v10, v185
	v_mul_f32_e32 v11, v11, v185
	v_mul_f32_e32 v12, v12, v185
	v_mul_f32_e32 v13, v13, v185
	v_mul_f32_e32 v174, 0xbfb8aa3b, v10
	v_mul_f32_e32 v175, 0xbfb8aa3b, v11
	v_mul_f32_e32 v176, 0xbfb8aa3b, v12
	v_mul_f32_e32 v177, 0xbfb8aa3b, v13
	v_exp_f32_e32 v174, v174
	v_exp_f32_e32 v175, v175
	v_exp_f32_e32 v176, v176
	v_exp_f32_e32 v177, v177
	v_mul_f32_e32 v2, v2, v185
	v_mul_f32_e32 v3, v3, v185
	v_mul_f32_e32 v4, v4, v185
	v_mul_f32_e32 v5, v5, v185
	v_add_f32_e32 v174, 1.0, v174
	v_add_f32_e32 v175, 1.0, v175
	v_add_f32_e32 v176, 1.0, v176
	v_add_f32_e32 v177, 1.0, v177
	v_rcp_f32_e32 v174, v174
	v_rcp_f32_e32 v175, v175
	v_rcp_f32_e32 v176, v176
	v_rcp_f32_e32 v177, v177
	v_mul_f32_e32 v10, v10, v174
	v_mul_f32_e32 v11, v11, v175
	v_mul_f32_e32 v12, v12, v176
	v_mul_f32_e32 v13, v13, v177
	v_mul_f32_e32 v2, v2, v10
	v_mul_f32_e32 v3, v3, v11
	v_mul_f32_e32 v4, v4, v12
	v_mul_f32_e32 v5, v5, v13
	v_cvt_pk_bf16_f32 v2, v2, v3
	v_cvt_pk_bf16_f32 v3, v4, v5
	global_store_dwordx2 v186, v[2:3], s[14:15]
	v_mul_f32_e32 v14, v14, v185
	v_mul_f32_e32 v15, v15, v185
	v_mul_f32_e32 v16, v16, v185
	v_mul_f32_e32 v17, v17, v185
	v_mul_f32_e32 v174, 0xbfb8aa3b, v14
	v_mul_f32_e32 v175, 0xbfb8aa3b, v15
	v_mul_f32_e32 v176, 0xbfb8aa3b, v16
	v_mul_f32_e32 v177, 0xbfb8aa3b, v17
	v_exp_f32_e32 v174, v174
	v_exp_f32_e32 v175, v175
	v_exp_f32_e32 v176, v176
	v_exp_f32_e32 v177, v177
	v_mul_f32_e32 v6, v6, v185
	v_mul_f32_e32 v7, v7, v185
	v_mul_f32_e32 v8, v8, v185
	v_mul_f32_e32 v9, v9, v185
	v_add_f32_e32 v174, 1.0, v174
	v_add_f32_e32 v175, 1.0, v175
	v_add_f32_e32 v176, 1.0, v176
	v_add_f32_e32 v177, 1.0, v177
	v_rcp_f32_e32 v174, v174
	v_rcp_f32_e32 v175, v175
	v_rcp_f32_e32 v176, v176
	v_rcp_f32_e32 v177, v177
	v_mul_f32_e32 v14, v14, v174
	v_mul_f32_e32 v15, v15, v175
	v_mul_f32_e32 v16, v16, v176
	v_mul_f32_e32 v17, v17, v177
	v_mul_f32_e32 v6, v6, v14
	v_mul_f32_e32 v7, v7, v15
	v_mul_f32_e32 v8, v8, v16
	v_mul_f32_e32 v9, v9, v17
	v_cvt_pk_bf16_f32 v6, v6, v7
	v_cvt_pk_bf16_f32 v7, v8, v9
	global_store_dwordx2 v186, v[6:7], s[14:15] offset:128
	s_and_b64 vcc, exec, s[12:13]
	s_cbranch_vccnz .Lup1_rr_skip
	v_cmp_gt_i32_e32 vcc, s34, v170
	s_and_saveexec_b64 s[18:19], vcc
	s_cbranch_execz .Lup1_rr_done
	s_lshl_b32 s15, s37, 10
	s_xor_b32 s15, s15, 0x400
	s_addk_i32 s15, 0x100
	v_lshl_add_u32 v130, v170, 2, s15
	v_add_u32_e32 v130, 0x20000, v130
	s_waitcnt vmcnt(16)
	v_mov_b32_e32 v132, v137
	v_mov_b32_e32 v133, v138
	v_mov_b32_e32 v137, v139
	v_mov_b32_e32 v138, v141
	v_mov_b32_e32 v139, v142
	v_mov_b32_e32 v141, v143
	v_pk_add_f32 v[132:133], v[132:133], v[136:137]
	v_pk_add_f32 v[136:137], v[138:139], v[140:141]
	v_pk_add_f32 v[132:133], v[132:133], v[132:133] op_sel:[0,1] op_sel_hi:[1,0]
	v_pk_add_f32 v[136:137], v[136:137], v[136:137] op_sel:[0,1] op_sel_hi:[1,0]
	v_add_f32_e32 v142, v144, v145
	v_add_f32_e32 v144, v146, v147
	v_mov_b32_e32 v143, v150
	v_mov_b32_e32 v145, v151
	v_mov_b32_e32 v133, v148
	v_mov_b32_e32 v137, v149
	v_pk_add_f32 v[138:139], v[142:143], v[144:145]
	v_pk_add_f32 v[132:133], v[132:133], v[136:137]
	s_nop 0
	v_pk_add_f32 v[132:133], v[132:133], v[138:139]
	s_nop 0
	v_add_f32_e32 v132, v132, v133
	v_fmamk_f32 v132, v132, 0x3a800000, v134
	v_mul_f32_e32 v133, 0x4b800000, v132
	v_cmp_gt_f32_e32 vcc, s39, v132
	s_nop 1
	v_cndmask_b32_e32 v132, v132, v133, vcc
	v_rsq_f32_e32 v132, v132
	s_nop 0
	v_mul_f32_e32 v133, 0x45800000, v132
	v_cndmask_b32_e32 v132, v132, v133, vcc
	ds_write_b32 v130, v132

; __device__ __forceinline__ void phase_up(int pass) {
;     ...
;     par ^= 1;
;   }
.Lup1_rr_skip:
	s_xor_b32 s37, s37, 1
	s_andn2_b64 vcc, exec, s[12:13]
	s_mov_b32 s41, s20
	s_cbranch_vccz .LBB0_890

; #define GAS __attribute__((address_space(1)))
; __device__ __forceinline__ int otid() { int t = threadIdx.x; asm volatile("" : "+v"(t)); return t; }
; #define WAIT_V(n) asm volatile("s_waitcnt vmcnt(" #n ")" ::: "memory")
; #define BAR __builtin_amdgcn_s_barrier()
; template <int K, int LD = K>
; __device__ __forceinline__ void gemm_main(const GAS bf16* A, const GAS bf16* Bt, int brow, int bcol, f32x4 (&acc)[2][2][4][2]) {
;   bf16* shm = (bf16*)smem_raw;
;   const int tid_ = otid();
;     ...
;   const int wid = tid_ >> 6, lane = tid_ & 63, wr = wid >> 2, wc = wid & 3, fr = lane & 15, fq = lane >> 4;
; #pragma unroll
;   for (int a = 0; a < 2; ++a)
; #pragma unroll
;     for (int b = 0; b < 2; ++b)
; #pragma unroll
;       for (int m = 0; m < 4; ++m)
; #pragma unroll
;         for (int n = 0; n < 2; ++n) acc[a][b][m][n] = f32x4{0.f, 0.f, 0.f, 0.f};
;   bf16x8 At[4][2], B0[2][2], B1[2][2];
;   unsigned so0, so1;
;   { int r_, c_; stage_rc(tid_ * 16, r_, c_); so0 = (unsigned)(r_ * LD + c_) * 2u; stage_rc(tid_ * 16 + 8192, r_, c_); so1 = (unsigned)(r_ * LD + c_) * 2u; }
;   const GAS char* pA0 = (const GAS char*)A + (long)brow * LD * 2; const GAS char* pA1 = pA0 + (long)HALF * LD * 2;
;   const GAS char* pB0 = (const GAS char*)Bt + (long)bcol * LD * 2; const GAS char* pB1 = pB0 + (long)HALF * LD * 2;
;   asm volatile("" : "+s"(pA0), "+s"(pA1), "+s"(pB0), "+s"(pB1));
;   constexpr int nt = K / BK;
;   static_assert(K % 128 == 0 && K >= 256, "K");
;   if (wr == 1) BAR;
;   WAIT_V(0); BAR;
;   BAR;
.LBB0_883:
	s_or_b64 exec, exec, s[22:23]
	v_bfe_i32 v7, v135, 27, 1
	v_lshlrev_b32_e32 v5, 4, v135
	v_lshrrev_b32_e32 v7, 22, v7
	v_add_u32_e32 v7, v5, v7
	v_and_b32_e32 v7, 0xfffffc00, v7
	v_sub_u32_e32 v7, v5, v7
	v_lshrrev_b32_e32 v8, 4, v7
	v_bitop3_b32 v8, v8, v7, 32 bitop3:0x6c
	v_ashrrev_i32_e32 v7, 31, v7
	v_ashrrev_i32_e32 v6, 31, v135
	v_lshrrev_b32_e32 v7, 26, v7
	v_lshrrev_b32_e32 v6, 26, v6
	v_add_u32_e32 v7, v8, v7
	v_add_u32_e32 v6, v135, v6
	v_ashrrev_i32_e32 v7, 6, v7
	v_ashrrev_i32_e32 v6, 6, v6
	v_mul_i32_i24_e32 v10, 64, v7
	v_lshlrev_b32_e32 v9, 3, v6
	v_lshlrev_b32_e32 v6, 5, v6
	v_sub_u32_e32 v8, v8, v10
	v_and_b32_e32 v9, 0x1ffff0, v9
	v_and_b32_e32 v6, 32, v6
	v_ashrrev_i16_sdwa v8, v1, sext(v8) dst_sel:DWORD dst_unused:UNUSED_PAD src0_sel:DWORD src1_sel:BYTE_0
	v_add_u32_sdwa v6, v6, sext(v8) dst_sel:DWORD dst_unused:UNUSED_PAD src0_sel:DWORD src1_sel:WORD_0
	v_add_lshl_u32 v7, v7, v9, 11
	v_lshl_add_u32 v130, v6, 1, v7
	v_add_u32_e32 v6, 0x2000, v5
	v_ashrrev_i32_e32 v7, 31, v6
	v_lshrrev_b32_e32 v7, 22, v7
	v_add_u32_e32 v7, v6, v7
	v_ashrrev_i32_e32 v7, 10, v7
	v_mul_i32_i24_e32 v8, 0x400, v7
	v_sub_u32_e32 v6, v6, v8
	v_lshrrev_b32_e32 v8, 4, v6
	v_bitop3_b32 v6, v8, v6, 32 bitop3:0x6c
	v_ashrrev_i32_e32 v9, 31, v6
	v_lshrrev_b32_e32 v9, 26, v9
	v_add_u32_e32 v9, v6, v9
	v_lshrrev_b32_e32 v10, 6, v9
	v_and_b32_e32 v9, 0xc0, v9
	v_lshlrev_b32_e32 v8, 3, v7
	v_lshlrev_b32_e32 v7, 5, v7
	v_sub_u32_e32 v6, v6, v9
	v_and_b32_e32 v8, 0x1ffff0, v8
	v_and_b32_e32 v7, 32, v7
	v_ashrrev_i16_sdwa v6, v1, sext(v6) dst_sel:DWORD dst_unused:UNUSED_PAD src0_sel:DWORD src1_sel:BYTE_0
	v_add_u32_sdwa v6, v7, sext(v6) dst_sel:DWORD dst_unused:UNUSED_PAD src0_sel:DWORD src1_sel:WORD_0
	v_add_lshl_u32 v7, v10, v8, 11
	v_and_b32_e32 v3, 15, v135
	v_lshl_add_u32 v132, v6, 1, v7
	v_lshlrev_b32_e32 v6, 2, v135
	v_and_b32_e32 v4, 48, v135
	v_lshlrev_b32_e32 v3, 6, v3
	v_and_b32_e32 v6, 32, v6
	v_lshlrev_b32_e32 v11, 6, v135
	s_waitcnt vmcnt(16)
	v_bitop3_b32 v3, v3, v6, v4 bitop3:0x36
	v_lshlrev_b32_e32 v13, 13, v2
	v_and_or_b32 v2, v11, s38, v4
	v_add_u32_e32 v7, s29, v3
	v_add_u32_e32 v8, s30, v3
	v_add_u32_e32 v9, s31, v3
	v_add_u32_e32 v10, s33, v3
	v_and_b32_e32 v12, 0x3000, v11
	v_add_u32_e32 v3, 0x100, v3
	v_xad_u32 v4, v2, v6, s34
	v_or_b32_e32 v6, 0x800, v13
	v_or_b32_e32 v11, 0x1000, v13
	v_or_b32_e32 v14, 0x1800, v13
	v_mov_b32_e32 v2, 0
	v_add_u32_e32 v146, 0x100, v5
	v_add_u32_e32 v152, s29, v5
	v_add_u32_e32 v154, s30, v5
	v_add_u32_e32 v156, s31, v5
	v_add_u32_e32 v158, s33, v5
	v_mov_b32_e32 v133, v131
	s_mov_b32 s15, -2
	v_add_u32_e32 v145, v7, v12
	v_add_u32_e32 v139, v3, v13
	v_add_u32_e32 v138, v4, v6
	v_add_u32_e32 v137, v4, v11
	v_add_u32_e32 v136, v4, v14
	v_add_u32_e32 v144, 0xc000, v146
	v_add_u32_e32 v143, 0xe000, v146
	v_add_u32_e32 v142, v8, v12
	v_add_u32_e32 v147, 0x2000, v146
	v_add_u32_e32 v141, v9, v12
	v_add_u32_e32 v148, 0x4000, v146
	v_add_u32_e32 v149, 0x6000, v146
	v_add_u32_e32 v140, v10, v12
	v_add_u32_e32 v150, 0x8000, v146
	v_add_u32_e32 v151, 0xa000, v146
	v_add_u32_e32 v153, 0x2000, v152
	v_add_u32_e32 v155, 0x2000, v154
	v_add_u32_e32 v157, 0x2000, v156
	v_add_u32_e32 v159, 0x2000, v158
	v_mov_b32_e32 v3, v2
	v_mov_b32_e32 v4, v2
	v_mov_b32_e32 v5, v2
	v_mov_b32_e32 v6, v2
	v_mov_b32_e32 v7, v2
	v_mov_b32_e32 v8, v2
	v_mov_b32_e32 v9, v2
	v_mov_b32_e32 v10, v2
	v_mov_b32_e32 v11, v2
	v_mov_b32_e32 v12, v2
	v_mov_b32_e32 v13, v2
	v_mov_b32_e32 v14, v2
	v_mov_b32_e32 v15, v2
	v_mov_b32_e32 v16, v2
	v_mov_b32_e32 v17, v2
	v_mov_b32_e32 v18, v2
	v_mov_b32_e32 v19, v2
	v_mov_b32_e32 v20, v2
	v_mov_b32_e32 v21, v2
	v_mov_b32_e32 v22, v2
	v_mov_b32_e32 v23, v2
	v_mov_b32_e32 v24, v2
	v_mov_b32_e32 v25, v2
	v_mov_b32_e32 v26, v2
	v_mov_b32_e32 v27, v2
	v_mov_b32_e32 v28, v2
	v_mov_b32_e32 v29, v2
	v_mov_b32_e32 v30, v2
	v_mov_b32_e32 v31, v2
	v_mov_b32_e32 v32, v2
	v_mov_b32_e32 v33, v2
	v_mov_b32_e32 v34, v2
	v_mov_b32_e32 v35, v2
	v_mov_b32_e32 v36, v2
	v_mov_b32_e32 v37, v2
	v_mov_b32_e32 v38, v2
	v_mov_b32_e32 v39, v2
	v_mov_b32_e32 v40, v2
	v_mov_b32_e32 v41, v2
	v_mov_b32_e32 v42, v2
	v_mov_b32_e32 v43, v2
	v_mov_b32_e32 v44, v2
	v_mov_b32_e32 v45, v2
	v_mov_b32_e32 v46, v2
	v_mov_b32_e32 v47, v2
	v_mov_b32_e32 v48, v2
	v_mov_b32_e32 v49, v2
	v_mov_b32_e32 v50, v2
	v_mov_b32_e32 v51, v2
	v_mov_b32_e32 v52, v2
	v_mov_b32_e32 v53, v2
	v_mov_b32_e32 v54, v2
	v_mov_b32_e32 v55, v2
	v_mov_b32_e32 v56, v2
	v_mov_b32_e32 v57, v2
	v_mov_b32_e32 v58, v2
	v_mov_b32_e32 v59, v2
	v_mov_b32_e32 v60, v2
	v_mov_b32_e32 v61, v2
	v_mov_b32_e32 v62, v2
	v_mov_b32_e32 v63, v2
	v_mov_b32_e32 v64, v2
	v_mov_b32_e32 v65, v2
	v_mov_b32_e32 v66, v2
	v_mov_b32_e32 v67, v2
	v_mov_b32_e32 v68, v2
	v_mov_b32_e32 v69, v2
	v_mov_b32_e32 v70, v2
	v_mov_b32_e32 v71, v2
	v_mov_b32_e32 v72, v2
	v_mov_b32_e32 v73, v2
	v_mov_b32_e32 v74, v2
	v_mov_b32_e32 v75, v2
	v_mov_b32_e32 v76, v2
	v_mov_b32_e32 v77, v2
	v_mov_b32_e32 v78, v2
	v_mov_b32_e32 v79, v2
	v_mov_b32_e32 v80, v2
	v_mov_b32_e32 v81, v2
	v_mov_b32_e32 v82, v2
	v_mov_b32_e32 v83, v2
	v_mov_b32_e32 v84, v2
	v_mov_b32_e32 v85, v2
	v_mov_b32_e32 v86, v2
	v_mov_b32_e32 v87, v2
	v_mov_b32_e32 v88, v2
	v_mov_b32_e32 v89, v2
	v_mov_b32_e32 v90, v2
	v_mov_b32_e32 v91, v2
	v_mov_b32_e32 v92, v2
	v_mov_b32_e32 v93, v2
	v_mov_b32_e32 v94, v2
	v_mov_b32_e32 v95, v2
	v_mov_b32_e32 v96, v2
	v_mov_b32_e32 v97, v2
	v_mov_b32_e32 v98, v2
	v_mov_b32_e32 v99, v2
	v_mov_b32_e32 v100, v2
	v_mov_b32_e32 v101, v2
	v_mov_b32_e32 v102, v2
	v_mov_b32_e32 v103, v2
	v_mov_b32_e32 v104, v2
	v_mov_b32_e32 v105, v2
	v_mov_b32_e32 v106, v2
	v_mov_b32_e32 v107, v2
	v_mov_b32_e32 v108, v2
	v_mov_b32_e32 v109, v2
	v_mov_b32_e32 v110, v2
	v_mov_b32_e32 v111, v2
	v_mov_b32_e32 v112, v2
	v_mov_b32_e32 v113, v2
	v_mov_b32_e32 v114, v2
	v_mov_b32_e32 v115, v2
	v_mov_b32_e32 v116, v2
	v_mov_b32_e32 v117, v2
	v_mov_b32_e32 v118, v2
	v_mov_b32_e32 v119, v2
	v_mov_b32_e32 v120, v2
	v_mov_b32_e32 v121, v2
	v_mov_b32_e32 v122, v2
	v_mov_b32_e32 v123, v2
	v_mov_b32_e32 v124, v2
	v_mov_b32_e32 v125, v2
	v_mov_b32_e32 v126, v2
	v_mov_b32_e32 v127, v2
	v_mov_b32_e32 v128, v2
	v_mov_b32_e32 v129, v2
	s_barrier
	s_barrier
; #define STAGE(P, GP, ktrel) do { const GAS char* _g = (GP) + (ktrel) * (BK * 2); \
;     __builtin_amdgcn_global_load_lds((const GAS unsigned*)(_g + so0), (unsigned*)((char*)(P) + tid_ * 16), 16, 0, 0); \
;     __builtin_amdgcn_global_load_lds((const GAS unsigned*)(_g + so1), (unsigned*)((char*)(P) + tid_ * 16 + 8192), 16, 0, 0); } while (0)
; #define WAIT_V(n) asm volatile("s_waitcnt vmcnt(" #n ")" ::: "memory")
; #define WAIT_L(n) asm volatile("s_waitcnt lgkmcnt(" #n ")" ::: "memory")
; #define BAR __builtin_amdgcn_s_barrier()
; #define SCHED __builtin_amdgcn_sched_barrier(0)
; #define LDA(dst, b, h) for (int m = 0; m < 4; ++m) for (int k = 0; k < 2; ++k) \
;     dst[m][k] = *reinterpret_cast<const bf16x8*>((char*)SA(b, h) + lds_byte(wr * 64 + m * 16 + fr, k * 32 + fq * 8))
; #define LDB(dst, b, h) for (int n = 0; n < 2; ++n) for (int k = 0; k < 2; ++k) \
;     dst[n][k] = *reinterpret_cast<const bf16x8*>((char*)SB(b, h) + lds_byte(wc * 32 + n * 16 + fr, k * 32 + fq * 8))
; template <int K, int LD = K>
; __device__ __forceinline__ void gemm_main(const GAS bf16* A, const GAS bf16* Bt, int brow, int bcol, f32x4 (&acc)[2][2][4][2]) {
;     ...
;   for (int t = 0; t < nt - 2; t += 2) {
;     LDB(B0, 0, 0); SCHED; LDA(At, 0, 0); STAGE(SA(1, 1), pA1, 1);
;     WAIT_L(8); BAR; WAIT_L(0); MMA(0, 0, At, B0); BAR; SCHED;
;     LDB(B1, 0, 1); STAGE(SB(0, 0), pB0, 2);
;     BAR; WAIT_L(0); MMA(0, 1, At, B1); BAR;
;     LDA(At, 0, 1); STAGE(SA(0, 0), pA0, 2);
;     BAR; WAIT_L(0); MMA(1, 0, At, B0); BAR; SCHED;
;     STAGE(SB(0, 1), pB1, 2);
;     WAIT_V(6); BAR; MMA(1, 1, At, B1); BAR;
;     LDB(B0, 1, 0); SCHED; LDA(At, 1, 0); STAGE(SA(0, 1), pA1, 2);
;     WAIT_L(8); BAR; WAIT_L(0); MMA(0, 0, At, B0); BAR; SCHED;
;     LDB(B1, 1, 1); STAGE(SB(1, 0), pB0, 3);
;     BAR; WAIT_L(0); MMA(0, 1, At, B1); BAR;
;     LDA(At, 1, 1); STAGE(SA(1, 0), pA0, 3);
;     BAR; WAIT_L(0); MMA(1, 0, At, B0); BAR; SCHED;
;     STAGE(SB(1, 1), pB1, 3);
;     WAIT_V(6); BAR; MMA(1, 1, At, B1); BAR;
;     pA0 += 4 * BK; pA1 += 4 * BK; pB0 += 4 * BK; pB1 += 4 * BK;
;     asm volatile("" : "+s"(pA0), "+s"(pA1), "+s"(pB0), "+s"(pB1));
;   }
.LBB0_884:
	ds_read_b128 v[160:163], v145
	ds_read_b128 v[164:167], v145 offset:1024
	ds_read_b128 v[174:177], v145 offset:2048
	ds_read_b128 v[178:181], v145 offset:3072
	v_lshl_add_u64 v[168:169], s[12:13], 0, v[130:131]
	v_readfirstlane_b32 s22, v144
	v_lshl_add_u64 v[214:215], v[168:169], 0, s[6:7]
	s_mov_b32 m0, s22
	v_lshl_add_u64 v[230:231], s[12:13], 0, v[132:133]
	v_readfirstlane_b32 s22, v143
	ds_read_b128 v[182:185], v139
	ds_read_b128 v[186:189], v139 offset:1024
	ds_read_b128 v[190:193], v138
	ds_read_b128 v[194:197], v138 offset:1024
	ds_read_b128 v[198:201], v137
	ds_read_b128 v[202:205], v137 offset:1024
	ds_read_b128 v[206:209], v136
	ds_read_b128 v[210:213], v136 offset:1024
	global_load_lds_dwordx4 v[214:215], off
	v_lshl_add_u64 v[214:215], v[230:231], 0, s[6:7]
	s_mov_b32 m0, s22
	s_nop 0
	global_load_lds_dwordx4 v[214:215], off
	s_waitcnt lgkmcnt(8)
	s_barrier
	s_waitcnt lgkmcnt(0)
	s_setprio 1
	s_waitcnt lgkmcnt(0)
	v_mfma_f32_16x16x32_bf16 v[126:129], v[160:163], v[182:185], v[126:129]
	v_mfma_f32_16x16x32_bf16 v[122:125], v[174:177], v[182:185], v[122:125]
	v_mfma_f32_16x16x32_bf16 v[118:121], v[160:163], v[190:193], v[118:121]
	v_mfma_f32_16x16x32_bf16 v[114:117], v[174:177], v[190:193], v[114:117]
	v_mfma_f32_16x16x32_bf16 v[110:113], v[160:163], v[198:201], v[110:113]
	v_mfma_f32_16x16x32_bf16 v[106:109], v[174:177], v[198:201], v[106:109]
	v_mfma_f32_16x16x32_bf16 v[102:105], v[160:163], v[206:209], v[102:105]
	v_mfma_f32_16x16x32_bf16 v[98:101], v[174:177], v[206:209], v[98:101]
	v_mfma_f32_16x16x32_bf16 v[126:129], v[164:167], v[186:189], v[126:129]
	v_mfma_f32_16x16x32_bf16 v[122:125], v[178:181], v[186:189], v[122:125]
	v_mfma_f32_16x16x32_bf16 v[118:121], v[164:167], v[194:197], v[118:121]
	v_mfma_f32_16x16x32_bf16 v[114:117], v[178:181], v[194:197], v[114:117]
	v_mfma_f32_16x16x32_bf16 v[110:113], v[164:167], v[202:205], v[110:113]
	v_mfma_f32_16x16x32_bf16 v[106:109], v[178:181], v[202:205], v[106:109]
	v_mfma_f32_16x16x32_bf16 v[102:105], v[164:167], v[210:213], v[102:105]
	v_mfma_f32_16x16x32_bf16 v[98:101], v[178:181], v[210:213], v[98:101]
	s_setprio 0
	s_barrier
	v_lshl_add_u64 v[232:233], s[20:21], 0, v[130:131]
	v_readfirstlane_b32 s22, v152
	v_lshl_add_u64 v[234:235], v[232:233], 0, s[8:9]
	s_mov_b32 m0, s22
	ds_read_b128 v[214:217], v142
	ds_read_b128 v[218:221], v142 offset:1024
	ds_read_b128 v[222:225], v142 offset:2048
	ds_read_b128 v[226:229], v142 offset:3072
	global_load_lds_dwordx4 v[234:235], off
	v_lshl_add_u64 v[234:235], s[20:21], 0, v[132:133]
	v_readfirstlane_b32 s22, v153
	v_lshl_add_u64 v[236:237], v[234:235], 0, s[8:9]
	s_mov_b32 m0, s22
	s_add_u32 s20, s20, 0x100
	global_load_lds_dwordx4 v[236:237], off
	s_barrier
	s_waitcnt lgkmcnt(0)
	s_addc_u32 s21, s21, 0
	s_setprio 1
	s_waitcnt lgkmcnt(0)
	v_mfma_f32_16x16x32_bf16 v[94:97], v[214:217], v[182:185], v[94:97]
	v_mfma_f32_16x16x32_bf16 v[90:93], v[222:225], v[182:185], v[90:93]
	v_mfma_f32_16x16x32_bf16 v[86:89], v[214:217], v[190:193], v[86:89]
	v_mfma_f32_16x16x32_bf16 v[82:85], v[222:225], v[190:193], v[82:85]
	v_mfma_f32_16x16x32_bf16 v[78:81], v[214:217], v[198:201], v[78:81]
	v_mfma_f32_16x16x32_bf16 v[74:77], v[222:225], v[198:201], v[74:77]
	v_mfma_f32_16x16x32_bf16 v[70:73], v[214:217], v[206:209], v[70:73]
	v_mfma_f32_16x16x32_bf16 v[66:69], v[222:225], v[206:209], v[66:69]
	v_mfma_f32_16x16x32_bf16 v[94:97], v[218:221], v[186:189], v[94:97]
	v_mfma_f32_16x16x32_bf16 v[90:93], v[226:229], v[186:189], v[90:93]
	v_mfma_f32_16x16x32_bf16 v[86:89], v[218:221], v[194:197], v[86:89]
	v_mfma_f32_16x16x32_bf16 v[82:85], v[226:229], v[194:197], v[82:85]
	v_mfma_f32_16x16x32_bf16 v[78:81], v[218:221], v[202:205], v[78:81]
	v_mfma_f32_16x16x32_bf16 v[74:77], v[226:229], v[202:205], v[74:77]
	v_mfma_f32_16x16x32_bf16 v[70:73], v[218:221], v[210:213], v[70:73]
	v_mfma_f32_16x16x32_bf16 v[66:69], v[226:229], v[210:213], v[66:69]
	s_setprio 0
	v_lshl_add_u64 v[236:237], s[18:19], 0, v[130:131]
	v_readfirstlane_b32 s22, v146
	v_lshl_add_u64 v[238:239], v[236:237], 0, s[8:9]
	s_mov_b32 m0, s22
	s_barrier
	ds_read_b128 v[182:185], v139 offset:16384
	ds_read_b128 v[186:189], v139 offset:17408
	ds_read_b128 v[190:193], v138 offset:16384
	ds_read_b128 v[194:197], v138 offset:17408
	ds_read_b128 v[198:201], v137 offset:16384
	ds_read_b128 v[202:205], v137 offset:17408
	ds_read_b128 v[206:209], v136 offset:16384
	ds_read_b128 v[210:213], v136 offset:17408
	global_load_lds_dwordx4 v[238:239], off
	v_lshl_add_u64 v[238:239], s[18:19], 0, v[132:133]
	v_readfirstlane_b32 s22, v147
	v_lshl_add_u64 v[240:241], v[238:239], 0, s[8:9]
	s_mov_b32 m0, s22
	s_add_u32 s18, s18, 0x100
	global_load_lds_dwordx4 v[240:241], off
	s_barrier
	s_waitcnt lgkmcnt(0)
	s_addc_u32 s19, s19, 0
	s_setprio 1
	s_waitcnt lgkmcnt(0)
	v_mfma_f32_16x16x32_bf16 v[62:65], v[160:163], v[182:185], v[62:65]
	v_mfma_f32_16x16x32_bf16 v[58:61], v[174:177], v[182:185], v[58:61]
	v_mfma_f32_16x16x32_bf16 v[54:57], v[160:163], v[190:193], v[54:57]
	v_mfma_f32_16x16x32_bf16 v[50:53], v[174:177], v[190:193], v[50:53]
	v_mfma_f32_16x16x32_bf16 v[46:49], v[160:163], v[198:201], v[46:49]
	v_mfma_f32_16x16x32_bf16 v[42:45], v[174:177], v[198:201], v[42:45]
	v_mfma_f32_16x16x32_bf16 v[38:41], v[160:163], v[206:209], v[38:41]
	v_mfma_f32_16x16x32_bf16 v[34:37], v[174:177], v[206:209], v[34:37]
	v_mfma_f32_16x16x32_bf16 v[62:65], v[164:167], v[186:189], v[62:65]
	v_mfma_f32_16x16x32_bf16 v[58:61], v[178:181], v[186:189], v[58:61]
	v_mfma_f32_16x16x32_bf16 v[54:57], v[164:167], v[194:197], v[54:57]
	v_mfma_f32_16x16x32_bf16 v[50:53], v[178:181], v[194:197], v[50:53]
	v_mfma_f32_16x16x32_bf16 v[46:49], v[164:167], v[202:205], v[46:49]
	v_mfma_f32_16x16x32_bf16 v[42:45], v[178:181], v[202:205], v[42:45]
	v_mfma_f32_16x16x32_bf16 v[38:41], v[164:167], v[210:213], v[38:41]
	v_mfma_f32_16x16x32_bf16 v[34:37], v[178:181], v[210:213], v[34:37]
	s_setprio 0
	s_barrier
; #define STAGE(P, GP, ktrel) do { const GAS char* _g = (GP) + (ktrel) * (BK * 2); \
;     __builtin_amdgcn_global_load_lds((const GAS unsigned*)(_g + so0), (unsigned*)((char*)(P) + tid_ * 16), 16, 0, 0); \
;     __builtin_amdgcn_global_load_lds((const GAS unsigned*)(_g + so1), (unsigned*)((char*)(P) + tid_ * 16 + 8192), 16, 0, 0); } while (0)
; #define WAIT_V(n) asm volatile("s_waitcnt vmcnt(" #n ")" ::: "memory")
; #define WAIT_L(n) asm volatile("s_waitcnt lgkmcnt(" #n ")" ::: "memory")
; #define BAR __builtin_amdgcn_s_barrier()
; #define SCHED __builtin_amdgcn_sched_barrier(0)
; #define LDA(dst, b, h) for (int m = 0; m < 4; ++m) for (int k = 0; k < 2; ++k) \
;     dst[m][k] = *reinterpret_cast<const bf16x8*>((char*)SA(b, h) + lds_byte(wr * 64 + m * 16 + fr, k * 32 + fq * 8))
; #define LDB(dst, b, h) for (int n = 0; n < 2; ++n) for (int k = 0; k < 2; ++k) \
;     dst[n][k] = *reinterpret_cast<const bf16x8*>((char*)SB(b, h) + lds_byte(wc * 32 + n * 16 + fr, k * 32 + fq * 8))
; template <int K, int LD = K>
; __device__ __forceinline__ void gemm_main(const GAS bf16* A, const GAS bf16* Bt, int brow, int bcol, f32x4 (&acc)[2][2][4][2]) {
;     ...
;   for (int t = 0; t < nt - 2; t += 2) {
;     LDB(B0, 0, 0); SCHED; LDA(At, 0, 0); STAGE(SA(1, 1), pA1, 1);
;     WAIT_L(8); BAR; WAIT_L(0); MMA(0, 0, At, B0); BAR; SCHED;
;     LDB(B1, 0, 1); STAGE(SB(0, 0), pB0, 2);
;     BAR; WAIT_L(0); MMA(0, 1, At, B1); BAR;
;     LDA(At, 0, 1); STAGE(SA(0, 0), pA0, 2);
;     BAR; WAIT_L(0); MMA(1, 0, At, B0); BAR; SCHED;
;     STAGE(SB(0, 1), pB1, 2);
;     WAIT_V(6); BAR; MMA(1, 1, At, B1); BAR;
;     LDB(B0, 1, 0); SCHED; LDA(At, 1, 0); STAGE(SA(0, 1), pA1, 2);
;     WAIT_L(8); BAR; WAIT_L(0); MMA(0, 0, At, B0); BAR; SCHED;
;     LDB(B1, 1, 1); STAGE(SB(1, 0), pB0, 3);
;     BAR; WAIT_L(0); MMA(0, 1, At, B1); BAR;
;     LDA(At, 1, 1); STAGE(SA(1, 0), pA0, 3);
;     BAR; WAIT_L(0); MMA(1, 0, At, B0); BAR; SCHED;
;     STAGE(SB(1, 1), pB1, 3);
;     WAIT_V(6); BAR; MMA(1, 1, At, B1); BAR;
;     pA0 += 4 * BK; pA1 += 4 * BK; pB0 += 4 * BK; pB1 += 4 * BK;
;     asm volatile("" : "+s"(pA0), "+s"(pA1), "+s"(pB0), "+s"(pB1));
;   }
	v_lshl_add_u64 v[240:241], s[16:17], 0, v[130:131]
	v_readfirstlane_b32 s22, v154
	v_lshl_add_u64 v[160:161], v[240:241], 0, s[8:9]
	s_mov_b32 m0, s22
	v_lshl_add_u64 v[242:243], s[16:17], 0, v[132:133]
	v_readfirstlane_b32 s22, v155
	global_load_lds_dwordx4 v[160:161], off
	v_lshl_add_u64 v[160:161], v[242:243], 0, s[8:9]
	s_mov_b32 m0, s22
	s_add_u32 s16, s16, 0x100
	global_load_lds_dwordx4 v[160:161], off
	s_waitcnt vmcnt(6)
	s_addc_u32 s17, s17, 0
	s_barrier
	s_setprio 1
	v_mfma_f32_16x16x32_bf16 v[30:33], v[214:217], v[182:185], v[30:33]
	v_mfma_f32_16x16x32_bf16 v[26:29], v[222:225], v[182:185], v[26:29]
	v_mfma_f32_16x16x32_bf16 v[22:25], v[214:217], v[190:193], v[22:25]
	v_mfma_f32_16x16x32_bf16 v[18:21], v[222:225], v[190:193], v[18:21]
	v_mfma_f32_16x16x32_bf16 v[14:17], v[214:217], v[198:201], v[14:17]
	v_mfma_f32_16x16x32_bf16 v[10:13], v[222:225], v[198:201], v[10:13]
	v_mfma_f32_16x16x32_bf16 v[6:9], v[214:217], v[206:209], v[6:9]
	v_mfma_f32_16x16x32_bf16 v[2:5], v[222:225], v[206:209], v[2:5]
	v_mfma_f32_16x16x32_bf16 v[30:33], v[218:221], v[186:189], v[30:33]
	v_mfma_f32_16x16x32_bf16 v[26:29], v[226:229], v[186:189], v[26:29]
	v_mfma_f32_16x16x32_bf16 v[22:25], v[218:221], v[194:197], v[22:25]
	v_mfma_f32_16x16x32_bf16 v[18:21], v[226:229], v[194:197], v[18:21]
	v_mfma_f32_16x16x32_bf16 v[14:17], v[218:221], v[202:205], v[14:17]
	v_mfma_f32_16x16x32_bf16 v[10:13], v[226:229], v[202:205], v[10:13]
	v_mfma_f32_16x16x32_bf16 v[6:9], v[218:221], v[210:213], v[6:9]
	v_mfma_f32_16x16x32_bf16 v[2:5], v[226:229], v[210:213], v[2:5]
	s_setprio 0
	s_barrier
	ds_read_b128 v[160:163], v141
	ds_read_b128 v[164:167], v141 offset:1024
	ds_read_b128 v[174:177], v141 offset:2048
	ds_read_b128 v[178:181], v141 offset:3072
	v_readfirstlane_b32 s22, v148
	v_lshl_add_u64 v[168:169], v[168:169], 0, s[8:9]
	s_mov_b32 m0, s22
	v_readfirstlane_b32 s22, v149
	ds_read_b128 v[182:185], v139 offset:32768
	ds_read_b128 v[186:189], v139 offset:33792
	ds_read_b128 v[190:193], v138 offset:32768
	ds_read_b128 v[194:197], v138 offset:33792
	ds_read_b128 v[198:201], v137 offset:32768
	ds_read_b128 v[202:205], v137 offset:33792
	ds_read_b128 v[206:209], v136 offset:32768
	ds_read_b128 v[210:213], v136 offset:33792
	global_load_lds_dwordx4 v[168:169], off
	v_lshl_add_u64 v[168:169], v[230:231], 0, s[8:9]
	s_mov_b32 m0, s22
	s_add_u32 s12, s12, 0x100
	global_load_lds_dwordx4 v[168:169], off
	s_waitcnt lgkmcnt(8)
	s_barrier
	s_waitcnt lgkmcnt(0)
	s_addc_u32 s13, s13, 0
	s_setprio 1
	s_waitcnt lgkmcnt(0)
	v_mfma_f32_16x16x32_bf16 v[126:129], v[160:163], v[182:185], v[126:129]
	v_mfma_f32_16x16x32_bf16 v[122:125], v[174:177], v[182:185], v[122:125]
	v_mfma_f32_16x16x32_bf16 v[118:121], v[160:163], v[190:193], v[118:121]
	v_mfma_f32_16x16x32_bf16 v[114:117], v[174:177], v[190:193], v[114:117]
	v_mfma_f32_16x16x32_bf16 v[110:113], v[160:163], v[198:201], v[110:113]
	v_mfma_f32_16x16x32_bf16 v[106:109], v[174:177], v[198:201], v[106:109]
	v_mfma_f32_16x16x32_bf16 v[102:105], v[160:163], v[206:209], v[102:105]
	v_mfma_f32_16x16x32_bf16 v[98:101], v[174:177], v[206:209], v[98:101]
	v_mfma_f32_16x16x32_bf16 v[126:129], v[164:167], v[186:189], v[126:129]
	v_mfma_f32_16x16x32_bf16 v[122:125], v[178:181], v[186:189], v[122:125]
	v_mfma_f32_16x16x32_bf16 v[118:121], v[164:167], v[194:197], v[118:121]
	v_mfma_f32_16x16x32_bf16 v[114:117], v[178:181], v[194:197], v[114:117]
	v_mfma_f32_16x16x32_bf16 v[110:113], v[164:167], v[202:205], v[110:113]
	v_mfma_f32_16x16x32_bf16 v[106:109], v[178:181], v[202:205], v[106:109]
	v_mfma_f32_16x16x32_bf16 v[102:105], v[164:167], v[210:213], v[102:105]
	v_mfma_f32_16x16x32_bf16 v[98:101], v[178:181], v[210:213], v[98:101]
	s_setprio 0
	s_barrier
	v_readfirstlane_b32 s22, v156
	v_lshl_add_u64 v[168:169], v[232:233], 0, s[10:11]
	s_mov_b32 m0, s22
	v_readfirstlane_b32 s22, v157
	ds_read_b128 v[214:217], v140
	ds_read_b128 v[218:221], v140 offset:1024
	ds_read_b128 v[222:225], v140 offset:2048
	ds_read_b128 v[226:229], v140 offset:3072
	global_load_lds_dwordx4 v[168:169], off
	v_lshl_add_u64 v[168:169], v[234:235], 0, s[10:11]
	s_mov_b32 m0, s22
	s_nop 0
	global_load_lds_dwordx4 v[168:169], off
	s_barrier
	s_waitcnt lgkmcnt(0)
	s_setprio 1
	s_waitcnt lgkmcnt(0)
	v_mfma_f32_16x16x32_bf16 v[94:97], v[214:217], v[182:185], v[94:97]
	v_mfma_f32_16x16x32_bf16 v[90:93], v[222:225], v[182:185], v[90:93]
	v_mfma_f32_16x16x32_bf16 v[86:89], v[214:217], v[190:193], v[86:89]
	v_mfma_f32_16x16x32_bf16 v[82:85], v[222:225], v[190:193], v[82:85]
	v_mfma_f32_16x16x32_bf16 v[78:81], v[214:217], v[198:201], v[78:81]
	v_mfma_f32_16x16x32_bf16 v[74:77], v[222:225], v[198:201], v[74:77]
	v_mfma_f32_16x16x32_bf16 v[70:73], v[214:217], v[206:209], v[70:73]
	v_mfma_f32_16x16x32_bf16 v[66:69], v[222:225], v[206:209], v[66:69]
	v_mfma_f32_16x16x32_bf16 v[94:97], v[218:221], v[186:189], v[94:97]
	v_mfma_f32_16x16x32_bf16 v[90:93], v[226:229], v[186:189], v[90:93]
	v_mfma_f32_16x16x32_bf16 v[86:89], v[218:221], v[194:197], v[86:89]
	v_mfma_f32_16x16x32_bf16 v[82:85], v[226:229], v[194:197], v[82:85]
	v_mfma_f32_16x16x32_bf16 v[78:81], v[218:221], v[202:205], v[78:81]
	v_mfma_f32_16x16x32_bf16 v[74:77], v[226:229], v[202:205], v[74:77]
	v_mfma_f32_16x16x32_bf16 v[70:73], v[218:221], v[210:213], v[70:73]
	v_mfma_f32_16x16x32_bf16 v[66:69], v[226:229], v[210:213], v[66:69]
	s_setprio 0
	v_readfirstlane_b32 s22, v150
	v_lshl_add_u64 v[168:169], v[236:237], 0, s[10:11]
	s_mov_b32 m0, s22
	v_readfirstlane_b32 s22, v151
	s_barrier
; #define STAGE(P, GP, ktrel) do { const GAS char* _g = (GP) + (ktrel) * (BK * 2); \
;     __builtin_amdgcn_global_load_lds((const GAS unsigned*)(_g + so0), (unsigned*)((char*)(P) + tid_ * 16), 16, 0, 0); \
;     __builtin_amdgcn_global_load_lds((const GAS unsigned*)(_g + so1), (unsigned*)((char*)(P) + tid_ * 16 + 8192), 16, 0, 0); } while (0)
; #define WAIT_V(n) asm volatile("s_waitcnt vmcnt(" #n ")" ::: "memory")
; #define WAIT_L(n) asm volatile("s_waitcnt lgkmcnt(" #n ")" ::: "memory")
; #define BAR __builtin_amdgcn_s_barrier()
; #define SCHED __builtin_amdgcn_sched_barrier(0)
; #define LDA(dst, b, h) for (int m = 0; m < 4; ++m) for (int k = 0; k < 2; ++k) \
;     dst[m][k] = *reinterpret_cast<const bf16x8*>((char*)SA(b, h) + lds_byte(wr * 64 + m * 16 + fr, k * 32 + fq * 8))
; #define LDB(dst, b, h) for (int n = 0; n < 2; ++n) for (int k = 0; k < 2; ++k) \
;     dst[n][k] = *reinterpret_cast<const bf16x8*>((char*)SB(b, h) + lds_byte(wc * 32 + n * 16 + fr, k * 32 + fq * 8))
; #define MMA(ai, bj, At_, Bt_) do { __builtin_amdgcn_s_setprio(1); \
;     for (int m = 0; m < 4; ++m) for (int n = 0; n < 2; ++n) for (int k = 0; k < 2; ++k) \
;       acc[ai][bj][m][n] = __builtin_amdgcn_mfma_f32_16x16x32_bf16(At_[m][k], Bt_[n][k], acc[ai][bj][m][n], 0, 0, 0); \
;     __builtin_amdgcn_s_setprio(0); } while (0)
; template <int K, int LD = K>
; __device__ __forceinline__ void gemm_main(const GAS bf16* A, const GAS bf16* Bt, int brow, int bcol, f32x4 (&acc)[2][2][4][2]) {
;     ...
;     LDA(At, 1, 1); STAGE(SA(1, 0), pA0, 3);
;     BAR; WAIT_L(0); MMA(1, 0, At, B0); BAR; SCHED;
;     STAGE(SB(1, 1), pB1, 3);
;     WAIT_V(6); BAR; MMA(1, 1, At, B1); BAR;
;     pA0 += 4 * BK; pA1 += 4 * BK; pB0 += 4 * BK; pB1 += 4 * BK;
;     asm volatile("" : "+s"(pA0), "+s"(pA1), "+s"(pB0), "+s"(pB1));
;   }
;   { LDB(B0, 0, 0); LDA(At, 0, 0); STAGE(SA(1, 1), pA1, 1);
;     BAR; WAIT_L(0); MMA(0, 0, At, B0); BAR;
	ds_read_b128 v[182:185], v139 offset:49152
	ds_read_b128 v[186:189], v139 offset:50176
	ds_read_b128 v[190:193], v138 offset:49152
	ds_read_b128 v[194:197], v138 offset:50176
	ds_read_b128 v[198:201], v137 offset:49152
	ds_read_b128 v[202:205], v137 offset:50176
	ds_read_b128 v[206:209], v136 offset:49152
	ds_read_b128 v[210:213], v136 offset:50176
	global_load_lds_dwordx4 v[168:169], off
	v_lshl_add_u64 v[168:169], v[238:239], 0, s[10:11]
	s_mov_b32 m0, s22
	s_nop 0
	global_load_lds_dwordx4 v[168:169], off
	s_barrier
	s_waitcnt lgkmcnt(0)
	s_setprio 1
	s_waitcnt lgkmcnt(0)
	v_mfma_f32_16x16x32_bf16 v[62:65], v[160:163], v[182:185], v[62:65]
	v_mfma_f32_16x16x32_bf16 v[58:61], v[174:177], v[182:185], v[58:61]
	v_mfma_f32_16x16x32_bf16 v[54:57], v[160:163], v[190:193], v[54:57]
	v_mfma_f32_16x16x32_bf16 v[50:53], v[174:177], v[190:193], v[50:53]
	v_mfma_f32_16x16x32_bf16 v[46:49], v[160:163], v[198:201], v[46:49]
	v_mfma_f32_16x16x32_bf16 v[42:45], v[174:177], v[198:201], v[42:45]
	v_mfma_f32_16x16x32_bf16 v[38:41], v[160:163], v[206:209], v[38:41]
	v_mfma_f32_16x16x32_bf16 v[34:37], v[174:177], v[206:209], v[34:37]
	v_mfma_f32_16x16x32_bf16 v[62:65], v[164:167], v[186:189], v[62:65]
	v_mfma_f32_16x16x32_bf16 v[58:61], v[178:181], v[186:189], v[58:61]
	v_mfma_f32_16x16x32_bf16 v[54:57], v[164:167], v[194:197], v[54:57]
	v_mfma_f32_16x16x32_bf16 v[50:53], v[178:181], v[194:197], v[50:53]
	v_mfma_f32_16x16x32_bf16 v[46:49], v[164:167], v[202:205], v[46:49]
	v_mfma_f32_16x16x32_bf16 v[42:45], v[178:181], v[202:205], v[42:45]
	v_mfma_f32_16x16x32_bf16 v[38:41], v[164:167], v[210:213], v[38:41]
	v_mfma_f32_16x16x32_bf16 v[34:37], v[178:181], v[210:213], v[34:37]
	s_setprio 0
	s_barrier
	v_readfirstlane_b32 s22, v158
	v_lshl_add_u64 v[160:161], v[240:241], 0, s[10:11]
	s_mov_b32 m0, s22
	v_readfirstlane_b32 s22, v159
	global_load_lds_dwordx4 v[160:161], off
	v_lshl_add_u64 v[160:161], v[242:243], 0, s[10:11]
	s_mov_b32 m0, s22
	s_nop 0
	global_load_lds_dwordx4 v[160:161], off
	s_waitcnt vmcnt(6)
	s_barrier
	s_setprio 1
	v_mfma_f32_16x16x32_bf16 v[30:33], v[214:217], v[182:185], v[30:33]
	v_mfma_f32_16x16x32_bf16 v[26:29], v[222:225], v[182:185], v[26:29]
	v_mfma_f32_16x16x32_bf16 v[22:25], v[214:217], v[190:193], v[22:25]
	v_mfma_f32_16x16x32_bf16 v[18:21], v[222:225], v[190:193], v[18:21]
	v_mfma_f32_16x16x32_bf16 v[14:17], v[214:217], v[198:201], v[14:17]
	v_mfma_f32_16x16x32_bf16 v[10:13], v[222:225], v[198:201], v[10:13]
	v_mfma_f32_16x16x32_bf16 v[6:9], v[214:217], v[206:209], v[6:9]
	v_mfma_f32_16x16x32_bf16 v[2:5], v[222:225], v[206:209], v[2:5]
	v_mfma_f32_16x16x32_bf16 v[30:33], v[218:221], v[186:189], v[30:33]
	v_mfma_f32_16x16x32_bf16 v[26:29], v[226:229], v[186:189], v[26:29]
	v_mfma_f32_16x16x32_bf16 v[22:25], v[218:221], v[194:197], v[22:25]
	v_mfma_f32_16x16x32_bf16 v[18:21], v[226:229], v[194:197], v[18:21]
	v_mfma_f32_16x16x32_bf16 v[14:17], v[218:221], v[202:205], v[14:17]
	v_mfma_f32_16x16x32_bf16 v[10:13], v[226:229], v[202:205], v[10:13]
	v_mfma_f32_16x16x32_bf16 v[6:9], v[218:221], v[210:213], v[6:9]
	v_mfma_f32_16x16x32_bf16 v[2:5], v[226:229], v[210:213], v[2:5]
	s_setprio 0
	s_add_i32 s15, s15, 2
	s_cmp_lt_u32 s15, 12
	s_barrier
	s_cbranch_scc1 .LBB0_884
	v_readfirstlane_b32 s42, v170
	v_readfirstlane_b32 s98, v171
	s_mov_b32 s99, 0
	s_nop 1
	s_lshl_b32 s42, s42, 4
	s_add_i32 s98, s98, s3
	s_cmpk_gt_i32 s98, 0x57f
	s_cbranch_scc1 .Lup1_noearly
	s_mul_hi_i32 s43, s98, 0x2e8ba2e9
	s_lshr_b32 s44, s43, 31
	s_ashr_i32 s43, s43, 5
	s_add_i32 s43, s43, s44
	s_mul_i32 s44, s43, 0xb0
	s_sub_i32 s44, s98, s44
	s_lshl_b32 s43, s43, 3
	s_and_b32 s45, s44, 7
	s_or_b32 s43, s45, s43
	s_ashr_i32 s44, s44, 3
	s_lshl_b32 s43, s43, 19
	s_lshl_b32 s44, s44, 19
	s_add_u32 s100, s26, s43
	s_addc_u32 s101, s27, 0
	s_add_u32 s98, s24, s44
	s_addc_u32 s99, s25, 0
.Lup1_noearly:
	v_lshl_add_u64 v[198:199], s[12:13], 0, v[130:131]
	v_readfirstlane_b32 s15, v144
	v_lshl_add_u64 v[198:199], v[198:199], 0, s[6:7]
	s_mov_b32 m0, s15
	v_lshl_add_u64 v[132:133], s[12:13], 0, v[132:133]
	v_readfirstlane_b32 s12, v143
	ds_read_b128 v[146:149], v145
	ds_read_b128 v[150:153], v145 offset:1024
	ds_read_b128 v[154:157], v145 offset:2048
	ds_read_b128 v[158:161], v145 offset:3072
	ds_read_b128 v[162:165], v139
	ds_read_b128 v[166:169], v139 offset:1024
	ds_read_b128 v[174:177], v138
	ds_read_b128 v[178:181], v138 offset:1024
	ds_read_b128 v[182:185], v137
	ds_read_b128 v[186:189], v137 offset:1024
	ds_read_b128 v[190:193], v136
	ds_read_b128 v[194:197], v136 offset:1024
	global_load_lds_dwordx4 v[198:199], off
	v_lshl_add_u64 v[132:133], v[132:133], 0, s[6:7]
	s_mov_b32 m0, s12
	s_nop 0
	global_load_lds_dwordx4 v[132:133], off
	s_barrier
	s_waitcnt lgkmcnt(0)
	s_setprio 1
	s_waitcnt lgkmcnt(0)
	v_mfma_f32_16x16x32_bf16 v[126:129], v[146:149], v[162:165], v[126:129]
	v_mfma_f32_16x16x32_bf16 v[122:125], v[154:157], v[162:165], v[122:125]
	v_mfma_f32_16x16x32_bf16 v[110:113], v[146:149], v[182:185], v[110:113]
	v_mfma_f32_16x16x32_bf16 v[106:109], v[154:157], v[182:185], v[106:109]
	v_mfma_f32_16x16x32_bf16 v[126:129], v[150:153], v[166:169], v[126:129]
	v_mfma_f32_16x16x32_bf16 v[122:125], v[158:161], v[166:169], v[122:125]
	v_mfma_f32_16x16x32_bf16 v[118:121], v[146:149], v[174:177], v[118:121]
	v_mfma_f32_16x16x32_bf16 v[114:117], v[154:157], v[174:177], v[114:117]
	v_mfma_f32_16x16x32_bf16 v[110:113], v[150:153], v[186:189], v[110:113]
	v_mfma_f32_16x16x32_bf16 v[106:109], v[158:161], v[186:189], v[106:109]
	v_mfma_f32_16x16x32_bf16 v[102:105], v[146:149], v[190:193], v[102:105]
	v_mfma_f32_16x16x32_bf16 v[98:101], v[154:157], v[190:193], v[98:101]
	v_mfma_f32_16x16x32_bf16 v[198:201], v[150:153], v[178:181], v[118:121]
	v_mfma_f32_16x16x32_bf16 v[202:205], v[158:161], v[178:181], v[114:117]
	v_mfma_f32_16x16x32_bf16 v[206:209], v[150:153], v[194:197], v[102:105]
	v_mfma_f32_16x16x32_bf16 v[210:213], v[158:161], v[194:197], v[98:101]
	s_setprio 0
	s_barrier
; #define STAGE(P, GP, ktrel) do { const GAS char* _g = (GP) + (ktrel) * (BK * 2); \
;     __builtin_amdgcn_global_load_lds((const GAS unsigned*)(_g + so0), (unsigned*)((char*)(P) + tid_ * 16), 16, 0, 0); \
;     __builtin_amdgcn_global_load_lds((const GAS unsigned*)(_g + so1), (unsigned*)((char*)(P) + tid_ * 16 + 8192), 16, 0, 0); } while (0)
; #define WAIT_V(n) asm volatile("s_waitcnt vmcnt(" #n ")" ::: "memory")
; #define WAIT_L(n) asm volatile("s_waitcnt lgkmcnt(" #n ")" ::: "memory")
; #define BAR __builtin_amdgcn_s_barrier()
; #define LDA(dst, b, h) for (int m = 0; m < 4; ++m) for (int k = 0; k < 2; ++k) \
;     dst[m][k] = *reinterpret_cast<const bf16x8*>((char*)SA(b, h) + lds_byte(wr * 64 + m * 16 + fr, k * 32 + fq * 8))
; #define LDB(dst, b, h) for (int n = 0; n < 2; ++n) for (int k = 0; k < 2; ++k) \
;     dst[n][k] = *reinterpret_cast<const bf16x8*>((char*)SB(b, h) + lds_byte(wc * 32 + n * 16 + fr, k * 32 + fq * 8))
; #define MMA(ai, bj, At_, Bt_) do { __builtin_amdgcn_s_setprio(1); \
;     for (int m = 0; m < 4; ++m) for (int n = 0; n < 2; ++n) for (int k = 0; k < 2; ++k) \
;       acc[ai][bj][m][n] = __builtin_amdgcn_mfma_f32_16x16x32_bf16(At_[m][k], Bt_[n][k], acc[ai][bj][m][n], 0, 0, 0); \
;     __builtin_amdgcn_s_setprio(0); } while (0)
; template <int K, int LD = K>
; __device__ __forceinline__ void gemm_prefetch(const GAS bf16* A, const GAS bf16* Bt, int brow, int bcol) {
;     ...
;   STAGE(SB(0, 0), pB0, 0); STAGE(SA(0, 0), pA0, 0);
;   STAGE(SB(0, 1), pB1, 0); STAGE(SA(0, 1), pA1, 0);
; template <int K, int LD = K>
; __device__ __forceinline__ void gemm_main(const GAS bf16* A, const GAS bf16* Bt, int brow, int bcol, f32x4 (&acc)[2][2][4][2]) {
;     ...
;     LDB(B1, 0, 1); BAR; WAIT_L(0); MMA(0, 1, At, B1); BAR;
;     LDA(At, 0, 1); WAIT_V(4); BAR; WAIT_L(0); MMA(1, 0, At, B0); MMA(1, 1, At, B1); BAR; }
;   { LDB(B0, 1, 0); LDA(At, 1, 0); WAIT_V(2); BAR; WAIT_L(0); MMA(0, 0, At, B0); BAR;
;     LDB(B1, 1, 1); WAIT_V(0); BAR; WAIT_L(0); MMA(0, 1, At, B1); BAR;
;     LDA(At, 1, 1); BAR; WAIT_L(0); MMA(1, 0, At, B0); MMA(1, 1, At, B1); BAR; }
	s_nop 1
	ds_read_b128 v[98:101], v142
	ds_read_b128 v[102:105], v142 offset:1024
	ds_read_b128 v[114:117], v142 offset:2048
	ds_read_b128 v[118:121], v142 offset:3072
	s_barrier
	s_waitcnt lgkmcnt(0)
	s_setprio 1
	s_waitcnt lgkmcnt(0)
	v_mfma_f32_16x16x32_bf16 v[94:97], v[98:101], v[162:165], v[94:97]
	v_mfma_f32_16x16x32_bf16 v[90:93], v[114:117], v[162:165], v[90:93]
	v_mfma_f32_16x16x32_bf16 v[78:81], v[98:101], v[182:185], v[78:81]
	v_mfma_f32_16x16x32_bf16 v[74:77], v[114:117], v[182:185], v[74:77]
	v_mfma_f32_16x16x32_bf16 v[94:97], v[102:105], v[166:169], v[94:97]
	v_mfma_f32_16x16x32_bf16 v[90:93], v[118:121], v[166:169], v[90:93]
	v_mfma_f32_16x16x32_bf16 v[86:89], v[98:101], v[174:177], v[86:89]
	v_mfma_f32_16x16x32_bf16 v[82:85], v[114:117], v[174:177], v[82:85]
	v_mfma_f32_16x16x32_bf16 v[78:81], v[102:105], v[186:189], v[78:81]
	v_mfma_f32_16x16x32_bf16 v[74:77], v[118:121], v[186:189], v[74:77]
	v_mfma_f32_16x16x32_bf16 v[70:73], v[98:101], v[190:193], v[70:73]
	v_mfma_f32_16x16x32_bf16 v[66:69], v[114:117], v[190:193], v[66:69]
	v_mfma_f32_16x16x32_bf16 v[142:145], v[102:105], v[178:181], v[86:89]
	v_mfma_f32_16x16x32_bf16 v[162:165], v[118:121], v[178:181], v[82:85]
	v_mfma_f32_16x16x32_bf16 v[166:169], v[102:105], v[194:197], v[70:73]
	v_mfma_f32_16x16x32_bf16 v[174:177], v[118:121], v[194:197], v[66:69]
	s_setprio 0
	s_barrier
	s_nop 1
	ds_read_b128 v[66:69], v139 offset:16384
	ds_read_b128 v[70:73], v139 offset:17408
	ds_read_b128 v[82:85], v138 offset:16384
	ds_read_b128 v[86:89], v138 offset:17408
	ds_read_b128 v[178:181], v137 offset:16384
	ds_read_b128 v[182:185], v137 offset:17408
	ds_read_b128 v[186:189], v136 offset:16384
	ds_read_b128 v[190:193], v136 offset:17408
	s_waitcnt vmcnt(4)
	s_barrier
	s_waitcnt lgkmcnt(0)
	s_setprio 1
	s_waitcnt lgkmcnt(0)
	v_mfma_f32_16x16x32_bf16 v[62:65], v[146:149], v[66:69], v[62:65]
	v_mfma_f32_16x16x32_bf16 v[58:61], v[154:157], v[66:69], v[58:61]
	v_mfma_f32_16x16x32_bf16 v[46:49], v[146:149], v[178:181], v[46:49]
	v_mfma_f32_16x16x32_bf16 v[38:41], v[146:149], v[186:189], v[38:41]
	v_mfma_f32_16x16x32_bf16 v[62:65], v[150:153], v[70:73], v[62:65]
	v_mfma_f32_16x16x32_bf16 v[58:61], v[158:161], v[70:73], v[58:61]
	v_mfma_f32_16x16x32_bf16 v[54:57], v[146:149], v[82:85], v[54:57]
	v_mfma_f32_16x16x32_bf16 v[50:53], v[154:157], v[82:85], v[50:53]
	v_mfma_f32_16x16x32_bf16 v[46:49], v[150:153], v[182:185], v[46:49]
	v_mfma_f32_16x16x32_bf16 v[42:45], v[154:157], v[178:181], v[42:45]
	v_mfma_f32_16x16x32_bf16 v[38:41], v[150:153], v[190:193], v[38:41]
	v_mfma_f32_16x16x32_bf16 v[34:37], v[154:157], v[186:189], v[34:37]
	v_mfma_f32_16x16x32_bf16 v[194:197], v[150:153], v[86:89], v[54:57]
	v_mfma_f32_16x16x32_bf16 v[214:217], v[158:161], v[86:89], v[50:53]
	v_mfma_f32_16x16x32_bf16 v[218:221], v[158:161], v[182:185], v[42:45]
	v_mfma_f32_16x16x32_bf16 v[146:149], v[158:161], v[190:193], v[34:37]
	s_setprio 0
	s_setprio 1
	v_mfma_f32_16x16x32_bf16 v[30:33], v[98:101], v[66:69], v[30:33]
	v_mfma_f32_16x16x32_bf16 v[26:29], v[114:117], v[66:69], v[26:29]
	v_mfma_f32_16x16x32_bf16 v[14:17], v[98:101], v[178:181], v[14:17]
	v_mfma_f32_16x16x32_bf16 v[6:9], v[98:101], v[186:189], v[6:9]
	v_mfma_f32_16x16x32_bf16 v[30:33], v[102:105], v[70:73], v[30:33]
	v_mfma_f32_16x16x32_bf16 v[26:29], v[118:121], v[70:73], v[26:29]
	v_mfma_f32_16x16x32_bf16 v[22:25], v[98:101], v[82:85], v[22:25]
	v_mfma_f32_16x16x32_bf16 v[18:21], v[114:117], v[82:85], v[18:21]
	v_mfma_f32_16x16x32_bf16 v[14:17], v[102:105], v[182:185], v[14:17]
	v_mfma_f32_16x16x32_bf16 v[10:13], v[114:117], v[178:181], v[10:13]
	v_mfma_f32_16x16x32_bf16 v[6:9], v[102:105], v[190:193], v[6:9]
	v_mfma_f32_16x16x32_bf16 v[2:5], v[114:117], v[186:189], v[2:5]
	v_mfma_f32_16x16x32_bf16 v[150:153], v[102:105], v[86:89], v[22:25]
	v_mfma_f32_16x16x32_bf16 v[154:157], v[118:121], v[86:89], v[18:21]
	v_mfma_f32_16x16x32_bf16 v[158:161], v[118:121], v[182:185], v[10:13]
	v_mfma_f32_16x16x32_bf16 v[178:181], v[118:121], v[190:193], v[2:5]
	s_setprio 0
	s_barrier
	s_nop 1
	ds_read_b128 v[2:5], v141
	ds_read_b128 v[10:13], v141 offset:1024
	ds_read_b128 v[182:185], v141 offset:2048
	ds_read_b128 v[186:189], v141 offset:3072
	ds_read_b128 v[18:21], v139 offset:32768
	ds_read_b128 v[22:25], v139 offset:33792
	ds_read_b128 v[34:37], v138 offset:32768
	ds_read_b128 v[42:45], v138 offset:33792
	ds_read_b128 v[50:53], v137 offset:32768
	ds_read_b128 v[54:57], v137 offset:33792
	ds_read_b128 v[190:193], v136 offset:32768
	ds_read_b128 v[222:225], v136 offset:33792
	s_waitcnt vmcnt(2)
	s_barrier
	s_waitcnt lgkmcnt(0)
	s_setprio 1
	s_waitcnt lgkmcnt(0)
	v_mfma_f32_16x16x32_bf16 v[66:69], v[2:5], v[18:21], v[126:129]
	v_mfma_f32_16x16x32_bf16 v[118:121], v[10:13], v[22:25], v[66:69]
	v_mfma_f32_16x16x32_bf16 v[66:69], v[182:185], v[18:21], v[122:125]
	v_mfma_f32_16x16x32_bf16 v[114:117], v[186:189], v[22:25], v[66:69]
	v_mfma_f32_16x16x32_bf16 v[66:69], v[2:5], v[34:37], v[198:201]
	v_mfma_f32_16x16x32_bf16 v[102:105], v[10:13], v[42:45], v[66:69]
	v_mfma_f32_16x16x32_bf16 v[66:69], v[182:185], v[34:37], v[202:205]
	v_mfma_f32_16x16x32_bf16 v[98:101], v[186:189], v[42:45], v[66:69]
	v_mfma_f32_16x16x32_bf16 v[66:69], v[2:5], v[50:53], v[110:113]
	v_mfma_f32_16x16x32_bf16 v[86:89], v[10:13], v[54:57], v[66:69]
	v_mfma_f32_16x16x32_bf16 v[66:69], v[182:185], v[50:53], v[106:109]
	v_mfma_f32_16x16x32_bf16 v[82:85], v[186:189], v[54:57], v[66:69]
	v_mfma_f32_16x16x32_bf16 v[66:69], v[2:5], v[190:193], v[206:209]
	v_mfma_f32_16x16x32_bf16 v[70:73], v[10:13], v[222:225], v[66:69]
	v_mfma_f32_16x16x32_bf16 v[66:69], v[182:185], v[190:193], v[210:213]
	v_mfma_f32_16x16x32_bf16 v[66:69], v[186:189], v[222:225], v[66:69]
	s_setprio 0
	s_barrier
	ds_read_b128 v[198:201], v140
	ds_read_b128 v[202:205], v140 offset:1024
	ds_read_b128 v[206:209], v140 offset:2048
	ds_read_b128 v[210:213], v140 offset:3072
	s_waitcnt vmcnt(0)
	s_cmp_eq_u32 s99, 0
	s_cbranch_scc1 .Lup1_early2_skip
	s_add_i32 s43, s42, 0x10100
	s_mov_b32 m0, s43
	s_nop 0
	global_load_lds_dwordx4 v130, s[98:99]
	s_add_u32 s98, s98, 0x20000
	s_addc_u32 s99, s99, 0
	s_add_i32 s43, s42, 0x12100
	s_mov_b32 m0, s43
	s_nop 0
	global_load_lds_dwordx4 v130, s[98:99]
	s_add_i32 s43, s42, 0x100
	s_mov_b32 m0, s43
	s_nop 0
	global_load_lds_dwordx4 v130, s[100:101]
	s_add_u32 s100, s100, 0x20000
	s_addc_u32 s101, s101, 0
	s_add_i32 s43, s42, 0x2100
	s_mov_b32 m0, s43
	s_nop 0
	global_load_lds_dwordx4 v130, s[100:101]
; #define STAGE(P, GP, ktrel) do { const GAS char* _g = (GP) + (ktrel) * (BK * 2); \
;     __builtin_amdgcn_global_load_lds((const GAS unsigned*)(_g + so0), (unsigned*)((char*)(P) + tid_ * 16), 16, 0, 0); \
;     __builtin_amdgcn_global_load_lds((const GAS unsigned*)(_g + so1), (unsigned*)((char*)(P) + tid_ * 16 + 8192), 16, 0, 0); } while (0)
; #define WAIT_L(n) asm volatile("s_waitcnt lgkmcnt(" #n ")" ::: "memory")
; #define BAR __builtin_amdgcn_s_barrier()
; #define LDA(dst, b, h) for (int m = 0; m < 4; ++m) for (int k = 0; k < 2; ++k) \
;     dst[m][k] = *reinterpret_cast<const bf16x8*>((char*)SA(b, h) + lds_byte(wr * 64 + m * 16 + fr, k * 32 + fq * 8))
; #define MMA(ai, bj, At_, Bt_) do { __builtin_amdgcn_s_setprio(1); \
;     for (int m = 0; m < 4; ++m) for (int n = 0; n < 2; ++n) for (int k = 0; k < 2; ++k) \
;       acc[ai][bj][m][n] = __builtin_amdgcn_mfma_f32_16x16x32_bf16(At_[m][k], Bt_[n][k], acc[ai][bj][m][n], 0, 0, 0); \
;     __builtin_amdgcn_s_setprio(0); } while (0)
; template <int K, int LD = K>
; __device__ __forceinline__ void gemm_prefetch(const GAS bf16* A, const GAS bf16* Bt, int brow, int bcol) {
;     ...
;   STAGE(SB(0, 1), pB1, 0); STAGE(SA(0, 1), pA1, 0);
; template <int K, int LD = K>
; __device__ __forceinline__ void gemm_main(const GAS bf16* A, const GAS bf16* Bt, int brow, int bcol, f32x4 (&acc)[2][2][4][2]) {
;     ...
;     LDA(At, 1, 1); BAR; WAIT_L(0); MMA(1, 0, At, B0); MMA(1, 1, At, B1); BAR; }
;   if (wr == 0) BAR;
.Lup1_early2_skip:
	s_barrier
	s_waitcnt lgkmcnt(0)
	s_setprio 1
	s_waitcnt lgkmcnt(0)
	v_mfma_f32_16x16x32_bf16 v[94:97], v[198:201], v[18:21], v[94:97]
	v_mfma_f32_16x16x32_bf16 v[18:21], v[206:209], v[18:21], v[90:93]
	v_mfma_f32_16x16x32_bf16 v[122:125], v[210:213], v[22:25], v[18:21]
	v_mfma_f32_16x16x32_bf16 v[18:21], v[198:201], v[34:37], v[142:145]
	v_mfma_f32_16x16x32_bf16 v[110:113], v[202:205], v[42:45], v[18:21]
	v_mfma_f32_16x16x32_bf16 v[18:21], v[206:209], v[34:37], v[162:165]
	v_mfma_f32_16x16x32_bf16 v[106:109], v[210:213], v[42:45], v[18:21]
	v_mfma_f32_16x16x32_bf16 v[18:21], v[198:201], v[50:53], v[78:81]
	v_mfma_f32_16x16x32_bf16 v[126:129], v[202:205], v[22:25], v[94:97]
	v_mfma_f32_16x16x32_bf16 v[94:97], v[202:205], v[54:57], v[18:21]
	v_mfma_f32_16x16x32_bf16 v[18:21], v[206:209], v[50:53], v[74:77]
	v_mfma_f32_16x16x32_bf16 v[90:93], v[210:213], v[54:57], v[18:21]
	v_mfma_f32_16x16x32_bf16 v[18:21], v[198:201], v[190:193], v[166:169]
	v_mfma_f32_16x16x32_bf16 v[78:81], v[202:205], v[222:225], v[18:21]
	v_mfma_f32_16x16x32_bf16 v[18:21], v[206:209], v[190:193], v[174:177]
	v_mfma_f32_16x16x32_bf16 v[74:77], v[210:213], v[222:225], v[18:21]
	s_setprio 0
	s_barrier
	ds_read_b128 v[140:143], v139 offset:49152
	ds_read_b128 v[162:165], v139 offset:50176
	ds_read_b128 v[166:169], v138 offset:49152
	ds_read_b128 v[174:177], v138 offset:50176
	ds_read_b128 v[190:193], v137 offset:49152
	ds_read_b128 v[222:225], v137 offset:50176
	ds_read_b128 v[226:229], v136 offset:49152
	ds_read_b128 v[136:139], v136 offset:50176
	s_cmp_eq_u32 s99, 0
	s_cbranch_scc1 .Lup1_early3_skip
	s_add_u32 s98, s98, 0x20000
	s_addc_u32 s99, s99, 0
	s_add_i32 s43, s42, 0x14100
	s_mov_b32 m0, s43
	s_nop 0
	global_load_lds_dwordx4 v130, s[98:99]
	s_add_u32 s98, s98, 0x20000
	s_addc_u32 s99, s99, 0
	s_add_i32 s43, s42, 0x16100
	s_mov_b32 m0, s43
	s_nop 0
	global_load_lds_dwordx4 v130, s[98:99]
	s_add_u32 s100, s100, 0x20000
	s_addc_u32 s101, s101, 0
	s_add_i32 s43, s42, 0x4100
	s_mov_b32 m0, s43
	s_nop 0
	global_load_lds_dwordx4 v130, s[100:101]
	s_add_u32 s100, s100, 0x20000
	s_addc_u32 s101, s101, 0
	s_add_i32 s43, s42, 0x6100
	s_mov_b32 m0, s43
	s_nop 0
	global_load_lds_dwordx4 v130, s[100:101]
.Lup1_early3_skip:
	s_barrier
	s_waitcnt lgkmcnt(0)
	s_setprio 1
	s_waitcnt lgkmcnt(0)
	v_mfma_f32_16x16x32_bf16 v[18:21], v[2:5], v[140:143], v[62:65]
	v_mfma_f32_16x16x32_bf16 v[54:57], v[10:13], v[162:165], v[18:21]
	v_mfma_f32_16x16x32_bf16 v[18:21], v[182:185], v[140:143], v[58:61]
	v_mfma_f32_16x16x32_bf16 v[50:53], v[186:189], v[162:165], v[18:21]
	v_mfma_f32_16x16x32_bf16 v[18:21], v[2:5], v[166:169], v[194:197]
	v_mfma_f32_16x16x32_bf16 v[42:45], v[10:13], v[174:177], v[18:21]
	v_mfma_f32_16x16x32_bf16 v[18:21], v[182:185], v[166:169], v[214:217]
	v_mfma_f32_16x16x32_bf16 v[34:37], v[186:189], v[174:177], v[18:21]
	v_mfma_f32_16x16x32_bf16 v[18:21], v[2:5], v[190:193], v[46:49]
	v_mfma_f32_16x16x32_bf16 v[2:5], v[2:5], v[226:229], v[38:41]
	v_mfma_f32_16x16x32_bf16 v[22:25], v[10:13], v[222:225], v[18:21]
	v_mfma_f32_16x16x32_bf16 v[18:21], v[182:185], v[190:193], v[218:221]
	v_mfma_f32_16x16x32_bf16 v[10:13], v[10:13], v[136:139], v[2:5]
	v_mfma_f32_16x16x32_bf16 v[2:5], v[182:185], v[226:229], v[146:149]
	v_mfma_f32_16x16x32_bf16 v[18:21], v[186:189], v[222:225], v[18:21]
	v_mfma_f32_16x16x32_bf16 v[2:5], v[186:189], v[136:139], v[2:5]
	s_setprio 0
	s_setprio 1
	v_mfma_f32_16x16x32_bf16 v[26:29], v[206:209], v[140:143], v[26:29]
	v_mfma_f32_16x16x32_bf16 v[30:33], v[198:201], v[140:143], v[30:33]
	v_mfma_f32_16x16x32_bf16 v[58:61], v[210:213], v[162:165], v[26:29]
	v_mfma_f32_16x16x32_bf16 v[26:29], v[198:201], v[166:169], v[150:153]
	v_mfma_f32_16x16x32_bf16 v[14:17], v[198:201], v[190:193], v[14:17]
	v_mfma_f32_16x16x32_bf16 v[62:65], v[202:205], v[162:165], v[30:33]
	v_mfma_f32_16x16x32_bf16 v[46:49], v[202:205], v[174:177], v[26:29]
	v_mfma_f32_16x16x32_bf16 v[26:29], v[206:209], v[166:169], v[154:157]
	v_mfma_f32_16x16x32_bf16 v[30:33], v[202:205], v[222:225], v[14:17]
	v_mfma_f32_16x16x32_bf16 v[14:17], v[206:209], v[190:193], v[158:161]
	v_mfma_f32_16x16x32_bf16 v[6:9], v[198:201], v[226:229], v[6:9]
	v_mfma_f32_16x16x32_bf16 v[38:41], v[210:213], v[174:177], v[26:29]
	v_mfma_f32_16x16x32_bf16 v[26:29], v[210:213], v[222:225], v[14:17]
	v_mfma_f32_16x16x32_bf16 v[14:17], v[202:205], v[136:139], v[6:9]
	v_mfma_f32_16x16x32_bf16 v[6:9], v[206:209], v[226:229], v[178:181]
	v_mfma_f32_16x16x32_bf16 v[6:9], v[210:213], v[136:139], v[6:9]
	s_setprio 0
	v_cmp_gt_u32_e32 vcc, s34, v135
	s_barrier
	s_and_saveexec_b64 s[12:13], vcc
	s_cbranch_execz .LBB0_887
	s_barrier
; #define GAS __attribute__((address_space(1)))
; __device__ __forceinline__ int otid() { int t = threadIdx.x; asm volatile("" : "+v"(t)); return t; }
; #define STAGE(P, GP, ktrel) do { const GAS char* _g = (GP) + (ktrel) * (BK * 2); \
;     __builtin_amdgcn_global_load_lds((const GAS unsigned*)(_g + so0), (unsigned*)((char*)(P) + tid_ * 16), 16, 0, 0); \
;     __builtin_amdgcn_global_load_lds((const GAS unsigned*)(_g + so1), (unsigned*)((char*)(P) + tid_ * 16 + 8192), 16, 0, 0); } while (0)
; template <int K, int LD = K>
; __device__ __forceinline__ void gemm_prefetch(const GAS bf16* A, const GAS bf16* Bt, int brow, int bcol) {
;   bf16* shm = (bf16*)smem_raw;
;   const int tid_ = otid();
;   unsigned so0, so1;
;   { int r_, c_; stage_rc(tid_ * 16, r_, c_); so0 = (unsigned)(r_ * LD + c_) * 2u; stage_rc(tid_ * 16 + 8192, r_, c_); so1 = (unsigned)(r_ * LD + c_) * 2u; }
;   const GAS char* pA0 = (const GAS char*)A + (long)brow * LD * 2; const GAS char* pA1 = pA0 + (long)HALF * LD * 2;
;   const GAS char* pB0 = (const GAS char*)Bt + (long)bcol * LD * 2; const GAS char* pB1 = pB0 + (long)HALF * LD * 2;
;   asm volatile("" : "+s"(pA0), "+s"(pA1), "+s"(pB0), "+s"(pB1));
;   STAGE(SB(0, 0), pB0, 0); STAGE(SA(0, 0), pA0, 0);
;   STAGE(SB(0, 1), pB1, 0); STAGE(SA(0, 1), pA1, 0);
;   STAGE(SB(1, 0), pB0, 1); STAGE(SA(1, 0), pA0, 1); STAGE(SB(1, 1), pB1, 1);
; }
; __device__ __forceinline__ void load_rr(const GAS float* ssq, int brow, int par) {
;   float* rr = (float*)(smem_raw + LDS_RR) + par * 256;
;   const int tx = otid();
;   if (tx < 256) {
;     const GAS f32x4* s = (const GAS f32x4*)(ssq + (size_t)(brow + tx) * 16);
;     f32x4 a = s[0], b = s[1], c = s[2], d = s[3];
;     float t = ((a.x + a.y) + (a.z + a.w)) + ((b.x + b.y) + (b.z + b.w)) + ((c.x + c.y) + (c.z + c.w)) + ((d.x + d.y) + (d.z + d.w));
.LBB0_887:
	s_or_b64 exec, exec, s[12:13]
	v_readfirstlane_b32 s12, v171
	s_add_i32 s3, s12, s3
	s_cmpk_gt_i32 s3, 0x57f
	s_cselect_b64 s[12:13], -1, 0
	s_and_b64 vcc, exec, s[12:13]
	s_mov_b32 s20, s41
	s_cbranch_vccnz .LBB0_880
	v_mov_b32_e32 v130, v170
	s_mul_hi_i32 s15, s3, 0x2e8ba2e9
	v_ashrrev_i32_e32 v132, 31, v130
	v_lshrrev_b32_e32 v132, 26, v132
	v_lshlrev_b32_e32 v135, 4, v130
	v_add_u32_e32 v132, v130, v132
	v_bfe_i32 v130, v130, 27, 1
	v_lshrrev_b32_e32 v130, 22, v130
	v_add_u32_e32 v130, v135, v130
	v_and_b32_e32 v130, 0xfffffc00, v130
	v_sub_u32_e32 v130, v135, v130
	v_lshrrev_b32_e32 v133, 4, v130
	v_bitop3_b32 v133, v133, v130, 32 bitop3:0x6c
	v_ashrrev_i32_e32 v130, 31, v130
	v_lshrrev_b32_e32 v130, 26, v130
	v_add_u32_e32 v130, v133, v130
	v_ashrrev_i32_e32 v130, 6, v130
	v_ashrrev_i32_e32 v132, 6, v132
	v_mul_i32_i24_e32 v137, 64, v130
	v_lshlrev_b32_e32 v136, 3, v132
	v_lshlrev_b32_e32 v132, 5, v132
	v_sub_u32_e32 v133, v133, v137
	s_lshr_b32 s16, s15, 31
	s_ashr_i32 s15, s15, 5
	v_and_b32_e32 v136, 0x1ffff0, v136
	v_and_b32_e32 v132, 32, v132
	v_ashrrev_i16_sdwa v133, v1, sext(v133) dst_sel:DWORD dst_unused:UNUSED_PAD src0_sel:DWORD src1_sel:BYTE_0
	s_add_i32 s15, s15, s16
	v_add_u32_sdwa v132, v132, sext(v133) dst_sel:DWORD dst_unused:UNUSED_PAD src0_sel:DWORD src1_sel:WORD_0
	v_add_lshl_u32 v130, v130, v136, 11
	s_mul_i32 s16, s15, 0xb0
	v_lshl_add_u32 v130, v132, 1, v130
	v_add_u32_e32 v132, 0x2000, v135
	s_sub_i32 s16, s3, s16
	v_ashrrev_i32_e32 v133, 31, v132
	s_lshl_b32 s15, s15, 3
	s_and_b32 s17, s16, 7
	v_lshrrev_b32_e32 v133, 22, v133
	s_or_b32 s28, s17, s15
	v_add_u32_e32 v133, v132, v133
	s_ashr_i32 s20, s16, 3
	s_lshl_b32 s16, s28, 8
	v_ashrrev_i32_e32 v133, 10, v133
	v_mul_i32_i24_e32 v136, 0x400, v133
	s_ashr_i32 s17, s16, 31
	s_lshl_b32 s18, s20, 8
	v_sub_u32_e32 v132, v132, v136
	s_lshl_b64 s[22:23], s[16:17], 11
	v_lshrrev_b32_e32 v136, 4, v132
	s_add_u32 s22, s26, s22
	v_bitop3_b32 v132, v136, v132, 32 bitop3:0x6c
	s_addc_u32 s23, s27, s23
	v_ashrrev_i32_e32 v137, 31, v132
	s_add_u32 s42, s22, 0x40000
	v_lshrrev_b32_e32 v137, 26, v137
	s_addc_u32 s43, s23, 0
	s_ashr_i32 s19, s18, 31
	v_add_u32_e32 v137, v132, v137
	s_lshl_b64 s[18:19], s[18:19], 11
	v_lshrrev_b32_e32 v138, 6, v137
	v_and_b32_e32 v137, 0xc0, v137
	s_add_u32 s18, s24, s18
	v_lshlrev_b32_e32 v136, 3, v133
	v_lshlrev_b32_e32 v133, 5, v133
	v_sub_u32_e32 v132, v132, v137
	s_addc_u32 s19, s25, s19
	v_add_u32_e32 v140, s29, v135
	v_and_b32_e32 v136, 0x1ffff0, v136
	v_and_b32_e32 v133, 32, v133
	v_ashrrev_i16_sdwa v132, v1, sext(v132) dst_sel:DWORD dst_unused:UNUSED_PAD src0_sel:DWORD src1_sel:BYTE_0
	s_add_u32 s44, s18, 0x40000
	v_readfirstlane_b32 s15, v140
	v_add_u32_e32 v140, 0x2000, v140
	v_add_u32_sdwa v132, v133, sext(v132) dst_sel:DWORD dst_unused:UNUSED_PAD src0_sel:DWORD src1_sel:WORD_0
	v_add_lshl_u32 v133, v138, v136, 11
	s_addc_u32 s45, s19, 0
	s_mov_b32 m0, s15
	v_readfirstlane_b32 s15, v140
	v_add_u32_e32 v148, 0x100, v135
	v_lshl_add_u32 v132, v132, 1, v133
	v_add_u32_e32 v144, 0x2000, v148
	s_mov_b32 m0, s15
	v_readfirstlane_b32 s15, v148
	v_mov_b32_e32 v133, v131
	s_mov_b32 m0, s15
	v_readfirstlane_b32 s15, v144
	v_add_u32_e32 v149, s30, v135
	v_lshl_add_u64 v[138:139], s[18:19], 0, v[132:133]
	v_lshl_add_u64 v[142:143], s[22:23], 0, v[132:133]
	s_mov_b32 m0, s15
	v_readfirstlane_b32 s15, v149
	v_lshl_add_u64 v[146:147], s[44:45], 0, v[132:133]
	v_add_u32_e32 v133, 0x2000, v149
	s_mov_b32 m0, s15
	v_readfirstlane_b32 s15, v133
	v_add_u32_e32 v133, 0x4000, v148
	s_mov_b32 m0, s15
	v_readfirstlane_b32 s15, v133
	s_mov_b32 m0, s15
	v_lshl_add_u64 v[136:137], s[18:19], 0, v[130:131]
	v_lshl_add_u64 v[140:141], s[22:23], 0, v[130:131]
	v_lshl_add_u64 v[144:145], s[44:45], 0, v[130:131]
	v_add_u32_e32 v130, 0x6000, v148
	s_nop 0
	v_readfirstlane_b32 s15, v130
	v_add_u32_e32 v130, s31, v135
	s_mov_b32 m0, s15
	v_readfirstlane_b32 s15, v130
	v_add_u32_e32 v130, 0x2000, v130
	v_lshl_add_u64 v[132:133], v[136:137], 0, s[6:7]
	s_mov_b32 m0, s15
	v_readfirstlane_b32 s15, v130
	v_add_u32_e32 v130, 0x8000, v148
	global_load_lds_dwordx4 v[132:133], off
	v_lshl_add_u64 v[132:133], v[138:139], 0, s[6:7]
	s_mov_b32 m0, s15
	v_readfirstlane_b32 s15, v130
	v_add_u32_e32 v130, 0xa000, v148
	global_load_lds_dwordx4 v[132:133], off
	v_lshl_add_u64 v[132:133], v[140:141], 0, s[6:7]
	s_mov_b32 m0, s15
	v_readfirstlane_b32 s15, v130
	v_add_u32_e32 v130, s33, v135
	global_load_lds_dwordx4 v[132:133], off
	v_lshl_add_u64 v[132:133], v[142:143], 0, s[6:7]
	s_mov_b32 m0, s15
	v_readfirstlane_b32 s15, v130
	v_add_u32_e32 v130, 0x2000, v130
	global_load_lds_dwordx4 v[132:133], off
	v_lshl_add_u64 v[132:133], v[144:145], 0, s[6:7]
	s_mov_b32 m0, s15
	v_readfirstlane_b32 s15, v130
	global_load_lds_dwordx4 v[132:133], off
	v_lshl_add_u64 v[132:133], v[146:147], 0, s[6:7]
	s_mov_b32 m0, s15
	v_mov_b32_e32 v130, v170
	global_load_lds_dwordx4 v[132:133], off
	s_nop 0
	v_cmp_gt_i32_e32 vcc, s34, v130
	s_and_saveexec_b64 s[18:19], vcc
	s_cbranch_execz .LBB0_879
	v_add_u32_e32 v132, s16, v130
	v_ashrrev_i32_e32 v133, 31, v132
	v_lshlrev_b64 v[132:133], 6, v[132:133]
	v_lshl_add_u64 v[132:133], s[4:5], 0, v[132:133]
	global_load_dwordx4 v[136:139], v[132:133], off
	global_load_dwordx4 v[140:143], v[132:133], off offset:16
	global_load_dwordx4 v[144:147], v[132:133], off offset:32
	global_load_dwordx4 v[148:151], v[132:133], off offset:48
	s_branch .LBB0_879

; __global__ void __launch_bounds__(NTHR, 2) fwd_megakernel(Params Pk) {
	.amdhsa_kernel _Z14fwd_megakernel6Params
		.amdhsa_group_segment_fixed_size 256
		.amdhsa_private_segment_fixed_size 0
		.amdhsa_kernarg_size 440
		.amdhsa_user_sgpr_count 2
		.amdhsa_user_sgpr_dispatch_ptr 0
		.amdhsa_user_sgpr_queue_ptr 0
		.amdhsa_user_sgpr_kernarg_segment_ptr 1
		.amdhsa_user_sgpr_dispatch_id 0
		.amdhsa_user_sgpr_kernarg_preload_length 0
		.amdhsa_user_sgpr_kernarg_preload_offset 0
		.amdhsa_user_sgpr_private_segment_size 0
		.amdhsa_uses_dynamic_stack 0
		.amdhsa_enable_private_segment 0
		.amdhsa_system_sgpr_workgroup_id_x 1
		.amdhsa_system_sgpr_workgroup_id_y 0
		.amdhsa_system_sgpr_workgroup_id_z 0
		.amdhsa_system_sgpr_workgroup_info 0
		.amdhsa_system_vgpr_workitem_id 2
		.amdhsa_next_free_vgpr 253
		.amdhsa_next_free_sgpr 102
		.amdhsa_accum_offset 256
		.amdhsa_reserve_vcc 1
		.amdhsa_float_round_mode_32 0
		.amdhsa_float_round_mode_16_64 0
		.amdhsa_float_denorm_mode_32 3
		.amdhsa_float_denorm_mode_16_64 3
		.amdhsa_dx10_clamp 1
		.amdhsa_ieee_mode 1
		.amdhsa_fp16_overflow 0
		.amdhsa_tg_split 0
		.amdhsa_exception_fp_ieee_invalid_op 0
		.amdhsa_exception_fp_denorm_src 0
		.amdhsa_exception_fp_ieee_div_zero 0
		.amdhsa_exception_fp_ieee_overflow 0
		.amdhsa_exception_fp_ieee_underflow 0
		.amdhsa_exception_fp_ieee_inexact 0
		.amdhsa_exception_int_div_zero 0
	.end_amdhsa_kernel

; __global__ void __launch_bounds__(NTHR, 2) fwd_megakernel(Params Pk) {
amdhsa.kernels:
  - .agpr_count:     0
    .args:
      - .offset:         0
        .size:           184
        .value_kind:     by_value
      - .offset:         184
        .size:           4
        .value_kind:     hidden_block_count_x
      - .offset:         188
        .size:           4
        .value_kind:     hidden_block_count_y
      - .offset:         192
        .size:           4
        .value_kind:     hidden_block_count_z
      - .offset:         196
        .size:           2
        .value_kind:     hidden_group_size_x
      - .offset:         198
        .size:           2
        .value_kind:     hidden_group_size_y
      - .offset:         200
        .size:           2
        .value_kind:     hidden_group_size_z
      - .offset:         202
        .size:           2
        .value_kind:     hidden_remainder_x
      - .offset:         204
        .size:           2
        .value_kind:     hidden_remainder_y
      - .offset:         206
        .size:           2
        .value_kind:     hidden_remainder_z
      - .offset:         224
        .size:           8
        .value_kind:     hidden_global_offset_x
      - .offset:         232
        .size:           8
        .value_kind:     hidden_global_offset_y
      - .offset:         240
        .size:           8
        .value_kind:     hidden_global_offset_z
      - .offset:         248
        .size:           2
        .value_kind:     hidden_grid_dims
      - .offset:         272
        .size:           8
        .value_kind:     hidden_multigrid_sync_arg
      - .offset:         304
        .size:           4
        .value_kind:     hidden_dynamic_lds_size
    .group_segment_fixed_size: 256
    .kernarg_segment_align: 8
    .kernarg_segment_size: 440
    .language:       OpenCL C
    .language_version:
      - 2
      - 0
    .max_flat_workgroup_size: 512
    .name:           _Z14fwd_megakernel6Params
    .private_segment_fixed_size: 0
    .sgpr_count:     108
    .sgpr_spill_count: 3
    .symbol:         _Z14fwd_megakernel6Params.kd
    .uniform_work_group_size: 1
    .uses_dynamic_stack: false
    .vgpr_count:     253
    .vgpr_spill_count: 0
    .wavefront_size: 64
